# GEMM K-loops load-segment slimming: M0->DMA wait state supplied by the address add, tail-only M0 offsets hoisted out of the loop, duplicate lgkmcnt(0) dropped
# speedup vs baseline: 1.0234x; 1.0010x over previous
.LBB0_33:
	s_or_b64 exec, exec, s[52:53]
	v_mov_b32_e32 v3, v1
	v_lshl_add_u64 v[12:13], s[0:1], 0, v[2:3]
	s_waitcnt vmcnt(8)
	v_lshl_add_u64 v[16:17], s[14:15], 0, v[2:3]
	v_lshl_add_u64 v[20:21], s[16:17], 0, v[2:3]
	v_lshl_add_u64 v[130:131], s[72:73], 0, v[2:3]
	v_and_b32_e32 v146, 15, v142
	v_bfe_u32 v145, v142, 4, 2
	v_lshlrev_b32_e32 v3, 2, v142
	v_add_u32_e32 v156, 0x18000, v147
	v_lshl_add_u64 v[10:11], s[0:1], 0, v[0:1]
	v_lshl_add_u64 v[14:15], s[14:15], 0, v[0:1]
	v_lshl_add_u64 v[18:19], s[16:17], 0, v[0:1]
	v_lshl_add_u64 v[132:133], s[72:73], 0, v[0:1]
	v_lshlrev_b32_e32 v0, 6, v146
	v_lshlrev_b32_e32 v2, 4, v145
	v_and_b32_e32 v3, 32, v3
	s_mov_b64 s[14:15], 0x80
	v_readfirstlane_b32 s0, v156
	v_add_u32_e32 v157, 0x1a000, v147
	v_bitop3_b32 v22, v2, v3, v0 bitop3:0x36
	v_lshl_add_u64 v[2:3], v[10:11], 0, s[14:15]
	s_mov_b32 m0, s0
	v_readfirstlane_b32 s0, v157
	v_add_u32_e32 v158, 0x8000, v147
	s_waitcnt vmcnt(4)
	s_barrier
	global_load_lds_dwordx4 v[2:3], off
	v_lshl_add_u64 v[2:3], v[12:13], 0, s[14:15]
	s_mov_b32 m0, s0
	v_readfirstlane_b32 s0, v158
	v_add_u32_e32 v159, 0xa000, v147
	global_load_lds_dwordx4 v[2:3], off
	v_lshl_add_u64 v[2:3], v[14:15], 0, s[14:15]
	s_mov_b32 m0, s0
	v_readfirstlane_b32 s0, v159
	v_add_u32_e32 v160, 0x1c000, v147
	global_load_lds_dwordx4 v[2:3], off
	v_lshl_add_u64 v[2:3], v[16:17], 0, s[14:15]
	s_mov_b32 m0, s0
	v_readfirstlane_b32 s0, v160
	v_add_u32_e32 v161, 0x1e000, v147
	global_load_lds_dwordx4 v[2:3], off
	v_lshl_add_u64 v[2:3], v[18:19], 0, s[14:15]
	s_mov_b32 m0, s0
	v_readfirstlane_b32 s0, v161
	global_load_lds_dwordx4 v[2:3], off
	v_lshl_add_u64 v[2:3], v[20:21], 0, s[14:15]
	s_mov_b32 m0, s0
	s_sub_i32 s1, s56, s63
	global_load_lds_dwordx4 v[2:3], off
	s_sub_i32 s1, s1, s62
	v_lshlrev_b32_e32 v0, 15, v4
	s_sext_i32_i16 s1, s1
	v_and_b32_e32 v0, 0xffff0000, v0
	s_lshl_b32 s0, s57, 10
	s_lshl_b32 s1, s1, 8
	v_lshl_add_u32 v0, v5, 12, v0
	v_and_b32_e32 v2, 1, v4
	s_add_i32 s0, s0, s1
	v_lshl_or_b32 v0, v2, 6, v0
	v_lshlrev_b32_e32 v2, 15, v6
	s_ashr_i32 s1, s0, 31
	v_and_b32_e32 v2, 0xffff0000, v2
	s_lshl_b64 s[0:1], s[0:1], 12
	v_lshl_add_u32 v2, v8, 12, v2
	v_and_b32_e32 v3, 1, v6
	s_add_u32 s0, s6, s0
	v_lshl_or_b32 v2, v3, 6, v2
	v_lshl_add_u32 v0, v7, 1, v0
	s_addc_u32 s1, s7, s1
	v_lshl_add_u32 v2, v9, 1, v2
	v_mov_b32_e32 v3, v1
	v_lshl_add_u64 v[134:135], s[0:1], 0, v[0:1]
	v_lshl_add_u64 v[136:137], s[0:1], 0, v[2:3]
	s_add_u32 s0, s88, s12
	v_bfe_u32 v144, v142, 6, 2
	s_waitcnt vmcnt(6)
	s_addc_u32 s1, s89, s13
	v_lshlrev_b32_e32 v23, 13, v143
	v_lshl_or_b32 v24, v144, 12, v212
	v_lshl_add_u64 v[140:141], s[0:1], 0, v[2:3]
	v_mov_b32_e32 v2, 0
	v_lshl_add_u64 v[138:139], s[0:1], 0, v[0:1]
	s_mov_b32 s0, -2
	s_mov_b64 s[12:13], 0
	v_add_u32_e32 v151, v24, v22
	v_add_u32_e32 v0, v23, v22
	v_mov_b32_e32 v3, v2
	v_mov_b32_e32 v4, v2
	v_mov_b32_e32 v5, v2
	v_mov_b32_e32 v6, v2
	v_mov_b32_e32 v7, v2
	v_mov_b32_e32 v8, v2
	v_mov_b32_e32 v9, v2
	v_mov_b32_e32 v10, v2
	v_mov_b32_e32 v11, v2
	v_mov_b32_e32 v12, v2
	v_mov_b32_e32 v13, v2
	v_mov_b32_e32 v14, v2
	v_mov_b32_e32 v15, v2
	v_mov_b32_e32 v16, v2
	v_mov_b32_e32 v17, v2
	v_mov_b32_e32 v18, v2
	v_mov_b32_e32 v19, v2
	v_mov_b32_e32 v20, v2
	v_mov_b32_e32 v21, v2
	v_mov_b32_e32 v22, v2
	v_mov_b32_e32 v23, v2
	v_mov_b32_e32 v24, v2
	v_mov_b32_e32 v25, v2
	v_mov_b32_e32 v26, v2
	v_mov_b32_e32 v27, v2
	v_mov_b32_e32 v28, v2
	v_mov_b32_e32 v29, v2
	v_mov_b32_e32 v30, v2
	v_mov_b32_e32 v31, v2
	v_mov_b32_e32 v32, v2
	v_mov_b32_e32 v33, v2
	v_mov_b32_e32 v34, v2
	v_mov_b32_e32 v35, v2
	v_mov_b32_e32 v36, v2
	v_mov_b32_e32 v37, v2
	v_mov_b32_e32 v38, v2
	v_mov_b32_e32 v39, v2
	v_mov_b32_e32 v40, v2
	v_mov_b32_e32 v41, v2
	v_mov_b32_e32 v42, v2
	v_mov_b32_e32 v43, v2
	v_mov_b32_e32 v44, v2
	v_mov_b32_e32 v45, v2
	v_mov_b32_e32 v46, v2
	v_mov_b32_e32 v47, v2
	v_mov_b32_e32 v48, v2
	v_mov_b32_e32 v49, v2
	v_mov_b32_e32 v50, v2
	v_mov_b32_e32 v51, v2
	v_mov_b32_e32 v52, v2
	v_mov_b32_e32 v53, v2
	v_mov_b32_e32 v54, v2
	v_mov_b32_e32 v55, v2
	v_mov_b32_e32 v56, v2
	v_mov_b32_e32 v57, v2
	v_mov_b32_e32 v58, v2
	v_mov_b32_e32 v59, v2
	v_mov_b32_e32 v60, v2
	v_mov_b32_e32 v61, v2
	v_mov_b32_e32 v62, v2
	v_mov_b32_e32 v63, v2
	v_mov_b32_e32 v64, v2
	v_mov_b32_e32 v65, v2
	v_mov_b32_e32 v70, v2
	v_mov_b32_e32 v71, v2
	v_mov_b32_e32 v72, v2
	v_mov_b32_e32 v73, v2
	v_mov_b32_e32 v86, v2
	v_mov_b32_e32 v87, v2
	v_mov_b32_e32 v88, v2
	v_mov_b32_e32 v89, v2
	v_mov_b32_e32 v90, v2
	v_mov_b32_e32 v91, v2
	v_mov_b32_e32 v92, v2
	v_mov_b32_e32 v93, v2
	v_mov_b32_e32 v94, v2
	v_mov_b32_e32 v95, v2
	v_mov_b32_e32 v96, v2
	v_mov_b32_e32 v97, v2
	v_mov_b32_e32 v98, v2
	v_mov_b32_e32 v99, v2
	v_mov_b32_e32 v100, v2
	v_mov_b32_e32 v101, v2
	v_mov_b32_e32 v102, v2
	v_mov_b32_e32 v103, v2
	v_mov_b32_e32 v104, v2
	v_mov_b32_e32 v105, v2
	v_mov_b32_e32 v106, v2
	v_mov_b32_e32 v107, v2
	v_mov_b32_e32 v108, v2
	v_mov_b32_e32 v109, v2
	v_mov_b32_e32 v110, v2
	v_mov_b32_e32 v111, v2
	v_mov_b32_e32 v112, v2
	v_mov_b32_e32 v113, v2
	v_mov_b32_e32 v114, v2
	v_mov_b32_e32 v115, v2
	v_mov_b32_e32 v116, v2
	v_mov_b32_e32 v117, v2
	v_mov_b32_e32 v118, v2
	v_mov_b32_e32 v119, v2
	v_mov_b32_e32 v120, v2
	v_mov_b32_e32 v121, v2
	v_mov_b32_e32 v122, v2
	v_mov_b32_e32 v123, v2
	v_mov_b32_e32 v124, v2
	v_mov_b32_e32 v125, v2
	v_mov_b32_e32 v126, v2
	v_mov_b32_e32 v127, v2
	v_mov_b32_e32 v128, v2
	v_mov_b32_e32 v129, v2
	v_mov_b32_e32 v66, v2
	v_mov_b32_e32 v67, v2
	v_mov_b32_e32 v68, v2
	v_mov_b32_e32 v69, v2
	v_mov_b32_e32 v74, v2
	v_mov_b32_e32 v75, v2
	v_mov_b32_e32 v76, v2
	v_mov_b32_e32 v77, v2
	v_mov_b32_e32 v78, v2
	v_mov_b32_e32 v79, v2
	v_mov_b32_e32 v80, v2
	v_mov_b32_e32 v81, v2
	v_mov_b32_e32 v82, v2
	v_mov_b32_e32 v83, v2
	v_mov_b32_e32 v84, v2
	v_mov_b32_e32 v85, v2
	s_barrier
	v_add_u32_e32 v162, 0xc000, v147
	v_add_u32_e32 v163, 0xe000, v147
	v_readfirstlane_b32 s1, v147
	s_nop 1
.LBB0_34:
	ds_read_b128 v[164:167], v151
	ds_read_b128 v[168:171], v151 offset:1024
	ds_read_b128 v[172:175], v151 offset:2048
	ds_read_b128 v[176:179], v151 offset:3072
	v_lshl_add_u64 v[204:205], v[138:139], 0, s[12:13]
	v_lshl_add_u64 v[228:229], v[204:205], 0, s[60:61]
	s_add_i32 m0, s1, 0xc000
	ds_read_b128 v[180:183], v0
	ds_read_b128 v[184:187], v0 offset:1024
	ds_read_b128 v[188:191], v0 offset:2048
	ds_read_b128 v[192:195], v0 offset:3072
	ds_read_b128 v[196:199], v0 offset:4096
	ds_read_b128 v[200:203], v0 offset:5120
	ds_read_b128 v[222:225], v0 offset:6144
	ds_read_b128 v[232:235], v0 offset:7168
	global_load_lds_dwordx4 v[228:229], off
	v_lshl_add_u64 v[210:211], v[140:141], 0, s[12:13]
	s_add_i32 m0, s1, 0xe000
	v_lshl_add_u64 v[152:153], v[210:211], 0, s[60:61]
	global_load_lds_dwordx4 v[152:153], off
	s_waitcnt lgkmcnt(8)
	s_barrier
	s_waitcnt lgkmcnt(0)
	s_setprio 1
	v_mfma_f32_16x16x32_bf16 v[126:129], v[164:167], v[180:183], v[126:129]
	v_mfma_f32_16x16x32_bf16 v[122:125], v[172:175], v[180:183], v[122:125]
	v_mfma_f32_16x16x32_bf16 v[118:121], v[164:167], v[188:191], v[118:121]
	v_mfma_f32_16x16x32_bf16 v[114:117], v[172:175], v[188:191], v[114:117]
	v_mfma_f32_16x16x32_bf16 v[110:113], v[164:167], v[196:199], v[110:113]
	v_mfma_f32_16x16x32_bf16 v[106:109], v[172:175], v[196:199], v[106:109]
	v_mfma_f32_16x16x32_bf16 v[102:105], v[164:167], v[222:225], v[102:105]
	v_mfma_f32_16x16x32_bf16 v[98:101], v[172:175], v[222:225], v[98:101]
	v_mfma_f32_16x16x32_bf16 v[126:129], v[168:171], v[184:187], v[126:129]
	v_mfma_f32_16x16x32_bf16 v[122:125], v[176:179], v[184:187], v[122:125]
	v_mfma_f32_16x16x32_bf16 v[118:121], v[168:171], v[192:195], v[118:121]
	v_mfma_f32_16x16x32_bf16 v[114:117], v[176:179], v[192:195], v[114:117]
	v_mfma_f32_16x16x32_bf16 v[110:113], v[168:171], v[200:203], v[110:113]
	v_mfma_f32_16x16x32_bf16 v[106:109], v[176:179], v[200:203], v[106:109]
	v_mfma_f32_16x16x32_bf16 v[102:105], v[168:171], v[232:235], v[102:105]
	v_mfma_f32_16x16x32_bf16 v[98:101], v[176:179], v[232:235], v[98:101]
	s_setprio 0
	s_barrier
	v_lshl_add_u64 v[216:217], v[134:135], 0, s[12:13]
	s_add_i32 m0, s1, 0xff00
	ds_read_b128 v[236:239], v151 offset:16384
	ds_read_b128 v[240:243], v151 offset:17408
	ds_read_b128 v[244:247], v151 offset:18432
	ds_read_b128 v[248:251], v151 offset:19456
	global_load_lds_dwordx4 v[216:217], off offset:256
	s_add_i32 m0, s1, 0x11f00
	v_lshl_add_u64 v[218:219], v[136:137], 0, s[12:13]
	global_load_lds_dwordx4 v[218:219], off offset:256
	s_barrier
	s_waitcnt lgkmcnt(0)
	s_setprio 1
	v_mfma_f32_16x16x32_bf16 v[94:97], v[236:239], v[180:183], v[94:97]
	v_mfma_f32_16x16x32_bf16 v[90:93], v[244:247], v[180:183], v[90:93]
	v_mfma_f32_16x16x32_bf16 v[86:89], v[236:239], v[188:191], v[86:89]
	v_mfma_f32_16x16x32_bf16 v[70:73], v[244:247], v[188:191], v[70:73]
	v_mfma_f32_16x16x32_bf16 v[62:65], v[236:239], v[196:199], v[62:65]
	v_mfma_f32_16x16x32_bf16 v[58:61], v[244:247], v[196:199], v[58:61]
	v_mfma_f32_16x16x32_bf16 v[54:57], v[236:239], v[222:225], v[54:57]
	v_mfma_f32_16x16x32_bf16 v[50:53], v[244:247], v[222:225], v[50:53]
	v_mfma_f32_16x16x32_bf16 v[94:97], v[240:243], v[184:187], v[94:97]
	v_mfma_f32_16x16x32_bf16 v[90:93], v[248:251], v[184:187], v[90:93]
	v_mfma_f32_16x16x32_bf16 v[86:89], v[240:243], v[192:195], v[86:89]
	v_mfma_f32_16x16x32_bf16 v[70:73], v[248:251], v[192:195], v[70:73]
	v_mfma_f32_16x16x32_bf16 v[62:65], v[240:243], v[200:203], v[62:65]
	v_mfma_f32_16x16x32_bf16 v[58:61], v[248:251], v[200:203], v[58:61]
	v_mfma_f32_16x16x32_bf16 v[54:57], v[240:243], v[232:235], v[54:57]
	v_mfma_f32_16x16x32_bf16 v[50:53], v[248:251], v[232:235], v[50:53]
	s_setprio 0
	v_lshl_add_u64 v[158:159], v[204:205], 0, s[74:75]
	s_mov_b32 m0, s1
	s_barrier
	ds_read_b128 v[180:183], v0 offset:16384
	ds_read_b128 v[184:187], v0 offset:17408
	ds_read_b128 v[188:191], v0 offset:18432
	ds_read_b128 v[192:195], v0 offset:19456
	ds_read_b128 v[196:199], v0 offset:20480
	ds_read_b128 v[200:203], v0 offset:21504
	ds_read_b128 v[222:225], v0 offset:22528
	ds_read_b128 v[232:235], v0 offset:23552
	global_load_lds_dwordx4 v[158:159], off
	s_add_i32 m0, s1, 0x1f00
	s_nop 0
	global_load_lds_dwordx4 v[210:211], off offset:256
	s_barrier
	s_waitcnt lgkmcnt(0)
	s_setprio 1
	v_mfma_f32_16x16x32_bf16 v[46:49], v[164:167], v[180:183], v[46:49]
	v_mfma_f32_16x16x32_bf16 v[42:45], v[172:175], v[180:183], v[42:45]
	v_mfma_f32_16x16x32_bf16 v[38:41], v[164:167], v[188:191], v[38:41]
	v_mfma_f32_16x16x32_bf16 v[34:37], v[172:175], v[188:191], v[34:37]
	v_mfma_f32_16x16x32_bf16 v[30:33], v[164:167], v[196:199], v[30:33]
	v_mfma_f32_16x16x32_bf16 v[26:29], v[172:175], v[196:199], v[26:29]
	v_mfma_f32_16x16x32_bf16 v[22:25], v[164:167], v[222:225], v[22:25]
	v_mfma_f32_16x16x32_bf16 v[18:21], v[172:175], v[222:225], v[18:21]
	v_mfma_f32_16x16x32_bf16 v[46:49], v[168:171], v[184:187], v[46:49]
	v_mfma_f32_16x16x32_bf16 v[42:45], v[176:179], v[184:187], v[42:45]
	v_mfma_f32_16x16x32_bf16 v[38:41], v[168:171], v[192:195], v[38:41]
	v_mfma_f32_16x16x32_bf16 v[34:37], v[176:179], v[192:195], v[34:37]
	v_mfma_f32_16x16x32_bf16 v[30:33], v[168:171], v[200:203], v[30:33]
	v_mfma_f32_16x16x32_bf16 v[26:29], v[176:179], v[200:203], v[26:29]
	v_mfma_f32_16x16x32_bf16 v[22:25], v[168:171], v[232:235], v[22:25]
	v_mfma_f32_16x16x32_bf16 v[18:21], v[176:179], v[232:235], v[18:21]
	s_setprio 0
	s_barrier
	s_add_i32 m0, s1, 0x14000
	v_lshl_add_u64 v[154:155], v[216:217], 0, s[18:19]
	global_load_lds_dwordx4 v[154:155], off
	s_add_i32 m0, s1, 0x16000
	v_lshl_add_u64 v[156:157], v[218:219], 0, s[18:19]
	global_load_lds_dwordx4 v[156:157], off
	s_waitcnt vmcnt(6)
	s_barrier
	s_setprio 1
	v_mfma_f32_16x16x32_bf16 v[14:17], v[236:239], v[180:183], v[14:17]
	v_mfma_f32_16x16x32_bf16 v[10:13], v[244:247], v[180:183], v[10:13]
	v_mfma_f32_16x16x32_bf16 v[6:9], v[236:239], v[188:191], v[6:9]
	v_mfma_f32_16x16x32_bf16 v[2:5], v[244:247], v[188:191], v[2:5]
	v_mfma_f32_16x16x32_bf16 v[66:69], v[236:239], v[196:199], v[66:69]
	v_mfma_f32_16x16x32_bf16 v[74:77], v[244:247], v[196:199], v[74:77]
	v_mfma_f32_16x16x32_bf16 v[78:81], v[236:239], v[222:225], v[78:81]
	v_mfma_f32_16x16x32_bf16 v[82:85], v[244:247], v[222:225], v[82:85]
	v_mfma_f32_16x16x32_bf16 v[14:17], v[240:243], v[184:187], v[14:17]
	v_mfma_f32_16x16x32_bf16 v[10:13], v[248:251], v[184:187], v[10:13]
	v_mfma_f32_16x16x32_bf16 v[6:9], v[240:243], v[192:195], v[6:9]
	v_mfma_f32_16x16x32_bf16 v[2:5], v[248:251], v[192:195], v[2:5]
	v_mfma_f32_16x16x32_bf16 v[66:69], v[240:243], v[200:203], v[66:69]
	v_mfma_f32_16x16x32_bf16 v[74:77], v[248:251], v[200:203], v[74:77]
	v_mfma_f32_16x16x32_bf16 v[78:81], v[240:243], v[232:235], v[78:81]
	v_mfma_f32_16x16x32_bf16 v[82:85], v[248:251], v[232:235], v[82:85]
	s_setprio 0
	s_barrier
	ds_read_b128 v[164:167], v151 offset:32768
	ds_read_b128 v[168:171], v151 offset:33792
	ds_read_b128 v[172:175], v151 offset:34816
	ds_read_b128 v[176:179], v151 offset:35840
	s_add_i32 m0, s1, 0x3f80
	ds_read_b128 v[180:183], v0 offset:32768
	ds_read_b128 v[184:187], v0 offset:33792
	ds_read_b128 v[188:191], v0 offset:34816
	ds_read_b128 v[192:195], v0 offset:35840
	ds_read_b128 v[196:199], v0 offset:36864
	ds_read_b128 v[200:203], v0 offset:37888
	ds_read_b128 v[222:225], v0 offset:38912
	ds_read_b128 v[232:235], v0 offset:39936
	global_load_lds_dwordx4 v[228:229], off offset:128
	s_add_i32 m0, s1, 0x5f80
	s_nop 0
	global_load_lds_dwordx4 v[152:153], off offset:128
	s_waitcnt lgkmcnt(8)
	s_barrier
	s_waitcnt lgkmcnt(0)
	s_setprio 1
	v_mfma_f32_16x16x32_bf16 v[126:129], v[164:167], v[180:183], v[126:129]
	v_mfma_f32_16x16x32_bf16 v[122:125], v[172:175], v[180:183], v[122:125]
	v_mfma_f32_16x16x32_bf16 v[118:121], v[164:167], v[188:191], v[118:121]
	v_mfma_f32_16x16x32_bf16 v[114:117], v[172:175], v[188:191], v[114:117]
	v_mfma_f32_16x16x32_bf16 v[110:113], v[164:167], v[196:199], v[110:113]
	v_mfma_f32_16x16x32_bf16 v[106:109], v[172:175], v[196:199], v[106:109]
	v_mfma_f32_16x16x32_bf16 v[102:105], v[164:167], v[222:225], v[102:105]
	v_mfma_f32_16x16x32_bf16 v[98:101], v[172:175], v[222:225], v[98:101]
	v_mfma_f32_16x16x32_bf16 v[126:129], v[168:171], v[184:187], v[126:129]
	v_mfma_f32_16x16x32_bf16 v[122:125], v[176:179], v[184:187], v[122:125]
	v_mfma_f32_16x16x32_bf16 v[118:121], v[168:171], v[192:195], v[118:121]
	v_mfma_f32_16x16x32_bf16 v[114:117], v[176:179], v[192:195], v[114:117]
	v_mfma_f32_16x16x32_bf16 v[110:113], v[168:171], v[200:203], v[110:113]
	v_mfma_f32_16x16x32_bf16 v[106:109], v[176:179], v[200:203], v[106:109]
	v_mfma_f32_16x16x32_bf16 v[102:105], v[168:171], v[232:235], v[102:105]
	v_mfma_f32_16x16x32_bf16 v[98:101], v[176:179], v[232:235], v[98:101]
	s_setprio 0
	s_barrier
	s_add_i32 m0, s1, 0x17e80
	ds_read_b128 v[236:239], v151 offset:49152
	ds_read_b128 v[240:243], v151 offset:50176
	ds_read_b128 v[244:247], v151 offset:51200
	ds_read_b128 v[248:251], v151 offset:52224
	global_load_lds_dwordx4 v[216:217], off offset:384
	s_add_i32 m0, s1, 0x19e80
	s_nop 0
	global_load_lds_dwordx4 v[218:219], off offset:384
	s_barrier
	s_waitcnt lgkmcnt(0)
	s_setprio 1
	v_mfma_f32_16x16x32_bf16 v[94:97], v[236:239], v[180:183], v[94:97]
	v_mfma_f32_16x16x32_bf16 v[90:93], v[244:247], v[180:183], v[90:93]
	v_mfma_f32_16x16x32_bf16 v[86:89], v[236:239], v[188:191], v[86:89]
	v_mfma_f32_16x16x32_bf16 v[70:73], v[244:247], v[188:191], v[70:73]
	v_mfma_f32_16x16x32_bf16 v[62:65], v[236:239], v[196:199], v[62:65]
	v_mfma_f32_16x16x32_bf16 v[58:61], v[244:247], v[196:199], v[58:61]
	v_mfma_f32_16x16x32_bf16 v[54:57], v[236:239], v[222:225], v[54:57]
	v_mfma_f32_16x16x32_bf16 v[50:53], v[244:247], v[222:225], v[50:53]
	v_mfma_f32_16x16x32_bf16 v[94:97], v[240:243], v[184:187], v[94:97]
	v_mfma_f32_16x16x32_bf16 v[90:93], v[248:251], v[184:187], v[90:93]
	v_mfma_f32_16x16x32_bf16 v[86:89], v[240:243], v[192:195], v[86:89]
	v_mfma_f32_16x16x32_bf16 v[70:73], v[248:251], v[192:195], v[70:73]
	v_mfma_f32_16x16x32_bf16 v[62:65], v[240:243], v[200:203], v[62:65]
	v_mfma_f32_16x16x32_bf16 v[58:61], v[248:251], v[200:203], v[58:61]
	v_mfma_f32_16x16x32_bf16 v[54:57], v[240:243], v[232:235], v[54:57]
	v_mfma_f32_16x16x32_bf16 v[50:53], v[248:251], v[232:235], v[50:53]
	s_setprio 0
	s_add_i32 m0, s1, 0x7e80
	s_barrier
	ds_read_b128 v[180:183], v0 offset:49152
	ds_read_b128 v[184:187], v0 offset:50176
	ds_read_b128 v[188:191], v0 offset:51200
	ds_read_b128 v[192:195], v0 offset:52224
	ds_read_b128 v[196:199], v0 offset:53248
	ds_read_b128 v[200:203], v0 offset:54272
	ds_read_b128 v[222:225], v0 offset:55296
	ds_read_b128 v[232:235], v0 offset:56320
	global_load_lds_dwordx4 v[204:205], off offset:384
	s_add_i32 m0, s1, 0x9e80
	s_nop 0
	global_load_lds_dwordx4 v[210:211], off offset:384
	s_barrier
	s_waitcnt lgkmcnt(0)
	s_setprio 1
	v_mfma_f32_16x16x32_bf16 v[46:49], v[164:167], v[180:183], v[46:49]
	v_mfma_f32_16x16x32_bf16 v[42:45], v[172:175], v[180:183], v[42:45]
	v_mfma_f32_16x16x32_bf16 v[38:41], v[164:167], v[188:191], v[38:41]
	v_mfma_f32_16x16x32_bf16 v[34:37], v[172:175], v[188:191], v[34:37]
	v_mfma_f32_16x16x32_bf16 v[30:33], v[164:167], v[196:199], v[30:33]
	v_mfma_f32_16x16x32_bf16 v[26:29], v[172:175], v[196:199], v[26:29]
	v_mfma_f32_16x16x32_bf16 v[22:25], v[164:167], v[222:225], v[22:25]
	v_mfma_f32_16x16x32_bf16 v[18:21], v[172:175], v[222:225], v[18:21]
	v_mfma_f32_16x16x32_bf16 v[46:49], v[168:171], v[184:187], v[46:49]
	v_mfma_f32_16x16x32_bf16 v[42:45], v[176:179], v[184:187], v[42:45]
	v_mfma_f32_16x16x32_bf16 v[38:41], v[168:171], v[192:195], v[38:41]
	v_mfma_f32_16x16x32_bf16 v[34:37], v[176:179], v[192:195], v[34:37]
	v_mfma_f32_16x16x32_bf16 v[30:33], v[168:171], v[200:203], v[30:33]
	v_mfma_f32_16x16x32_bf16 v[26:29], v[176:179], v[200:203], v[26:29]
	v_mfma_f32_16x16x32_bf16 v[22:25], v[168:171], v[232:235], v[22:25]
	v_mfma_f32_16x16x32_bf16 v[18:21], v[176:179], v[232:235], v[18:21]
	s_setprio 0
	s_barrier
	s_add_i32 m0, s1, 0x1bf80
	s_nop 0
	global_load_lds_dwordx4 v[154:155], off offset:128
	s_add_i32 m0, s1, 0x1df80
	s_nop 0
	global_load_lds_dwordx4 v[156:157], off offset:128
	s_waitcnt vmcnt(6)
	s_barrier
	s_setprio 1
	v_mfma_f32_16x16x32_bf16 v[14:17], v[236:239], v[180:183], v[14:17]
	v_mfma_f32_16x16x32_bf16 v[10:13], v[244:247], v[180:183], v[10:13]
	v_mfma_f32_16x16x32_bf16 v[6:9], v[236:239], v[188:191], v[6:9]
	v_mfma_f32_16x16x32_bf16 v[2:5], v[244:247], v[188:191], v[2:5]
	v_mfma_f32_16x16x32_bf16 v[66:69], v[236:239], v[196:199], v[66:69]
	v_mfma_f32_16x16x32_bf16 v[74:77], v[244:247], v[196:199], v[74:77]
	v_mfma_f32_16x16x32_bf16 v[78:81], v[236:239], v[222:225], v[78:81]
	v_mfma_f32_16x16x32_bf16 v[82:85], v[244:247], v[222:225], v[82:85]
	v_mfma_f32_16x16x32_bf16 v[14:17], v[240:243], v[184:187], v[14:17]
	v_mfma_f32_16x16x32_bf16 v[10:13], v[248:251], v[184:187], v[10:13]
	v_mfma_f32_16x16x32_bf16 v[6:9], v[240:243], v[192:195], v[6:9]
	v_mfma_f32_16x16x32_bf16 v[2:5], v[248:251], v[192:195], v[2:5]
	v_mfma_f32_16x16x32_bf16 v[66:69], v[240:243], v[200:203], v[66:69]
	v_mfma_f32_16x16x32_bf16 v[74:77], v[248:251], v[200:203], v[74:77]
	v_mfma_f32_16x16x32_bf16 v[78:81], v[240:243], v[232:235], v[78:81]
	v_mfma_f32_16x16x32_bf16 v[82:85], v[248:251], v[232:235], v[82:85]
	s_setprio 0
	s_add_i32 s0, s0, 2
	s_add_u32 s12, s12, 0x100
	s_addc_u32 s13, s13, 0
	s_cmp_lt_u32 s0, 28
	s_barrier
	s_cbranch_scc1 .LBB0_34
	s_add_i32 s1, s1, 0x1e000
	s_mov_b64 s[12:13], 0xf80
	v_readfirstlane_b32 s0, v162
	v_lshl_add_u64 v[132:133], v[132:133], 0, s[12:13]
	s_mov_b32 m0, s0
	v_readfirstlane_b32 s0, v163
	ds_read_b128 v[134:137], v151
	ds_read_b128 v[138:141], v151 offset:1024
	ds_read_b128 v[152:155], v151 offset:2048
	ds_read_b128 v[156:159], v151 offset:3072
	ds_read_b128 v[164:167], v0
	ds_read_b128 v[168:171], v0 offset:1024
	ds_read_b128 v[172:175], v0 offset:2048
	ds_read_b128 v[176:179], v0 offset:3072
	ds_read_b128 v[180:183], v0 offset:4096
	ds_read_b128 v[184:187], v0 offset:5120
	ds_read_b128 v[188:191], v0 offset:6144
	ds_read_b128 v[192:195], v0 offset:7168
	global_load_lds_dwordx4 v[132:133], off
	v_lshl_add_u64 v[130:131], v[130:131], 0, s[12:13]
	s_mov_b32 m0, s0
	s_nop 0
	global_load_lds_dwordx4 v[130:131], off
	s_barrier
	s_waitcnt lgkmcnt(0)
	s_setprio 1
	s_waitcnt lgkmcnt(0)
	v_mfma_f32_16x16x32_bf16 v[122:125], v[152:155], v[164:167], v[122:125]
	v_mfma_f32_16x16x32_bf16 v[118:121], v[134:137], v[172:175], v[118:121]
	v_mfma_f32_16x16x32_bf16 v[114:117], v[152:155], v[172:175], v[114:117]
	v_mfma_f32_16x16x32_bf16 v[102:105], v[134:137], v[188:191], v[102:105]
	v_mfma_f32_16x16x32_bf16 v[98:101], v[152:155], v[188:191], v[98:101]
	v_mfma_f32_16x16x32_bf16 v[126:129], v[134:137], v[164:167], v[126:129]
	v_mfma_f32_16x16x32_bf16 v[122:125], v[156:159], v[168:171], v[122:125]
	v_mfma_f32_16x16x32_bf16 v[118:121], v[138:141], v[176:179], v[118:121]
	v_mfma_f32_16x16x32_bf16 v[114:117], v[156:159], v[176:179], v[114:117]
	v_mfma_f32_16x16x32_bf16 v[110:113], v[134:137], v[180:183], v[110:113]
	v_mfma_f32_16x16x32_bf16 v[106:109], v[152:155], v[180:183], v[106:109]
	v_mfma_f32_16x16x32_bf16 v[102:105], v[138:141], v[192:195], v[102:105]
	v_mfma_f32_16x16x32_bf16 v[98:101], v[156:159], v[192:195], v[98:101]
	v_mfma_f32_16x16x32_bf16 v[126:129], v[138:141], v[168:171], v[126:129]
	v_mfma_f32_16x16x32_bf16 v[130:133], v[138:141], v[184:187], v[110:113]
	v_mfma_f32_16x16x32_bf16 v[160:163], v[156:159], v[184:187], v[106:109]
	s_setprio 0
	s_barrier
	ds_read_b128 v[106:109], v151 offset:16384
	ds_read_b128 v[110:113], v151 offset:17408
	ds_read_b128 v[196:199], v151 offset:18432
	ds_read_b128 v[200:203], v151 offset:19456
	s_barrier
	s_waitcnt lgkmcnt(0)
	s_setprio 1
	s_waitcnt lgkmcnt(3)
	v_mfma_f32_16x16x32_bf16 v[86:89], v[106:109], v[172:175], v[86:89]
	s_waitcnt lgkmcnt(1)
	v_mfma_f32_16x16x32_bf16 v[70:73], v[196:199], v[172:175], v[70:73]
	v_mfma_f32_16x16x32_bf16 v[62:65], v[106:109], v[180:183], v[62:65]
	v_mfma_f32_16x16x32_bf16 v[58:61], v[196:199], v[180:183], v[58:61]
	v_mfma_f32_16x16x32_bf16 v[54:57], v[106:109], v[188:191], v[54:57]
	v_mfma_f32_16x16x32_bf16 v[50:53], v[196:199], v[188:191], v[50:53]
	v_mfma_f32_16x16x32_bf16 v[94:97], v[106:109], v[164:167], v[94:97]
	v_mfma_f32_16x16x32_bf16 v[90:93], v[196:199], v[164:167], v[90:93]
	v_mfma_f32_16x16x32_bf16 v[86:89], v[110:113], v[176:179], v[86:89]
	s_waitcnt lgkmcnt(0)
	v_mfma_f32_16x16x32_bf16 v[70:73], v[200:203], v[176:179], v[70:73]
	v_mfma_f32_16x16x32_bf16 v[62:65], v[110:113], v[184:187], v[62:65]
	v_mfma_f32_16x16x32_bf16 v[58:61], v[200:203], v[184:187], v[58:61]
	v_mfma_f32_16x16x32_bf16 v[54:57], v[110:113], v[192:195], v[54:57]
	v_mfma_f32_16x16x32_bf16 v[50:53], v[200:203], v[192:195], v[50:53]
	v_mfma_f32_16x16x32_bf16 v[222:225], v[110:113], v[168:171], v[94:97]
	v_mfma_f32_16x16x32_bf16 v[164:167], v[200:203], v[168:171], v[90:93]
	s_setprio 0
	s_barrier
	s_nop 0
	ds_read_b128 v[90:93], v0 offset:16384
	ds_read_b128 v[94:97], v0 offset:17408
	ds_read_b128 v[168:171], v0 offset:18432
	ds_read_b128 v[172:175], v0 offset:19456
	ds_read_b128 v[176:179], v0 offset:20480
	ds_read_b128 v[180:183], v0 offset:21504
	ds_read_b128 v[184:187], v0 offset:22528
	ds_read_b128 v[188:191], v0 offset:23552
	s_waitcnt vmcnt(4)
	s_barrier
	s_waitcnt lgkmcnt(0)
	s_setprio 1
	s_waitcnt lgkmcnt(7)
	v_mfma_f32_16x16x32_bf16 v[46:49], v[134:137], v[90:93], v[46:49]
	v_mfma_f32_16x16x32_bf16 v[42:45], v[152:155], v[90:93], v[42:45]
	s_waitcnt lgkmcnt(5)
	v_mfma_f32_16x16x32_bf16 v[38:41], v[134:137], v[168:171], v[38:41]
	v_mfma_f32_16x16x32_bf16 v[34:37], v[152:155], v[168:171], v[34:37]
	s_waitcnt lgkmcnt(3)
	v_mfma_f32_16x16x32_bf16 v[30:33], v[134:137], v[176:179], v[30:33]
	v_mfma_f32_16x16x32_bf16 v[26:29], v[152:155], v[176:179], v[26:29]
	s_waitcnt lgkmcnt(1)
	v_mfma_f32_16x16x32_bf16 v[22:25], v[134:137], v[184:187], v[22:25]
	v_mfma_f32_16x16x32_bf16 v[18:21], v[152:155], v[184:187], v[18:21]
	v_mfma_f32_16x16x32_bf16 v[46:49], v[138:141], v[94:97], v[46:49]
	v_mfma_f32_16x16x32_bf16 v[42:45], v[156:159], v[94:97], v[42:45]
	v_mfma_f32_16x16x32_bf16 v[38:41], v[138:141], v[172:175], v[38:41]
	v_mfma_f32_16x16x32_bf16 v[34:37], v[156:159], v[172:175], v[34:37]
	v_mfma_f32_16x16x32_bf16 v[30:33], v[138:141], v[180:183], v[30:33]
	v_mfma_f32_16x16x32_bf16 v[26:29], v[156:159], v[180:183], v[26:29]
	s_waitcnt lgkmcnt(0)
	v_mfma_f32_16x16x32_bf16 v[22:25], v[138:141], v[188:191], v[22:25]
	v_mfma_f32_16x16x32_bf16 v[18:21], v[156:159], v[188:191], v[18:21]
	s_setprio 0
	s_setprio 1
	v_mfma_f32_16x16x32_bf16 v[10:13], v[196:199], v[90:93], v[10:13]
	v_mfma_f32_16x16x32_bf16 v[152:155], v[200:203], v[94:97], v[10:13]
	v_mfma_f32_16x16x32_bf16 v[10:13], v[106:109], v[176:179], v[66:69]
	v_mfma_f32_16x16x32_bf16 v[156:159], v[110:113], v[180:183], v[10:13]
	v_mfma_f32_16x16x32_bf16 v[10:13], v[196:199], v[176:179], v[74:77]
	v_mfma_f32_16x16x32_bf16 v[6:9], v[106:109], v[168:171], v[6:9]
	v_mfma_f32_16x16x32_bf16 v[2:5], v[196:199], v[168:171], v[2:5]
	v_mfma_f32_16x16x32_bf16 v[168:171], v[200:203], v[180:183], v[10:13]
	v_mfma_f32_16x16x32_bf16 v[10:13], v[106:109], v[184:187], v[78:81]
	v_mfma_f32_16x16x32_bf16 v[14:17], v[106:109], v[90:93], v[14:17]
	v_mfma_f32_16x16x32_bf16 v[6:9], v[110:113], v[172:175], v[6:9]
	v_mfma_f32_16x16x32_bf16 v[2:5], v[200:203], v[172:175], v[2:5]
	v_mfma_f32_16x16x32_bf16 v[172:175], v[110:113], v[188:191], v[10:13]
	v_mfma_f32_16x16x32_bf16 v[10:13], v[196:199], v[184:187], v[82:85]
	v_mfma_f32_16x16x32_bf16 v[134:137], v[110:113], v[94:97], v[14:17]
	v_mfma_f32_16x16x32_bf16 v[176:179], v[200:203], v[188:191], v[10:13]
	s_setprio 0
	s_barrier
	s_nop 3
	ds_read_b128 v[10:13], v151 offset:32768
	ds_read_b128 v[14:17], v151 offset:33792
	ds_read_b128 v[180:183], v151 offset:34816
	ds_read_b128 v[184:187], v151 offset:35840
	ds_read_b128 v[66:69], v0 offset:32768
	ds_read_b128 v[82:85], v0 offset:33792
	ds_read_b128 v[188:191], v0 offset:34816
	ds_read_b128 v[192:195], v0 offset:35840
	ds_read_b128 v[196:199], v0 offset:36864
	ds_read_b128 v[200:203], v0 offset:37888
	ds_read_b128 v[232:235], v0 offset:38912
	ds_read_b128 v[236:239], v0 offset:39936
	s_waitcnt vmcnt(2)
	s_barrier
	s_waitcnt lgkmcnt(0)
	s_setprio 1
	s_waitcnt lgkmcnt(7)
	v_mfma_f32_16x16x32_bf16 v[74:77], v[10:13], v[66:69], v[126:129]
	s_waitcnt lgkmcnt(6)
	v_mfma_f32_16x16x32_bf16 v[138:141], v[14:17], v[82:85], v[74:77]
	v_mfma_f32_16x16x32_bf16 v[74:77], v[180:183], v[66:69], v[122:125]
	v_mfma_f32_16x16x32_bf16 v[122:125], v[184:187], v[82:85], v[74:77]
	s_waitcnt lgkmcnt(5)
	v_mfma_f32_16x16x32_bf16 v[74:77], v[10:13], v[188:191], v[118:121]
	s_waitcnt lgkmcnt(4)
	v_mfma_f32_16x16x32_bf16 v[110:113], v[14:17], v[192:195], v[74:77]
	v_mfma_f32_16x16x32_bf16 v[74:77], v[180:183], v[188:191], v[114:117]
	v_mfma_f32_16x16x32_bf16 v[106:109], v[184:187], v[192:195], v[74:77]
	s_waitcnt lgkmcnt(3)
	v_mfma_f32_16x16x32_bf16 v[74:77], v[10:13], v[196:199], v[130:133]
	s_waitcnt lgkmcnt(2)
	v_mfma_f32_16x16x32_bf16 v[94:97], v[14:17], v[200:203], v[74:77]
	v_mfma_f32_16x16x32_bf16 v[74:77], v[180:183], v[196:199], v[160:163]
	v_mfma_f32_16x16x32_bf16 v[90:93], v[184:187], v[200:203], v[74:77]
	s_waitcnt lgkmcnt(1)
	v_mfma_f32_16x16x32_bf16 v[74:77], v[10:13], v[232:235], v[102:105]
	s_waitcnt lgkmcnt(0)
	v_mfma_f32_16x16x32_bf16 v[78:81], v[14:17], v[236:239], v[74:77]
	v_mfma_f32_16x16x32_bf16 v[74:77], v[180:183], v[232:235], v[98:101]
	v_mfma_f32_16x16x32_bf16 v[74:77], v[184:187], v[236:239], v[74:77]
	s_setprio 0
	s_barrier
	ds_read_b128 v[126:129], v151 offset:49152
	ds_read_b128 v[130:133], v151 offset:50176
	ds_read_b128 v[160:163], v151 offset:51200
	ds_read_b128 v[148:151], v151 offset:52224
	s_waitcnt vmcnt(0)
	s_barrier
	s_waitcnt lgkmcnt(0)
	s_setprio 1
	s_waitcnt lgkmcnt(3)
	v_mfma_f32_16x16x32_bf16 v[98:101], v[126:129], v[66:69], v[222:225]
	s_waitcnt lgkmcnt(1)
	v_mfma_f32_16x16x32_bf16 v[66:69], v[160:163], v[66:69], v[164:167]
	s_waitcnt lgkmcnt(0)
	v_mfma_f32_16x16x32_bf16 v[114:117], v[148:151], v[82:85], v[66:69]
	v_mfma_f32_16x16x32_bf16 v[66:69], v[126:129], v[188:191], v[86:89]
	v_mfma_f32_16x16x32_bf16 v[102:105], v[130:133], v[192:195], v[66:69]
	v_mfma_f32_16x16x32_bf16 v[66:69], v[160:163], v[188:191], v[70:73]
	v_mfma_f32_16x16x32_bf16 v[62:65], v[126:129], v[196:199], v[62:65]
	v_mfma_f32_16x16x32_bf16 v[58:61], v[160:163], v[196:199], v[58:61]
	v_mfma_f32_16x16x32_bf16 v[54:57], v[126:129], v[232:235], v[54:57]
	v_mfma_f32_16x16x32_bf16 v[50:53], v[160:163], v[232:235], v[50:53]
	v_mfma_f32_16x16x32_bf16 v[118:121], v[130:133], v[82:85], v[98:101]
	v_mfma_f32_16x16x32_bf16 v[98:101], v[148:151], v[192:195], v[66:69]
	v_mfma_f32_16x16x32_bf16 v[86:89], v[130:133], v[200:203], v[62:65]
	v_mfma_f32_16x16x32_bf16 v[82:85], v[148:151], v[200:203], v[58:61]
	v_mfma_f32_16x16x32_bf16 v[70:73], v[130:133], v[236:239], v[54:57]
	v_mfma_f32_16x16x32_bf16 v[66:69], v[148:151], v[236:239], v[50:53]
	s_setprio 0
	s_barrier
	s_nop 0
	ds_read_b128 v[50:53], v0 offset:49152
	ds_read_b128 v[164:167], v0 offset:50176
	ds_read_b128 v[188:191], v0 offset:51200
	ds_read_b128 v[192:195], v0 offset:52224
	ds_read_b128 v[196:199], v0 offset:53248
	ds_read_b128 v[200:203], v0 offset:54272
	ds_read_b128 v[222:225], v0 offset:55296
	ds_read_b128 v[232:235], v0 offset:56320
	s_barrier
	s_waitcnt lgkmcnt(0)
	s_setprio 1
	s_waitcnt lgkmcnt(7)
	v_mfma_f32_16x16x32_bf16 v[46:49], v[10:13], v[50:53], v[46:49]
	s_waitcnt lgkmcnt(5)
	v_mfma_f32_16x16x32_bf16 v[38:41], v[10:13], v[188:191], v[38:41]
	s_waitcnt lgkmcnt(3)
	v_mfma_f32_16x16x32_bf16 v[30:33], v[10:13], v[196:199], v[30:33]
	s_waitcnt lgkmcnt(1)
	v_mfma_f32_16x16x32_bf16 v[10:13], v[10:13], v[222:225], v[22:25]
	v_mfma_f32_16x16x32_bf16 v[62:65], v[14:17], v[164:167], v[46:49]
	v_mfma_f32_16x16x32_bf16 v[42:45], v[180:183], v[50:53], v[42:45]
	v_mfma_f32_16x16x32_bf16 v[46:49], v[14:17], v[192:195], v[38:41]
	v_mfma_f32_16x16x32_bf16 v[34:37], v[180:183], v[188:191], v[34:37]
	v_mfma_f32_16x16x32_bf16 v[30:33], v[14:17], v[200:203], v[30:33]
	v_mfma_f32_16x16x32_bf16 v[26:29], v[180:183], v[196:199], v[26:29]
	s_waitcnt lgkmcnt(0)
	v_mfma_f32_16x16x32_bf16 v[14:17], v[14:17], v[232:235], v[10:13]
	v_mfma_f32_16x16x32_bf16 v[10:13], v[180:183], v[222:225], v[18:21]
	v_mfma_f32_16x16x32_bf16 v[58:61], v[184:187], v[164:167], v[42:45]
	v_mfma_f32_16x16x32_bf16 v[42:45], v[184:187], v[192:195], v[34:37]
	v_mfma_f32_16x16x32_bf16 v[26:29], v[184:187], v[200:203], v[26:29]
	v_mfma_f32_16x16x32_bf16 v[10:13], v[184:187], v[232:235], v[10:13]
	s_setprio 0
	s_setprio 1
	v_mfma_f32_16x16x32_bf16 v[2:5], v[160:163], v[188:191], v[2:5]
	v_mfma_f32_16x16x32_bf16 v[18:21], v[126:129], v[50:53], v[134:137]
	v_mfma_f32_16x16x32_bf16 v[34:37], v[148:151], v[192:195], v[2:5]
	v_mfma_f32_16x16x32_bf16 v[2:5], v[126:129], v[196:199], v[156:159]
	v_mfma_f32_16x16x32_bf16 v[54:57], v[130:133], v[164:167], v[18:21]
	v_mfma_f32_16x16x32_bf16 v[18:21], v[160:163], v[50:53], v[152:155]
	v_mfma_f32_16x16x32_bf16 v[22:25], v[130:133], v[200:203], v[2:5]
	v_mfma_f32_16x16x32_bf16 v[2:5], v[160:163], v[196:199], v[168:171]
	v_mfma_f32_16x16x32_bf16 v[50:53], v[148:151], v[164:167], v[18:21]
	v_mfma_f32_16x16x32_bf16 v[6:9], v[126:129], v[188:191], v[6:9]
	v_mfma_f32_16x16x32_bf16 v[18:21], v[148:151], v[200:203], v[2:5]
	v_mfma_f32_16x16x32_bf16 v[2:5], v[126:129], v[222:225], v[172:175]
	v_mfma_f32_16x16x32_bf16 v[38:41], v[130:133], v[192:195], v[6:9]
	v_mfma_f32_16x16x32_bf16 v[6:9], v[130:133], v[232:235], v[2:5]
	v_mfma_f32_16x16x32_bf16 v[2:5], v[160:163], v[222:225], v[176:179]
	v_mfma_f32_16x16x32_bf16 v[2:5], v[148:151], v[232:235], v[2:5]
	s_setprio 0
	s_movk_i32 s0, 0x100
	v_cmp_gt_u32_e32 vcc, s0, v142
	s_barrier
	s_and_saveexec_b64 s[0:1], vcc
	s_cbranch_execz .LBB0_37
	s_barrier

.LBB0_84:
	s_or_b64 exec, exec, s[52:53]
	v_mov_b32_e32 v3, v1
	v_lshl_add_u64 v[12:13], s[0:1], 0, v[2:3]
	v_lshl_add_u64 v[16:17], s[12:13], 0, v[2:3]
	v_lshl_add_u64 v[20:21], s[14:15], 0, v[2:3]
	v_lshl_add_u64 v[130:131], s[16:17], 0, v[2:3]
	v_and_b32_e32 v146, 15, v142
	v_bfe_u32 v145, v142, 4, 2
	v_lshlrev_b32_e32 v3, 2, v142
	v_add_u32_e32 v156, 0x18000, v147
	v_lshl_add_u64 v[10:11], s[0:1], 0, v[0:1]
	v_lshl_add_u64 v[14:15], s[12:13], 0, v[0:1]
	v_lshl_add_u64 v[18:19], s[14:15], 0, v[0:1]
	v_lshl_add_u64 v[132:133], s[16:17], 0, v[0:1]
	v_lshlrev_b32_e32 v0, 6, v146
	v_lshlrev_b32_e32 v2, 4, v145
	v_and_b32_e32 v3, 32, v3
	s_mov_b64 s[12:13], 0x80
	v_readfirstlane_b32 s0, v156
	v_add_u32_e32 v157, 0x1a000, v147
	v_bitop3_b32 v22, v2, v3, v0 bitop3:0x36
	v_lshl_add_u64 v[2:3], v[10:11], 0, s[12:13]
	s_mov_b32 m0, s0
	v_readfirstlane_b32 s0, v157
	v_add_u32_e32 v158, 0x8000, v147
	s_waitcnt vmcnt(4)
	s_barrier
	global_load_lds_dwordx4 v[2:3], off
	v_lshl_add_u64 v[2:3], v[12:13], 0, s[12:13]
	s_mov_b32 m0, s0
	v_readfirstlane_b32 s0, v158
	v_add_u32_e32 v159, 0xa000, v147
	global_load_lds_dwordx4 v[2:3], off
	v_lshl_add_u64 v[2:3], v[14:15], 0, s[12:13]
	s_mov_b32 m0, s0
	v_readfirstlane_b32 s0, v159
	v_add_u32_e32 v160, 0x1c000, v147
	global_load_lds_dwordx4 v[2:3], off
	v_lshl_add_u64 v[2:3], v[16:17], 0, s[12:13]
	s_mov_b32 m0, s0
	v_readfirstlane_b32 s0, v160
	v_add_u32_e32 v161, 0x1e000, v147
	global_load_lds_dwordx4 v[2:3], off
	v_lshl_add_u64 v[2:3], v[18:19], 0, s[12:13]
	s_mov_b32 m0, s0
	v_readfirstlane_b32 s0, v161
	global_load_lds_dwordx4 v[2:3], off
	v_lshl_add_u64 v[2:3], v[20:21], 0, s[12:13]
	s_mov_b32 m0, s0
	s_sub_i32 s1, s57, s64
	global_load_lds_dwordx4 v[2:3], off
	s_sub_i32 s1, s1, s63
	v_lshlrev_b32_e32 v0, 15, v4
	s_sext_i32_i16 s1, s1
	v_and_b32_e32 v0, 0xffff0000, v0
	s_lshl_b32 s0, s62, 10
	s_lshl_b32 s1, s1, 8
	v_lshl_add_u32 v0, v5, 12, v0
	v_and_b32_e32 v2, 1, v4
	s_add_i32 s0, s0, s1
	v_lshl_or_b32 v0, v2, 6, v0
	v_lshlrev_b32_e32 v2, 15, v6
	s_ashr_i32 s1, s0, 31
	v_and_b32_e32 v2, 0xffff0000, v2
	s_lshl_b64 s[0:1], s[0:1], 12
	v_lshl_add_u32 v2, v8, 12, v2
	v_and_b32_e32 v3, 1, v6
	s_add_u32 s0, s4, s0
	v_lshl_or_b32 v2, v3, 6, v2
	v_lshl_add_u32 v0, v7, 1, v0
	s_addc_u32 s1, s5, s1
	v_lshl_add_u32 v2, v9, 1, v2
	v_mov_b32_e32 v3, v1
	s_waitcnt vmcnt(6)
	v_lshl_add_u64 v[134:135], s[0:1], 0, v[0:1]
	v_lshl_add_u64 v[136:137], s[0:1], 0, v[2:3]
	s_add_u32 s0, s88, s10
	v_bfe_u32 v144, v142, 6, 2
	s_addc_u32 s1, s89, s11
	v_lshlrev_b32_e32 v23, 13, v143
	v_lshl_or_b32 v24, v144, 12, v212
	v_lshl_add_u64 v[140:141], s[0:1], 0, v[2:3]
	v_mov_b32_e32 v2, 0
	s_barrier
	v_lshl_add_u64 v[138:139], s[0:1], 0, v[0:1]
	s_mov_b32 s0, -2
	s_mov_b64 s[10:11], 0
	v_add_u32_e32 v151, v24, v22
	v_add_u32_e32 v0, v23, v22
	v_mov_b32_e32 v3, v2
	v_mov_b32_e32 v4, v2
	v_mov_b32_e32 v5, v2
	v_mov_b32_e32 v6, v2
	v_mov_b32_e32 v7, v2
	v_mov_b32_e32 v8, v2
	v_mov_b32_e32 v9, v2
	v_mov_b32_e32 v10, v2
	v_mov_b32_e32 v11, v2
	v_mov_b32_e32 v12, v2
	v_mov_b32_e32 v13, v2
	v_mov_b32_e32 v14, v2
	v_mov_b32_e32 v15, v2
	v_mov_b32_e32 v16, v2
	v_mov_b32_e32 v17, v2
	v_mov_b32_e32 v18, v2
	v_mov_b32_e32 v19, v2
	v_mov_b32_e32 v20, v2
	v_mov_b32_e32 v21, v2
	v_mov_b32_e32 v22, v2
	v_mov_b32_e32 v23, v2
	v_mov_b32_e32 v24, v2
	v_mov_b32_e32 v25, v2
	v_mov_b32_e32 v26, v2
	v_mov_b32_e32 v27, v2
	v_mov_b32_e32 v28, v2
	v_mov_b32_e32 v29, v2
	v_mov_b32_e32 v30, v2
	v_mov_b32_e32 v31, v2
	v_mov_b32_e32 v32, v2
	v_mov_b32_e32 v33, v2
	v_mov_b32_e32 v34, v2
	v_mov_b32_e32 v35, v2
	v_mov_b32_e32 v36, v2
	v_mov_b32_e32 v37, v2
	v_mov_b32_e32 v38, v2
	v_mov_b32_e32 v39, v2
	v_mov_b32_e32 v40, v2
	v_mov_b32_e32 v41, v2
	v_mov_b32_e32 v42, v2
	v_mov_b32_e32 v43, v2
	v_mov_b32_e32 v44, v2
	v_mov_b32_e32 v45, v2
	v_mov_b32_e32 v46, v2
	v_mov_b32_e32 v47, v2
	v_mov_b32_e32 v48, v2
	v_mov_b32_e32 v49, v2
	v_mov_b32_e32 v50, v2
	v_mov_b32_e32 v51, v2
	v_mov_b32_e32 v52, v2
	v_mov_b32_e32 v53, v2
	v_mov_b32_e32 v54, v2
	v_mov_b32_e32 v55, v2
	v_mov_b32_e32 v56, v2
	v_mov_b32_e32 v57, v2
	v_mov_b32_e32 v58, v2
	v_mov_b32_e32 v59, v2
	v_mov_b32_e32 v60, v2
	v_mov_b32_e32 v61, v2
	v_mov_b32_e32 v62, v2
	v_mov_b32_e32 v63, v2
	v_mov_b32_e32 v64, v2
	v_mov_b32_e32 v65, v2
	v_mov_b32_e32 v66, v2
	v_mov_b32_e32 v67, v2
	v_mov_b32_e32 v68, v2
	v_mov_b32_e32 v69, v2
	v_mov_b32_e32 v70, v2
	v_mov_b32_e32 v71, v2
	v_mov_b32_e32 v72, v2
	v_mov_b32_e32 v73, v2
	v_mov_b32_e32 v74, v2
	v_mov_b32_e32 v75, v2
	v_mov_b32_e32 v76, v2
	v_mov_b32_e32 v77, v2
	v_mov_b32_e32 v78, v2
	v_mov_b32_e32 v79, v2
	v_mov_b32_e32 v80, v2
	v_mov_b32_e32 v81, v2
	v_mov_b32_e32 v82, v2
	v_mov_b32_e32 v83, v2
	v_mov_b32_e32 v84, v2
	v_mov_b32_e32 v85, v2
	v_mov_b32_e32 v86, v2
	v_mov_b32_e32 v87, v2
	v_mov_b32_e32 v88, v2
	v_mov_b32_e32 v89, v2
	v_mov_b32_e32 v90, v2
	v_mov_b32_e32 v91, v2
	v_mov_b32_e32 v92, v2
	v_mov_b32_e32 v93, v2
	v_mov_b32_e32 v94, v2
	v_mov_b32_e32 v95, v2
	v_mov_b32_e32 v96, v2
	v_mov_b32_e32 v97, v2
	v_mov_b32_e32 v98, v2
	v_mov_b32_e32 v99, v2
	v_mov_b32_e32 v100, v2
	v_mov_b32_e32 v101, v2
	v_mov_b32_e32 v102, v2
	v_mov_b32_e32 v103, v2
	v_mov_b32_e32 v104, v2
	v_mov_b32_e32 v105, v2
	v_mov_b32_e32 v106, v2
	v_mov_b32_e32 v107, v2
	v_mov_b32_e32 v108, v2
	v_mov_b32_e32 v109, v2
	v_mov_b32_e32 v110, v2
	v_mov_b32_e32 v111, v2
	v_mov_b32_e32 v112, v2
	v_mov_b32_e32 v113, v2
	v_mov_b32_e32 v114, v2
	v_mov_b32_e32 v115, v2
	v_mov_b32_e32 v116, v2
	v_mov_b32_e32 v117, v2
	v_mov_b32_e32 v118, v2
	v_mov_b32_e32 v119, v2
	v_mov_b32_e32 v120, v2
	v_mov_b32_e32 v121, v2
	v_mov_b32_e32 v122, v2
	v_mov_b32_e32 v123, v2
	v_mov_b32_e32 v124, v2
	v_mov_b32_e32 v125, v2
	v_mov_b32_e32 v126, v2
	v_mov_b32_e32 v127, v2
	v_mov_b32_e32 v128, v2
	v_mov_b32_e32 v129, v2
	v_add_u32_e32 v162, 0xc000, v147
	v_add_u32_e32 v163, 0xe000, v147
	v_readfirstlane_b32 s1, v147
	s_nop 1
.LBB0_85:
	ds_read_b128 v[164:167], v151
	ds_read_b128 v[168:171], v151 offset:1024
	ds_read_b128 v[172:175], v151 offset:2048
	ds_read_b128 v[176:179], v151 offset:3072
	v_lshl_add_u64 v[204:205], v[138:139], 0, s[10:11]
	v_lshl_add_u64 v[228:229], v[204:205], 0, s[60:61]
	s_add_i32 m0, s1, 0xc000
	ds_read_b128 v[180:183], v0
	ds_read_b128 v[184:187], v0 offset:1024
	ds_read_b128 v[188:191], v0 offset:2048
	ds_read_b128 v[192:195], v0 offset:3072
	ds_read_b128 v[196:199], v0 offset:4096
	ds_read_b128 v[200:203], v0 offset:5120
	ds_read_b128 v[222:225], v0 offset:6144
	ds_read_b128 v[232:235], v0 offset:7168
	global_load_lds_dwordx4 v[228:229], off
	v_lshl_add_u64 v[210:211], v[140:141], 0, s[10:11]
	s_add_i32 m0, s1, 0xe000
	v_lshl_add_u64 v[152:153], v[210:211], 0, s[60:61]
	global_load_lds_dwordx4 v[152:153], off
	s_waitcnt lgkmcnt(8)
	s_barrier
	s_waitcnt lgkmcnt(0)
	s_setprio 1
	v_mfma_f32_16x16x32_bf16 v[126:129], v[164:167], v[180:183], v[126:129]
	v_mfma_f32_16x16x32_bf16 v[122:125], v[172:175], v[180:183], v[122:125]
	v_mfma_f32_16x16x32_bf16 v[118:121], v[164:167], v[188:191], v[118:121]
	v_mfma_f32_16x16x32_bf16 v[114:117], v[172:175], v[188:191], v[114:117]
	v_mfma_f32_16x16x32_bf16 v[110:113], v[164:167], v[196:199], v[110:113]
	v_mfma_f32_16x16x32_bf16 v[106:109], v[172:175], v[196:199], v[106:109]
	v_mfma_f32_16x16x32_bf16 v[102:105], v[164:167], v[222:225], v[102:105]
	v_mfma_f32_16x16x32_bf16 v[98:101], v[172:175], v[222:225], v[98:101]
	v_mfma_f32_16x16x32_bf16 v[126:129], v[168:171], v[184:187], v[126:129]
	v_mfma_f32_16x16x32_bf16 v[122:125], v[176:179], v[184:187], v[122:125]
	v_mfma_f32_16x16x32_bf16 v[118:121], v[168:171], v[192:195], v[118:121]
	v_mfma_f32_16x16x32_bf16 v[114:117], v[176:179], v[192:195], v[114:117]
	v_mfma_f32_16x16x32_bf16 v[110:113], v[168:171], v[200:203], v[110:113]
	v_mfma_f32_16x16x32_bf16 v[106:109], v[176:179], v[200:203], v[106:109]
	v_mfma_f32_16x16x32_bf16 v[102:105], v[168:171], v[232:235], v[102:105]
	v_mfma_f32_16x16x32_bf16 v[98:101], v[176:179], v[232:235], v[98:101]
	s_setprio 0
	s_barrier
	v_lshl_add_u64 v[216:217], v[134:135], 0, s[10:11]
	s_add_i32 m0, s1, 0xff00
	ds_read_b128 v[236:239], v151 offset:16384
	ds_read_b128 v[240:243], v151 offset:17408
	ds_read_b128 v[244:247], v151 offset:18432
	ds_read_b128 v[248:251], v151 offset:19456
	global_load_lds_dwordx4 v[216:217], off offset:256
	s_add_i32 m0, s1, 0x11f00
	v_lshl_add_u64 v[218:219], v[136:137], 0, s[10:11]
	global_load_lds_dwordx4 v[218:219], off offset:256
	s_barrier
	s_waitcnt lgkmcnt(0)
	s_setprio 1
	v_mfma_f32_16x16x32_bf16 v[94:97], v[236:239], v[180:183], v[94:97]
	v_mfma_f32_16x16x32_bf16 v[90:93], v[244:247], v[180:183], v[90:93]
	v_mfma_f32_16x16x32_bf16 v[86:89], v[236:239], v[188:191], v[86:89]
	v_mfma_f32_16x16x32_bf16 v[82:85], v[244:247], v[188:191], v[82:85]
	v_mfma_f32_16x16x32_bf16 v[78:81], v[236:239], v[196:199], v[78:81]
	v_mfma_f32_16x16x32_bf16 v[74:77], v[244:247], v[196:199], v[74:77]
	v_mfma_f32_16x16x32_bf16 v[70:73], v[236:239], v[222:225], v[70:73]
	v_mfma_f32_16x16x32_bf16 v[66:69], v[244:247], v[222:225], v[66:69]
	v_mfma_f32_16x16x32_bf16 v[94:97], v[240:243], v[184:187], v[94:97]
	v_mfma_f32_16x16x32_bf16 v[90:93], v[248:251], v[184:187], v[90:93]
	v_mfma_f32_16x16x32_bf16 v[86:89], v[240:243], v[192:195], v[86:89]
	v_mfma_f32_16x16x32_bf16 v[82:85], v[248:251], v[192:195], v[82:85]
	v_mfma_f32_16x16x32_bf16 v[78:81], v[240:243], v[200:203], v[78:81]
	v_mfma_f32_16x16x32_bf16 v[74:77], v[248:251], v[200:203], v[74:77]
	v_mfma_f32_16x16x32_bf16 v[70:73], v[240:243], v[232:235], v[70:73]
	v_mfma_f32_16x16x32_bf16 v[66:69], v[248:251], v[232:235], v[66:69]
	s_setprio 0
	v_lshl_add_u64 v[158:159], v[204:205], 0, s[74:75]
	s_mov_b32 m0, s1
	s_barrier
	ds_read_b128 v[180:183], v0 offset:16384
	ds_read_b128 v[184:187], v0 offset:17408
	ds_read_b128 v[188:191], v0 offset:18432
	ds_read_b128 v[192:195], v0 offset:19456
	ds_read_b128 v[196:199], v0 offset:20480
	ds_read_b128 v[200:203], v0 offset:21504
	ds_read_b128 v[222:225], v0 offset:22528
	ds_read_b128 v[232:235], v0 offset:23552
	global_load_lds_dwordx4 v[158:159], off
	s_add_i32 m0, s1, 0x1f00
	s_nop 0
	global_load_lds_dwordx4 v[210:211], off offset:256
	s_barrier
	s_waitcnt lgkmcnt(0)
	s_setprio 1
	v_mfma_f32_16x16x32_bf16 v[62:65], v[164:167], v[180:183], v[62:65]
	v_mfma_f32_16x16x32_bf16 v[58:61], v[172:175], v[180:183], v[58:61]
	v_mfma_f32_16x16x32_bf16 v[54:57], v[164:167], v[188:191], v[54:57]
	v_mfma_f32_16x16x32_bf16 v[50:53], v[172:175], v[188:191], v[50:53]
	v_mfma_f32_16x16x32_bf16 v[46:49], v[164:167], v[196:199], v[46:49]
	v_mfma_f32_16x16x32_bf16 v[42:45], v[172:175], v[196:199], v[42:45]
	v_mfma_f32_16x16x32_bf16 v[38:41], v[164:167], v[222:225], v[38:41]
	v_mfma_f32_16x16x32_bf16 v[34:37], v[172:175], v[222:225], v[34:37]
	v_mfma_f32_16x16x32_bf16 v[62:65], v[168:171], v[184:187], v[62:65]
	v_mfma_f32_16x16x32_bf16 v[58:61], v[176:179], v[184:187], v[58:61]
	v_mfma_f32_16x16x32_bf16 v[54:57], v[168:171], v[192:195], v[54:57]
	v_mfma_f32_16x16x32_bf16 v[50:53], v[176:179], v[192:195], v[50:53]
	v_mfma_f32_16x16x32_bf16 v[46:49], v[168:171], v[200:203], v[46:49]
	v_mfma_f32_16x16x32_bf16 v[42:45], v[176:179], v[200:203], v[42:45]
	v_mfma_f32_16x16x32_bf16 v[38:41], v[168:171], v[232:235], v[38:41]
	v_mfma_f32_16x16x32_bf16 v[34:37], v[176:179], v[232:235], v[34:37]
	s_setprio 0
	s_barrier
	s_add_i32 m0, s1, 0x14000
	v_lshl_add_u64 v[154:155], v[216:217], 0, s[18:19]
	global_load_lds_dwordx4 v[154:155], off
	s_add_i32 m0, s1, 0x16000
	v_lshl_add_u64 v[156:157], v[218:219], 0, s[18:19]
	global_load_lds_dwordx4 v[156:157], off
	s_waitcnt vmcnt(6)
	s_barrier
	s_setprio 1
	v_mfma_f32_16x16x32_bf16 v[30:33], v[236:239], v[180:183], v[30:33]
	v_mfma_f32_16x16x32_bf16 v[26:29], v[244:247], v[180:183], v[26:29]
	v_mfma_f32_16x16x32_bf16 v[22:25], v[236:239], v[188:191], v[22:25]
	v_mfma_f32_16x16x32_bf16 v[18:21], v[244:247], v[188:191], v[18:21]
	v_mfma_f32_16x16x32_bf16 v[14:17], v[236:239], v[196:199], v[14:17]
	v_mfma_f32_16x16x32_bf16 v[10:13], v[244:247], v[196:199], v[10:13]
	v_mfma_f32_16x16x32_bf16 v[6:9], v[236:239], v[222:225], v[6:9]
	v_mfma_f32_16x16x32_bf16 v[2:5], v[244:247], v[222:225], v[2:5]
	v_mfma_f32_16x16x32_bf16 v[30:33], v[240:243], v[184:187], v[30:33]
	v_mfma_f32_16x16x32_bf16 v[26:29], v[248:251], v[184:187], v[26:29]
	v_mfma_f32_16x16x32_bf16 v[22:25], v[240:243], v[192:195], v[22:25]
	v_mfma_f32_16x16x32_bf16 v[18:21], v[248:251], v[192:195], v[18:21]
	v_mfma_f32_16x16x32_bf16 v[14:17], v[240:243], v[200:203], v[14:17]
	v_mfma_f32_16x16x32_bf16 v[10:13], v[248:251], v[200:203], v[10:13]
	v_mfma_f32_16x16x32_bf16 v[6:9], v[240:243], v[232:235], v[6:9]
	v_mfma_f32_16x16x32_bf16 v[2:5], v[248:251], v[232:235], v[2:5]
	s_setprio 0
	s_barrier
	ds_read_b128 v[164:167], v151 offset:32768
	ds_read_b128 v[168:171], v151 offset:33792
	ds_read_b128 v[172:175], v151 offset:34816
	ds_read_b128 v[176:179], v151 offset:35840
	s_add_i32 m0, s1, 0x3f80
	ds_read_b128 v[180:183], v0 offset:32768
	ds_read_b128 v[184:187], v0 offset:33792
	ds_read_b128 v[188:191], v0 offset:34816
	ds_read_b128 v[192:195], v0 offset:35840
	ds_read_b128 v[196:199], v0 offset:36864
	ds_read_b128 v[200:203], v0 offset:37888
	ds_read_b128 v[222:225], v0 offset:38912
	ds_read_b128 v[232:235], v0 offset:39936
	global_load_lds_dwordx4 v[228:229], off offset:128
	s_add_i32 m0, s1, 0x5f80
	s_nop 0
	global_load_lds_dwordx4 v[152:153], off offset:128
	s_waitcnt lgkmcnt(8)
	s_barrier
	s_waitcnt lgkmcnt(0)
	s_setprio 1
	v_mfma_f32_16x16x32_bf16 v[126:129], v[164:167], v[180:183], v[126:129]
	v_mfma_f32_16x16x32_bf16 v[122:125], v[172:175], v[180:183], v[122:125]
	v_mfma_f32_16x16x32_bf16 v[118:121], v[164:167], v[188:191], v[118:121]
	v_mfma_f32_16x16x32_bf16 v[114:117], v[172:175], v[188:191], v[114:117]
	v_mfma_f32_16x16x32_bf16 v[110:113], v[164:167], v[196:199], v[110:113]
	v_mfma_f32_16x16x32_bf16 v[106:109], v[172:175], v[196:199], v[106:109]
	v_mfma_f32_16x16x32_bf16 v[102:105], v[164:167], v[222:225], v[102:105]
	v_mfma_f32_16x16x32_bf16 v[98:101], v[172:175], v[222:225], v[98:101]
	v_mfma_f32_16x16x32_bf16 v[126:129], v[168:171], v[184:187], v[126:129]
	v_mfma_f32_16x16x32_bf16 v[122:125], v[176:179], v[184:187], v[122:125]
	v_mfma_f32_16x16x32_bf16 v[118:121], v[168:171], v[192:195], v[118:121]
	v_mfma_f32_16x16x32_bf16 v[114:117], v[176:179], v[192:195], v[114:117]
	v_mfma_f32_16x16x32_bf16 v[110:113], v[168:171], v[200:203], v[110:113]
	v_mfma_f32_16x16x32_bf16 v[106:109], v[176:179], v[200:203], v[106:109]
	v_mfma_f32_16x16x32_bf16 v[102:105], v[168:171], v[232:235], v[102:105]
	v_mfma_f32_16x16x32_bf16 v[98:101], v[176:179], v[232:235], v[98:101]
	s_setprio 0
	s_barrier
	s_add_i32 m0, s1, 0x17e80
	ds_read_b128 v[236:239], v151 offset:49152
	ds_read_b128 v[240:243], v151 offset:50176
	ds_read_b128 v[244:247], v151 offset:51200
	ds_read_b128 v[248:251], v151 offset:52224
	global_load_lds_dwordx4 v[216:217], off offset:384
	s_add_i32 m0, s1, 0x19e80
	s_nop 0
	global_load_lds_dwordx4 v[218:219], off offset:384
	s_barrier
	s_waitcnt lgkmcnt(0)
	s_setprio 1
	v_mfma_f32_16x16x32_bf16 v[94:97], v[236:239], v[180:183], v[94:97]
	v_mfma_f32_16x16x32_bf16 v[90:93], v[244:247], v[180:183], v[90:93]
	v_mfma_f32_16x16x32_bf16 v[86:89], v[236:239], v[188:191], v[86:89]
	v_mfma_f32_16x16x32_bf16 v[82:85], v[244:247], v[188:191], v[82:85]
	v_mfma_f32_16x16x32_bf16 v[78:81], v[236:239], v[196:199], v[78:81]
	v_mfma_f32_16x16x32_bf16 v[74:77], v[244:247], v[196:199], v[74:77]
	v_mfma_f32_16x16x32_bf16 v[70:73], v[236:239], v[222:225], v[70:73]
	v_mfma_f32_16x16x32_bf16 v[66:69], v[244:247], v[222:225], v[66:69]
	v_mfma_f32_16x16x32_bf16 v[94:97], v[240:243], v[184:187], v[94:97]
	v_mfma_f32_16x16x32_bf16 v[90:93], v[248:251], v[184:187], v[90:93]
	v_mfma_f32_16x16x32_bf16 v[86:89], v[240:243], v[192:195], v[86:89]
	v_mfma_f32_16x16x32_bf16 v[82:85], v[248:251], v[192:195], v[82:85]
	v_mfma_f32_16x16x32_bf16 v[78:81], v[240:243], v[200:203], v[78:81]
	v_mfma_f32_16x16x32_bf16 v[74:77], v[248:251], v[200:203], v[74:77]
	v_mfma_f32_16x16x32_bf16 v[70:73], v[240:243], v[232:235], v[70:73]
	v_mfma_f32_16x16x32_bf16 v[66:69], v[248:251], v[232:235], v[66:69]
	s_setprio 0
	s_add_i32 m0, s1, 0x7e80
	s_barrier
	ds_read_b128 v[180:183], v0 offset:49152
	ds_read_b128 v[184:187], v0 offset:50176
	ds_read_b128 v[188:191], v0 offset:51200
	ds_read_b128 v[192:195], v0 offset:52224
	ds_read_b128 v[196:199], v0 offset:53248
	ds_read_b128 v[200:203], v0 offset:54272
	ds_read_b128 v[222:225], v0 offset:55296
	ds_read_b128 v[232:235], v0 offset:56320
	global_load_lds_dwordx4 v[204:205], off offset:384
	s_add_i32 m0, s1, 0x9e80
	s_nop 0
	global_load_lds_dwordx4 v[210:211], off offset:384
	s_barrier
	s_waitcnt lgkmcnt(0)
	s_setprio 1
	v_mfma_f32_16x16x32_bf16 v[62:65], v[164:167], v[180:183], v[62:65]
	v_mfma_f32_16x16x32_bf16 v[58:61], v[172:175], v[180:183], v[58:61]
	v_mfma_f32_16x16x32_bf16 v[54:57], v[164:167], v[188:191], v[54:57]
	v_mfma_f32_16x16x32_bf16 v[50:53], v[172:175], v[188:191], v[50:53]
	v_mfma_f32_16x16x32_bf16 v[46:49], v[164:167], v[196:199], v[46:49]
	v_mfma_f32_16x16x32_bf16 v[42:45], v[172:175], v[196:199], v[42:45]
	v_mfma_f32_16x16x32_bf16 v[38:41], v[164:167], v[222:225], v[38:41]
	v_mfma_f32_16x16x32_bf16 v[34:37], v[172:175], v[222:225], v[34:37]
	v_mfma_f32_16x16x32_bf16 v[62:65], v[168:171], v[184:187], v[62:65]
	v_mfma_f32_16x16x32_bf16 v[58:61], v[176:179], v[184:187], v[58:61]
	v_mfma_f32_16x16x32_bf16 v[54:57], v[168:171], v[192:195], v[54:57]
	v_mfma_f32_16x16x32_bf16 v[50:53], v[176:179], v[192:195], v[50:53]
	v_mfma_f32_16x16x32_bf16 v[46:49], v[168:171], v[200:203], v[46:49]
	v_mfma_f32_16x16x32_bf16 v[42:45], v[176:179], v[200:203], v[42:45]
	v_mfma_f32_16x16x32_bf16 v[38:41], v[168:171], v[232:235], v[38:41]
	v_mfma_f32_16x16x32_bf16 v[34:37], v[176:179], v[232:235], v[34:37]
	s_setprio 0
	s_barrier
	s_add_i32 m0, s1, 0x1bf80
	s_nop 0
	global_load_lds_dwordx4 v[154:155], off offset:128
	s_add_i32 m0, s1, 0x1df80
	s_nop 0
	global_load_lds_dwordx4 v[156:157], off offset:128
	s_waitcnt vmcnt(6)
	s_barrier
	s_setprio 1
	v_mfma_f32_16x16x32_bf16 v[30:33], v[236:239], v[180:183], v[30:33]
	v_mfma_f32_16x16x32_bf16 v[26:29], v[244:247], v[180:183], v[26:29]
	v_mfma_f32_16x16x32_bf16 v[22:25], v[236:239], v[188:191], v[22:25]
	v_mfma_f32_16x16x32_bf16 v[18:21], v[244:247], v[188:191], v[18:21]
	v_mfma_f32_16x16x32_bf16 v[14:17], v[236:239], v[196:199], v[14:17]
	v_mfma_f32_16x16x32_bf16 v[10:13], v[244:247], v[196:199], v[10:13]
	v_mfma_f32_16x16x32_bf16 v[6:9], v[236:239], v[222:225], v[6:9]
	v_mfma_f32_16x16x32_bf16 v[2:5], v[244:247], v[222:225], v[2:5]
	v_mfma_f32_16x16x32_bf16 v[30:33], v[240:243], v[184:187], v[30:33]
	v_mfma_f32_16x16x32_bf16 v[26:29], v[248:251], v[184:187], v[26:29]
	v_mfma_f32_16x16x32_bf16 v[22:25], v[240:243], v[192:195], v[22:25]
	v_mfma_f32_16x16x32_bf16 v[18:21], v[248:251], v[192:195], v[18:21]
	v_mfma_f32_16x16x32_bf16 v[14:17], v[240:243], v[200:203], v[14:17]
	v_mfma_f32_16x16x32_bf16 v[10:13], v[248:251], v[200:203], v[10:13]
	v_mfma_f32_16x16x32_bf16 v[6:9], v[240:243], v[232:235], v[6:9]
	v_mfma_f32_16x16x32_bf16 v[2:5], v[248:251], v[232:235], v[2:5]
	s_setprio 0
	s_add_i32 s0, s0, 2
	s_add_u32 s10, s10, 0x100
	s_addc_u32 s11, s11, 0
	s_cmp_lt_u32 s0, 28
	s_barrier
	s_cbranch_scc1 .LBB0_85
	s_add_i32 s1, s1, 0x1e000
	s_mov_b64 s[10:11], 0xf80
	v_readfirstlane_b32 s0, v162
	v_lshl_add_u64 v[132:133], v[132:133], 0, s[10:11]
	s_mov_b32 m0, s0
	v_readfirstlane_b32 s0, v163
	ds_read_b128 v[134:137], v151
	ds_read_b128 v[138:141], v151 offset:1024
	ds_read_b128 v[152:155], v151 offset:2048
	ds_read_b128 v[156:159], v151 offset:3072
	ds_read_b128 v[164:167], v0
	ds_read_b128 v[168:171], v0 offset:1024
	ds_read_b128 v[172:175], v0 offset:2048
	ds_read_b128 v[176:179], v0 offset:3072
	ds_read_b128 v[180:183], v0 offset:4096
	ds_read_b128 v[184:187], v0 offset:5120
	ds_read_b128 v[188:191], v0 offset:6144
	ds_read_b128 v[192:195], v0 offset:7168
	global_load_lds_dwordx4 v[132:133], off
	v_lshl_add_u64 v[130:131], v[130:131], 0, s[10:11]
	s_mov_b32 m0, s0
	s_nop 0
	global_load_lds_dwordx4 v[130:131], off
	s_barrier
	s_waitcnt lgkmcnt(0)
	s_setprio 1
	s_waitcnt lgkmcnt(0)
	v_mfma_f32_16x16x32_bf16 v[126:129], v[134:137], v[164:167], v[126:129]
	v_mfma_f32_16x16x32_bf16 v[122:125], v[152:155], v[164:167], v[122:125]
	v_mfma_f32_16x16x32_bf16 v[114:117], v[152:155], v[172:175], v[114:117]
	v_mfma_f32_16x16x32_bf16 v[106:109], v[152:155], v[180:183], v[106:109]
	v_mfma_f32_16x16x32_bf16 v[98:101], v[152:155], v[188:191], v[98:101]
	v_mfma_f32_16x16x32_bf16 v[126:129], v[138:141], v[168:171], v[126:129]
	v_mfma_f32_16x16x32_bf16 v[122:125], v[156:159], v[168:171], v[122:125]
	v_mfma_f32_16x16x32_bf16 v[118:121], v[134:137], v[172:175], v[118:121]
	v_mfma_f32_16x16x32_bf16 v[114:117], v[156:159], v[176:179], v[114:117]
	v_mfma_f32_16x16x32_bf16 v[110:113], v[134:137], v[180:183], v[110:113]
	v_mfma_f32_16x16x32_bf16 v[106:109], v[156:159], v[184:187], v[106:109]
	v_mfma_f32_16x16x32_bf16 v[102:105], v[134:137], v[188:191], v[102:105]
	v_mfma_f32_16x16x32_bf16 v[98:101], v[156:159], v[192:195], v[98:101]
	v_mfma_f32_16x16x32_bf16 v[130:133], v[138:141], v[176:179], v[118:121]
	v_mfma_f32_16x16x32_bf16 v[160:163], v[138:141], v[184:187], v[110:113]
	v_mfma_f32_16x16x32_bf16 v[196:199], v[138:141], v[192:195], v[102:105]
	s_setprio 0
	s_barrier
	s_nop 0
	ds_read_b128 v[102:105], v151 offset:16384
	ds_read_b128 v[110:113], v151 offset:17408
	ds_read_b128 v[118:121], v151 offset:18432
	ds_read_b128 v[200:203], v151 offset:19456
	s_barrier
	s_waitcnt lgkmcnt(0)
	s_setprio 1
	s_waitcnt lgkmcnt(1)
	v_mfma_f32_16x16x32_bf16 v[90:93], v[118:121], v[164:167], v[90:93]
	v_mfma_f32_16x16x32_bf16 v[86:89], v[102:105], v[172:175], v[86:89]
	v_mfma_f32_16x16x32_bf16 v[82:85], v[118:121], v[172:175], v[82:85]
	v_mfma_f32_16x16x32_bf16 v[78:81], v[102:105], v[180:183], v[78:81]
	v_mfma_f32_16x16x32_bf16 v[70:73], v[102:105], v[188:191], v[70:73]
	v_mfma_f32_16x16x32_bf16 v[94:97], v[102:105], v[164:167], v[94:97]
	s_waitcnt lgkmcnt(0)
	v_mfma_f32_16x16x32_bf16 v[90:93], v[200:203], v[168:171], v[90:93]
	v_mfma_f32_16x16x32_bf16 v[86:89], v[110:113], v[176:179], v[86:89]
	v_mfma_f32_16x16x32_bf16 v[82:85], v[200:203], v[176:179], v[82:85]
	v_mfma_f32_16x16x32_bf16 v[78:81], v[110:113], v[184:187], v[78:81]
	v_mfma_f32_16x16x32_bf16 v[74:77], v[118:121], v[180:183], v[74:77]
	v_mfma_f32_16x16x32_bf16 v[70:73], v[110:113], v[192:195], v[70:73]
	v_mfma_f32_16x16x32_bf16 v[66:69], v[118:121], v[188:191], v[66:69]
	v_mfma_f32_16x16x32_bf16 v[222:225], v[110:113], v[168:171], v[94:97]
	v_mfma_f32_16x16x32_bf16 v[164:167], v[200:203], v[184:187], v[74:77]
	v_mfma_f32_16x16x32_bf16 v[168:171], v[200:203], v[192:195], v[66:69]
	s_setprio 0
	s_barrier
	s_nop 2
	ds_read_b128 v[66:69], v0 offset:16384
	ds_read_b128 v[74:77], v0 offset:17408
	ds_read_b128 v[94:97], v0 offset:18432
	ds_read_b128 v[172:175], v0 offset:19456
	ds_read_b128 v[176:179], v0 offset:20480
	ds_read_b128 v[180:183], v0 offset:21504
	ds_read_b128 v[184:187], v0 offset:22528
	ds_read_b128 v[188:191], v0 offset:23552
	s_waitcnt vmcnt(4)
	s_barrier
	s_waitcnt lgkmcnt(0)
	s_setprio 1
	s_waitcnt lgkmcnt(5)
	v_mfma_f32_16x16x32_bf16 v[54:57], v[134:137], v[94:97], v[54:57]
	v_mfma_f32_16x16x32_bf16 v[50:53], v[152:155], v[94:97], v[50:53]
	v_mfma_f32_16x16x32_bf16 v[62:65], v[134:137], v[66:69], v[62:65]
	v_mfma_f32_16x16x32_bf16 v[58:61], v[152:155], v[66:69], v[58:61]
	s_waitcnt lgkmcnt(4)
	v_mfma_f32_16x16x32_bf16 v[54:57], v[138:141], v[172:175], v[54:57]
	v_mfma_f32_16x16x32_bf16 v[50:53], v[156:159], v[172:175], v[50:53]
	s_waitcnt lgkmcnt(3)
	v_mfma_f32_16x16x32_bf16 v[46:49], v[134:137], v[176:179], v[46:49]
	v_mfma_f32_16x16x32_bf16 v[42:45], v[152:155], v[176:179], v[42:45]
	s_waitcnt lgkmcnt(1)
	v_mfma_f32_16x16x32_bf16 v[38:41], v[134:137], v[184:187], v[38:41]
	v_mfma_f32_16x16x32_bf16 v[34:37], v[152:155], v[184:187], v[34:37]
	v_mfma_f32_16x16x32_bf16 v[192:195], v[138:141], v[74:77], v[62:65]
	v_mfma_f32_16x16x32_bf16 v[232:235], v[156:159], v[74:77], v[58:61]
	v_mfma_f32_16x16x32_bf16 v[236:239], v[138:141], v[180:183], v[46:49]
	v_mfma_f32_16x16x32_bf16 v[240:243], v[156:159], v[180:183], v[42:45]
	s_waitcnt lgkmcnt(0)
	v_mfma_f32_16x16x32_bf16 v[134:137], v[138:141], v[188:191], v[38:41]
	v_mfma_f32_16x16x32_bf16 v[138:141], v[156:159], v[188:191], v[34:37]
	s_setprio 0
	s_setprio 1
	v_mfma_f32_16x16x32_bf16 v[30:33], v[102:105], v[66:69], v[30:33]
	v_mfma_f32_16x16x32_bf16 v[26:29], v[118:121], v[66:69], v[26:29]
	v_mfma_f32_16x16x32_bf16 v[14:17], v[102:105], v[176:179], v[14:17]
	v_mfma_f32_16x16x32_bf16 v[10:13], v[118:121], v[176:179], v[10:13]
	v_mfma_f32_16x16x32_bf16 v[30:33], v[110:113], v[74:77], v[30:33]
	v_mfma_f32_16x16x32_bf16 v[26:29], v[200:203], v[74:77], v[26:29]
	v_mfma_f32_16x16x32_bf16 v[22:25], v[102:105], v[94:97], v[22:25]
	v_mfma_f32_16x16x32_bf16 v[18:21], v[118:121], v[94:97], v[18:21]
	v_mfma_f32_16x16x32_bf16 v[14:17], v[110:113], v[180:183], v[14:17]
	v_mfma_f32_16x16x32_bf16 v[10:13], v[200:203], v[180:183], v[10:13]
	v_mfma_f32_16x16x32_bf16 v[6:9], v[102:105], v[184:187], v[6:9]
	v_mfma_f32_16x16x32_bf16 v[2:5], v[118:121], v[184:187], v[2:5]
	v_mfma_f32_16x16x32_bf16 v[152:155], v[110:113], v[172:175], v[22:25]
	v_mfma_f32_16x16x32_bf16 v[156:159], v[200:203], v[172:175], v[18:21]
	v_mfma_f32_16x16x32_bf16 v[172:175], v[110:113], v[188:191], v[6:9]
	v_mfma_f32_16x16x32_bf16 v[176:179], v[200:203], v[188:191], v[2:5]
	s_setprio 0
	s_barrier
	s_nop 1
	ds_read_b128 v[2:5], v151 offset:32768
	ds_read_b128 v[6:9], v151 offset:33792
	ds_read_b128 v[180:183], v151 offset:34816
	ds_read_b128 v[184:187], v151 offset:35840
	ds_read_b128 v[18:21], v0 offset:32768
	ds_read_b128 v[22:25], v0 offset:33792
	ds_read_b128 v[38:41], v0 offset:34816
	ds_read_b128 v[46:49], v0 offset:35840
	ds_read_b128 v[58:61], v0 offset:36864
	ds_read_b128 v[66:69], v0 offset:37888
	ds_read_b128 v[188:191], v0 offset:38912
	ds_read_b128 v[200:203], v0 offset:39936
	s_waitcnt vmcnt(2)
	s_barrier
	s_waitcnt lgkmcnt(0)
	s_setprio 1
	s_waitcnt lgkmcnt(7)
	v_mfma_f32_16x16x32_bf16 v[34:37], v[2:5], v[18:21], v[126:129]
	s_waitcnt lgkmcnt(6)
	v_mfma_f32_16x16x32_bf16 v[118:121], v[6:9], v[22:25], v[34:37]
	v_mfma_f32_16x16x32_bf16 v[34:37], v[180:183], v[18:21], v[122:125]
	v_mfma_f32_16x16x32_bf16 v[110:113], v[184:187], v[22:25], v[34:37]
	s_waitcnt lgkmcnt(5)
	v_mfma_f32_16x16x32_bf16 v[34:37], v[2:5], v[38:41], v[130:133]
	s_waitcnt lgkmcnt(4)
	v_mfma_f32_16x16x32_bf16 v[102:105], v[6:9], v[46:49], v[34:37]
	v_mfma_f32_16x16x32_bf16 v[34:37], v[180:183], v[38:41], v[114:117]
	v_mfma_f32_16x16x32_bf16 v[94:97], v[184:187], v[46:49], v[34:37]
	s_waitcnt lgkmcnt(3)
	v_mfma_f32_16x16x32_bf16 v[34:37], v[2:5], v[58:61], v[160:163]
	s_waitcnt lgkmcnt(2)
	v_mfma_f32_16x16x32_bf16 v[74:77], v[6:9], v[66:69], v[34:37]
	v_mfma_f32_16x16x32_bf16 v[34:37], v[180:183], v[58:61], v[106:109]
	v_mfma_f32_16x16x32_bf16 v[62:65], v[184:187], v[66:69], v[34:37]
	s_waitcnt lgkmcnt(1)
	v_mfma_f32_16x16x32_bf16 v[34:37], v[2:5], v[188:191], v[196:199]
	s_waitcnt lgkmcnt(0)
	v_mfma_f32_16x16x32_bf16 v[42:45], v[6:9], v[200:203], v[34:37]
	v_mfma_f32_16x16x32_bf16 v[34:37], v[180:183], v[188:191], v[98:101]
	v_mfma_f32_16x16x32_bf16 v[34:37], v[184:187], v[200:203], v[34:37]
	s_setprio 0
	s_barrier
	ds_read_b128 v[130:133], v151 offset:49152
	ds_read_b128 v[160:163], v151 offset:50176
	ds_read_b128 v[196:199], v151 offset:51200
	ds_read_b128 v[148:151], v151 offset:52224
	s_waitcnt vmcnt(0)
	s_barrier
	s_waitcnt lgkmcnt(0)
	s_setprio 1
	s_waitcnt lgkmcnt(3)
	v_mfma_f32_16x16x32_bf16 v[98:101], v[130:133], v[18:21], v[222:225]
	s_waitcnt lgkmcnt(1)
	v_mfma_f32_16x16x32_bf16 v[18:21], v[196:199], v[18:21], v[90:93]
	s_waitcnt lgkmcnt(0)
	v_mfma_f32_16x16x32_bf16 v[122:125], v[148:151], v[22:25], v[18:21]
	v_mfma_f32_16x16x32_bf16 v[18:21], v[130:133], v[38:41], v[86:89]
	v_mfma_f32_16x16x32_bf16 v[114:117], v[160:163], v[46:49], v[18:21]
	v_mfma_f32_16x16x32_bf16 v[18:21], v[196:199], v[38:41], v[82:85]
	v_mfma_f32_16x16x32_bf16 v[106:109], v[148:151], v[46:49], v[18:21]
	v_mfma_f32_16x16x32_bf16 v[18:21], v[130:133], v[58:61], v[78:81]
	v_mfma_f32_16x16x32_bf16 v[126:129], v[160:163], v[22:25], v[98:101]
	v_mfma_f32_16x16x32_bf16 v[98:101], v[160:163], v[66:69], v[18:21]
	v_mfma_f32_16x16x32_bf16 v[18:21], v[196:199], v[58:61], v[164:167]
	v_mfma_f32_16x16x32_bf16 v[90:93], v[148:151], v[66:69], v[18:21]
	v_mfma_f32_16x16x32_bf16 v[18:21], v[130:133], v[188:191], v[70:73]
	v_mfma_f32_16x16x32_bf16 v[66:69], v[160:163], v[200:203], v[18:21]
	v_mfma_f32_16x16x32_bf16 v[18:21], v[196:199], v[188:191], v[168:171]
	v_mfma_f32_16x16x32_bf16 v[58:61], v[148:151], v[200:203], v[18:21]
	s_setprio 0
	s_barrier
	ds_read_b128 v[82:85], v0 offset:49152
	ds_read_b128 v[164:167], v0 offset:50176
	ds_read_b128 v[168:171], v0 offset:51200
	ds_read_b128 v[188:191], v0 offset:52224
	ds_read_b128 v[200:203], v0 offset:53248
	ds_read_b128 v[222:225], v0 offset:54272
	ds_read_b128 v[244:247], v0 offset:55296
	ds_read_b128 v[248:251], v0 offset:56320
	s_barrier
	s_waitcnt lgkmcnt(0)
	s_setprio 1
	s_waitcnt lgkmcnt(7)
	v_mfma_f32_16x16x32_bf16 v[18:21], v[2:5], v[82:85], v[192:195]
	s_waitcnt lgkmcnt(6)
	v_mfma_f32_16x16x32_bf16 v[78:81], v[6:9], v[164:167], v[18:21]
	v_mfma_f32_16x16x32_bf16 v[18:21], v[180:183], v[82:85], v[232:235]
	v_mfma_f32_16x16x32_bf16 v[70:73], v[184:187], v[164:167], v[18:21]
	s_waitcnt lgkmcnt(5)
	v_mfma_f32_16x16x32_bf16 v[18:21], v[2:5], v[168:171], v[54:57]
	s_waitcnt lgkmcnt(4)
	v_mfma_f32_16x16x32_bf16 v[46:49], v[6:9], v[188:191], v[18:21]
	v_mfma_f32_16x16x32_bf16 v[18:21], v[180:183], v[168:171], v[50:53]
	v_mfma_f32_16x16x32_bf16 v[38:41], v[184:187], v[188:191], v[18:21]
	s_waitcnt lgkmcnt(3)
	v_mfma_f32_16x16x32_bf16 v[18:21], v[2:5], v[200:203], v[236:239]
	s_waitcnt lgkmcnt(1)
	v_mfma_f32_16x16x32_bf16 v[2:5], v[2:5], v[244:247], v[134:137]
	v_mfma_f32_16x16x32_bf16 v[22:25], v[6:9], v[222:225], v[18:21]
	v_mfma_f32_16x16x32_bf16 v[18:21], v[180:183], v[200:203], v[240:243]
	s_waitcnt lgkmcnt(0)
	v_mfma_f32_16x16x32_bf16 v[6:9], v[6:9], v[248:251], v[2:5]
	v_mfma_f32_16x16x32_bf16 v[2:5], v[180:183], v[244:247], v[138:141]
	v_mfma_f32_16x16x32_bf16 v[18:21], v[184:187], v[222:225], v[18:21]
	v_mfma_f32_16x16x32_bf16 v[2:5], v[184:187], v[248:251], v[2:5]
	s_setprio 0
	s_setprio 1
	v_mfma_f32_16x16x32_bf16 v[26:29], v[196:199], v[82:85], v[26:29]
	v_mfma_f32_16x16x32_bf16 v[30:33], v[130:133], v[82:85], v[30:33]
	v_mfma_f32_16x16x32_bf16 v[82:85], v[148:151], v[164:167], v[26:29]
	v_mfma_f32_16x16x32_bf16 v[26:29], v[130:133], v[168:171], v[152:155]
	v_mfma_f32_16x16x32_bf16 v[54:57], v[160:163], v[188:191], v[26:29]
	v_mfma_f32_16x16x32_bf16 v[26:29], v[196:199], v[168:171], v[156:159]
	v_mfma_f32_16x16x32_bf16 v[10:13], v[196:199], v[200:203], v[10:13]
	v_mfma_f32_16x16x32_bf16 v[50:53], v[148:151], v[188:191], v[26:29]
	v_mfma_f32_16x16x32_bf16 v[14:17], v[130:133], v[200:203], v[14:17]
	v_mfma_f32_16x16x32_bf16 v[26:29], v[148:151], v[222:225], v[10:13]
	v_mfma_f32_16x16x32_bf16 v[10:13], v[130:133], v[244:247], v[172:175]
	v_mfma_f32_16x16x32_bf16 v[86:89], v[160:163], v[164:167], v[30:33]
	v_mfma_f32_16x16x32_bf16 v[30:33], v[160:163], v[222:225], v[14:17]
	v_mfma_f32_16x16x32_bf16 v[14:17], v[160:163], v[248:251], v[10:13]
	v_mfma_f32_16x16x32_bf16 v[10:13], v[196:199], v[244:247], v[176:179]
	v_mfma_f32_16x16x32_bf16 v[10:13], v[148:151], v[248:251], v[10:13]
	s_setprio 0
	s_movk_i32 s0, 0x100
	v_cmp_gt_u32_e32 vcc, s0, v142
	s_barrier
	s_and_saveexec_b64 s[0:1], vcc
	s_cbranch_execz .LBB0_81
	s_barrier
	s_branch .LBB0_81

.LBB0_179:
	s_or_b64 exec, exec, s[52:53]
	v_mov_b32_e32 v3, v1
	v_lshl_add_u64 v[14:15], s[0:1], 0, v[2:3]
	v_lshl_add_u64 v[18:19], s[16:17], 0, v[2:3]
	v_lshl_add_u64 v[22:23], s[72:73], 0, v[2:3]
	v_lshl_add_u64 v[130:131], s[76:77], 0, v[2:3]
	v_and_b32_e32 v146, 15, v142
	v_bfe_u32 v145, v142, 4, 2
	v_lshlrev_b32_e32 v3, 2, v142
	v_add_u32_e32 v156, 0x18000, v147
	v_lshl_add_u64 v[12:13], s[0:1], 0, v[0:1]
	v_lshl_add_u64 v[16:17], s[16:17], 0, v[0:1]
	v_lshl_add_u64 v[20:21], s[72:73], 0, v[0:1]
	v_lshl_add_u64 v[132:133], s[76:77], 0, v[0:1]
	v_lshlrev_b32_e32 v0, 6, v146
	v_lshlrev_b32_e32 v2, 4, v145
	v_and_b32_e32 v3, 32, v3
	s_mov_b64 s[16:17], 0x80
	v_readfirstlane_b32 s0, v156
	v_add_u32_e32 v157, 0x1a000, v147
	v_bitop3_b32 v24, v2, v3, v0 bitop3:0x36
	v_lshl_add_u64 v[2:3], v[12:13], 0, s[16:17]
	s_mov_b32 m0, s0
	v_readfirstlane_b32 s0, v157
	v_add_u32_e32 v158, 0x8000, v147
	s_waitcnt vmcnt(4)
	s_barrier
	global_load_lds_dwordx4 v[2:3], off
	v_lshl_add_u64 v[2:3], v[14:15], 0, s[16:17]
	s_mov_b32 m0, s0
	v_readfirstlane_b32 s0, v158
	v_add_u32_e32 v159, 0xa000, v147
	global_load_lds_dwordx4 v[2:3], off
	v_lshl_add_u64 v[2:3], v[16:17], 0, s[16:17]
	s_mov_b32 m0, s0
	v_readfirstlane_b32 s0, v159
	v_add_u32_e32 v160, 0x1c000, v147
	global_load_lds_dwordx4 v[2:3], off
	v_lshl_add_u64 v[2:3], v[18:19], 0, s[16:17]
	s_mov_b32 m0, s0
	v_readfirstlane_b32 s0, v160
	v_add_u32_e32 v161, 0x1e000, v147
	global_load_lds_dwordx4 v[2:3], off
	v_lshl_add_u64 v[2:3], v[20:21], 0, s[16:17]
	s_mov_b32 m0, s0
	v_readfirstlane_b32 s0, v161
	global_load_lds_dwordx4 v[2:3], off
	v_lshl_add_u64 v[2:3], v[22:23], 0, s[16:17]
	s_mov_b32 m0, s0
	v_lshlrev_b32_e32 v0, 14, v4
	global_load_lds_dwordx4 v[2:3], off
	v_lshlrev_b32_e32 v2, 14, v7
	v_and_b32_e32 v0, 0x7fff8000, v0
	v_and_b32_e32 v2, 0x7fff8000, v2
	v_lshl_add_u32 v0, v5, 11, v0
	v_lshl_add_u32 v2, v9, 11, v2
	v_or_b32_e32 v0, v0, v6
	s_add_u32 s0, s57, s12
	v_or_b32_e32 v2, v2, v10
	v_readlane_b32 s36, v253, 33
	v_add_lshl_u32 v0, v0, v8, 1
	s_addc_u32 s1, s63, s13
	v_add_lshl_u32 v2, v2, v11, 1
	v_mov_b32_e32 v3, v1
	v_readlane_b32 s48, v253, 45
	v_lshl_add_u64 v[134:135], s[0:1], 0, v[0:1]
	v_lshl_add_u64 v[136:137], s[0:1], 0, v[2:3]
	v_readlane_b32 s49, v253, 46
	s_add_u32 s0, s48, s14
	v_bfe_u32 v144, v142, 6, 2
	s_waitcnt vmcnt(6)
	s_addc_u32 s1, s49, s15
	v_lshlrev_b32_e32 v25, 13, v143
	v_lshl_or_b32 v26, v144, 12, v212
	v_lshl_add_u64 v[140:141], s[0:1], 0, v[2:3]
	v_mov_b32_e32 v2, 0
	v_lshl_add_u64 v[138:139], s[0:1], 0, v[0:1]
	s_mov_b32 s0, -2
	s_mov_b64 s[12:13], 0
	v_add_u32_e32 v151, v26, v24
	v_add_u32_e32 v0, v25, v24
	v_mov_b32_e32 v3, v2
	v_mov_b32_e32 v4, v2
	v_mov_b32_e32 v5, v2
	v_mov_b32_e32 v6, v2
	v_mov_b32_e32 v7, v2
	v_mov_b32_e32 v8, v2
	v_mov_b32_e32 v9, v2
	v_mov_b32_e32 v10, v2
	v_mov_b32_e32 v11, v2
	v_mov_b32_e32 v12, v2
	v_mov_b32_e32 v13, v2
	v_mov_b32_e32 v14, v2
	v_mov_b32_e32 v15, v2
	v_mov_b32_e32 v16, v2
	v_mov_b32_e32 v17, v2
	v_mov_b32_e32 v18, v2
	v_mov_b32_e32 v19, v2
	v_mov_b32_e32 v20, v2
	v_mov_b32_e32 v21, v2
	v_mov_b32_e32 v22, v2
	v_mov_b32_e32 v23, v2
	v_mov_b32_e32 v24, v2
	v_mov_b32_e32 v25, v2
	v_mov_b32_e32 v26, v2
	v_mov_b32_e32 v27, v2
	v_mov_b32_e32 v28, v2
	v_mov_b32_e32 v29, v2
	v_mov_b32_e32 v30, v2
	v_mov_b32_e32 v31, v2
	v_mov_b32_e32 v32, v2
	v_mov_b32_e32 v33, v2
	v_mov_b32_e32 v34, v2
	v_mov_b32_e32 v35, v2
	v_mov_b32_e32 v36, v2
	v_mov_b32_e32 v37, v2
	v_mov_b32_e32 v38, v2
	v_mov_b32_e32 v39, v2
	v_mov_b32_e32 v40, v2
	v_mov_b32_e32 v41, v2
	v_mov_b32_e32 v42, v2
	v_mov_b32_e32 v43, v2
	v_mov_b32_e32 v44, v2
	v_mov_b32_e32 v45, v2
	v_mov_b32_e32 v46, v2
	v_mov_b32_e32 v47, v2
	v_mov_b32_e32 v48, v2
	v_mov_b32_e32 v49, v2
	v_mov_b32_e32 v50, v2
	v_mov_b32_e32 v51, v2
	v_mov_b32_e32 v52, v2
	v_mov_b32_e32 v53, v2
	v_mov_b32_e32 v54, v2
	v_mov_b32_e32 v55, v2
	v_mov_b32_e32 v56, v2
	v_mov_b32_e32 v57, v2
	v_mov_b32_e32 v58, v2
	v_mov_b32_e32 v59, v2
	v_mov_b32_e32 v60, v2
	v_mov_b32_e32 v61, v2
	v_mov_b32_e32 v62, v2
	v_mov_b32_e32 v63, v2
	v_mov_b32_e32 v64, v2
	v_mov_b32_e32 v65, v2
	v_mov_b32_e32 v66, v2
	v_mov_b32_e32 v67, v2
	v_mov_b32_e32 v68, v2
	v_mov_b32_e32 v69, v2
	v_mov_b32_e32 v70, v2
	v_mov_b32_e32 v71, v2
	v_mov_b32_e32 v72, v2
	v_mov_b32_e32 v73, v2
	v_mov_b32_e32 v74, v2
	v_mov_b32_e32 v75, v2
	v_mov_b32_e32 v76, v2
	v_mov_b32_e32 v77, v2
	v_mov_b32_e32 v78, v2
	v_mov_b32_e32 v79, v2
	v_mov_b32_e32 v80, v2
	v_mov_b32_e32 v81, v2
	v_mov_b32_e32 v82, v2
	v_mov_b32_e32 v83, v2
	v_mov_b32_e32 v84, v2
	v_mov_b32_e32 v85, v2
	v_mov_b32_e32 v86, v2
	v_mov_b32_e32 v87, v2
	v_mov_b32_e32 v88, v2
	v_mov_b32_e32 v89, v2
	v_mov_b32_e32 v90, v2
	v_mov_b32_e32 v91, v2
	v_mov_b32_e32 v92, v2
	v_mov_b32_e32 v93, v2
	v_mov_b32_e32 v94, v2
	v_mov_b32_e32 v95, v2
	v_mov_b32_e32 v96, v2
	v_mov_b32_e32 v97, v2
	v_mov_b32_e32 v98, v2
	v_mov_b32_e32 v99, v2
	v_mov_b32_e32 v100, v2
	v_mov_b32_e32 v101, v2
	v_mov_b32_e32 v102, v2
	v_mov_b32_e32 v103, v2
	v_mov_b32_e32 v104, v2
	v_mov_b32_e32 v105, v2
	v_mov_b32_e32 v106, v2
	v_mov_b32_e32 v107, v2
	v_mov_b32_e32 v108, v2
	v_mov_b32_e32 v109, v2
	v_mov_b32_e32 v110, v2
	v_mov_b32_e32 v111, v2
	v_mov_b32_e32 v112, v2
	v_mov_b32_e32 v113, v2
	v_mov_b32_e32 v114, v2
	v_mov_b32_e32 v115, v2
	v_mov_b32_e32 v116, v2
	v_mov_b32_e32 v117, v2
	v_mov_b32_e32 v118, v2
	v_mov_b32_e32 v119, v2
	v_mov_b32_e32 v120, v2
	v_mov_b32_e32 v121, v2
	v_mov_b32_e32 v122, v2
	v_mov_b32_e32 v123, v2
	v_mov_b32_e32 v124, v2
	v_mov_b32_e32 v125, v2
	v_mov_b32_e32 v126, v2
	v_mov_b32_e32 v127, v2
	v_mov_b32_e32 v128, v2
	v_mov_b32_e32 v129, v2
	s_barrier
	v_readlane_b32 s37, v253, 34
	v_readlane_b32 s38, v253, 35
	v_readlane_b32 s39, v253, 36
	v_readlane_b32 s40, v253, 37
	v_readlane_b32 s41, v253, 38
	v_readlane_b32 s42, v253, 39
	v_readlane_b32 s43, v253, 40
	v_readlane_b32 s44, v253, 41
	v_readlane_b32 s45, v253, 42
	v_readlane_b32 s46, v253, 43
	v_readlane_b32 s47, v253, 44
	v_readlane_b32 s50, v253, 47
	v_readlane_b32 s51, v253, 48
	v_add_u32_e32 v162, 0xc000, v147
	v_add_u32_e32 v163, 0xe000, v147
	v_readfirstlane_b32 s1, v147
	s_nop 1
.LBB0_180:
	ds_read_b128 v[164:167], v151
	ds_read_b128 v[168:171], v151 offset:1024
	ds_read_b128 v[172:175], v151 offset:2048
	ds_read_b128 v[176:179], v151 offset:3072
	v_lshl_add_u64 v[204:205], v[138:139], 0, s[12:13]
	v_lshl_add_u64 v[228:229], v[204:205], 0, s[60:61]
	s_add_i32 m0, s1, 0xc000
	ds_read_b128 v[180:183], v0
	ds_read_b128 v[184:187], v0 offset:1024
	ds_read_b128 v[188:191], v0 offset:2048
	ds_read_b128 v[192:195], v0 offset:3072
	ds_read_b128 v[196:199], v0 offset:4096
	ds_read_b128 v[200:203], v0 offset:5120
	ds_read_b128 v[222:225], v0 offset:6144
	ds_read_b128 v[232:235], v0 offset:7168
	global_load_lds_dwordx4 v[228:229], off
	v_lshl_add_u64 v[210:211], v[140:141], 0, s[12:13]
	s_add_i32 m0, s1, 0xe000
	v_lshl_add_u64 v[152:153], v[210:211], 0, s[60:61]
	global_load_lds_dwordx4 v[152:153], off
	s_waitcnt lgkmcnt(8)
	s_barrier
	s_waitcnt lgkmcnt(0)
	s_setprio 1
	v_mfma_f32_16x16x32_bf16 v[126:129], v[164:167], v[180:183], v[126:129]
	v_mfma_f32_16x16x32_bf16 v[122:125], v[172:175], v[180:183], v[122:125]
	v_mfma_f32_16x16x32_bf16 v[118:121], v[164:167], v[188:191], v[118:121]
	v_mfma_f32_16x16x32_bf16 v[114:117], v[172:175], v[188:191], v[114:117]
	v_mfma_f32_16x16x32_bf16 v[110:113], v[164:167], v[196:199], v[110:113]
	v_mfma_f32_16x16x32_bf16 v[106:109], v[172:175], v[196:199], v[106:109]
	v_mfma_f32_16x16x32_bf16 v[102:105], v[164:167], v[222:225], v[102:105]
	v_mfma_f32_16x16x32_bf16 v[98:101], v[172:175], v[222:225], v[98:101]
	v_mfma_f32_16x16x32_bf16 v[126:129], v[168:171], v[184:187], v[126:129]
	v_mfma_f32_16x16x32_bf16 v[122:125], v[176:179], v[184:187], v[122:125]
	v_mfma_f32_16x16x32_bf16 v[118:121], v[168:171], v[192:195], v[118:121]
	v_mfma_f32_16x16x32_bf16 v[114:117], v[176:179], v[192:195], v[114:117]
	v_mfma_f32_16x16x32_bf16 v[110:113], v[168:171], v[200:203], v[110:113]
	v_mfma_f32_16x16x32_bf16 v[106:109], v[176:179], v[200:203], v[106:109]
	v_mfma_f32_16x16x32_bf16 v[102:105], v[168:171], v[232:235], v[102:105]
	v_mfma_f32_16x16x32_bf16 v[98:101], v[176:179], v[232:235], v[98:101]
	s_setprio 0
	s_barrier
	v_lshl_add_u64 v[216:217], v[134:135], 0, s[12:13]
	s_add_i32 m0, s1, 0xff00
	ds_read_b128 v[236:239], v151 offset:16384
	ds_read_b128 v[240:243], v151 offset:17408
	ds_read_b128 v[244:247], v151 offset:18432
	ds_read_b128 v[248:251], v151 offset:19456
	global_load_lds_dwordx4 v[216:217], off offset:256
	s_add_i32 m0, s1, 0x11f00
	v_lshl_add_u64 v[218:219], v[136:137], 0, s[12:13]
	global_load_lds_dwordx4 v[218:219], off offset:256
	s_barrier
	s_waitcnt lgkmcnt(0)
	s_setprio 1
	v_mfma_f32_16x16x32_bf16 v[94:97], v[236:239], v[180:183], v[94:97]
	v_mfma_f32_16x16x32_bf16 v[90:93], v[244:247], v[180:183], v[90:93]
	v_mfma_f32_16x16x32_bf16 v[86:89], v[236:239], v[188:191], v[86:89]
	v_mfma_f32_16x16x32_bf16 v[82:85], v[244:247], v[188:191], v[82:85]
	v_mfma_f32_16x16x32_bf16 v[78:81], v[236:239], v[196:199], v[78:81]
	v_mfma_f32_16x16x32_bf16 v[74:77], v[244:247], v[196:199], v[74:77]
	v_mfma_f32_16x16x32_bf16 v[70:73], v[236:239], v[222:225], v[70:73]
	v_mfma_f32_16x16x32_bf16 v[66:69], v[244:247], v[222:225], v[66:69]
	v_mfma_f32_16x16x32_bf16 v[94:97], v[240:243], v[184:187], v[94:97]
	v_mfma_f32_16x16x32_bf16 v[90:93], v[248:251], v[184:187], v[90:93]
	v_mfma_f32_16x16x32_bf16 v[86:89], v[240:243], v[192:195], v[86:89]
	v_mfma_f32_16x16x32_bf16 v[82:85], v[248:251], v[192:195], v[82:85]
	v_mfma_f32_16x16x32_bf16 v[78:81], v[240:243], v[200:203], v[78:81]
	v_mfma_f32_16x16x32_bf16 v[74:77], v[248:251], v[200:203], v[74:77]
	v_mfma_f32_16x16x32_bf16 v[70:73], v[240:243], v[232:235], v[70:73]
	v_mfma_f32_16x16x32_bf16 v[66:69], v[248:251], v[232:235], v[66:69]
	s_setprio 0
	v_lshl_add_u64 v[158:159], v[204:205], 0, s[74:75]
	s_mov_b32 m0, s1
	s_barrier
	ds_read_b128 v[180:183], v0 offset:16384
	ds_read_b128 v[184:187], v0 offset:17408
	ds_read_b128 v[188:191], v0 offset:18432
	ds_read_b128 v[192:195], v0 offset:19456
	ds_read_b128 v[196:199], v0 offset:20480
	ds_read_b128 v[200:203], v0 offset:21504
	ds_read_b128 v[222:225], v0 offset:22528
	ds_read_b128 v[232:235], v0 offset:23552
	global_load_lds_dwordx4 v[158:159], off
	s_add_i32 m0, s1, 0x1f00
	s_nop 0
	global_load_lds_dwordx4 v[210:211], off offset:256
	s_barrier
	s_waitcnt lgkmcnt(0)
	s_setprio 1
	v_mfma_f32_16x16x32_bf16 v[62:65], v[164:167], v[180:183], v[62:65]
	v_mfma_f32_16x16x32_bf16 v[58:61], v[172:175], v[180:183], v[58:61]
	v_mfma_f32_16x16x32_bf16 v[54:57], v[164:167], v[188:191], v[54:57]
	v_mfma_f32_16x16x32_bf16 v[50:53], v[172:175], v[188:191], v[50:53]
	v_mfma_f32_16x16x32_bf16 v[46:49], v[164:167], v[196:199], v[46:49]
	v_mfma_f32_16x16x32_bf16 v[42:45], v[172:175], v[196:199], v[42:45]
	v_mfma_f32_16x16x32_bf16 v[38:41], v[164:167], v[222:225], v[38:41]
	v_mfma_f32_16x16x32_bf16 v[34:37], v[172:175], v[222:225], v[34:37]
	v_mfma_f32_16x16x32_bf16 v[62:65], v[168:171], v[184:187], v[62:65]
	v_mfma_f32_16x16x32_bf16 v[58:61], v[176:179], v[184:187], v[58:61]
	v_mfma_f32_16x16x32_bf16 v[54:57], v[168:171], v[192:195], v[54:57]
	v_mfma_f32_16x16x32_bf16 v[50:53], v[176:179], v[192:195], v[50:53]
	v_mfma_f32_16x16x32_bf16 v[46:49], v[168:171], v[200:203], v[46:49]
	v_mfma_f32_16x16x32_bf16 v[42:45], v[176:179], v[200:203], v[42:45]
	v_mfma_f32_16x16x32_bf16 v[38:41], v[168:171], v[232:235], v[38:41]
	v_mfma_f32_16x16x32_bf16 v[34:37], v[176:179], v[232:235], v[34:37]
	s_setprio 0
	s_barrier
	s_add_i32 m0, s1, 0x14000
	v_lshl_add_u64 v[154:155], v[216:217], 0, s[18:19]
	global_load_lds_dwordx4 v[154:155], off
	s_add_i32 m0, s1, 0x16000
	v_lshl_add_u64 v[156:157], v[218:219], 0, s[18:19]
	global_load_lds_dwordx4 v[156:157], off
	s_waitcnt vmcnt(6)
	s_barrier
	s_setprio 1
	v_mfma_f32_16x16x32_bf16 v[30:33], v[236:239], v[180:183], v[30:33]
	v_mfma_f32_16x16x32_bf16 v[26:29], v[244:247], v[180:183], v[26:29]
	v_mfma_f32_16x16x32_bf16 v[22:25], v[236:239], v[188:191], v[22:25]
	v_mfma_f32_16x16x32_bf16 v[18:21], v[244:247], v[188:191], v[18:21]
	v_mfma_f32_16x16x32_bf16 v[14:17], v[236:239], v[196:199], v[14:17]
	v_mfma_f32_16x16x32_bf16 v[10:13], v[244:247], v[196:199], v[10:13]
	v_mfma_f32_16x16x32_bf16 v[6:9], v[236:239], v[222:225], v[6:9]
	v_mfma_f32_16x16x32_bf16 v[2:5], v[244:247], v[222:225], v[2:5]
	v_mfma_f32_16x16x32_bf16 v[30:33], v[240:243], v[184:187], v[30:33]
	v_mfma_f32_16x16x32_bf16 v[26:29], v[248:251], v[184:187], v[26:29]
	v_mfma_f32_16x16x32_bf16 v[22:25], v[240:243], v[192:195], v[22:25]
	v_mfma_f32_16x16x32_bf16 v[18:21], v[248:251], v[192:195], v[18:21]
	v_mfma_f32_16x16x32_bf16 v[14:17], v[240:243], v[200:203], v[14:17]
	v_mfma_f32_16x16x32_bf16 v[10:13], v[248:251], v[200:203], v[10:13]
	v_mfma_f32_16x16x32_bf16 v[6:9], v[240:243], v[232:235], v[6:9]
	v_mfma_f32_16x16x32_bf16 v[2:5], v[248:251], v[232:235], v[2:5]
	s_setprio 0
	s_barrier
	ds_read_b128 v[164:167], v151 offset:32768
	ds_read_b128 v[168:171], v151 offset:33792
	ds_read_b128 v[172:175], v151 offset:34816
	ds_read_b128 v[176:179], v151 offset:35840
	s_add_i32 m0, s1, 0x3f80
	ds_read_b128 v[180:183], v0 offset:32768
	ds_read_b128 v[184:187], v0 offset:33792
	ds_read_b128 v[188:191], v0 offset:34816
	ds_read_b128 v[192:195], v0 offset:35840
	ds_read_b128 v[196:199], v0 offset:36864
	ds_read_b128 v[200:203], v0 offset:37888
	ds_read_b128 v[222:225], v0 offset:38912
	ds_read_b128 v[232:235], v0 offset:39936
	global_load_lds_dwordx4 v[228:229], off offset:128
	s_add_i32 m0, s1, 0x5f80
	s_nop 0
	global_load_lds_dwordx4 v[152:153], off offset:128
	s_waitcnt lgkmcnt(8)
	s_barrier
	s_waitcnt lgkmcnt(0)
	s_setprio 1
	v_mfma_f32_16x16x32_bf16 v[126:129], v[164:167], v[180:183], v[126:129]
	v_mfma_f32_16x16x32_bf16 v[122:125], v[172:175], v[180:183], v[122:125]
	v_mfma_f32_16x16x32_bf16 v[118:121], v[164:167], v[188:191], v[118:121]
	v_mfma_f32_16x16x32_bf16 v[114:117], v[172:175], v[188:191], v[114:117]
	v_mfma_f32_16x16x32_bf16 v[110:113], v[164:167], v[196:199], v[110:113]
	v_mfma_f32_16x16x32_bf16 v[106:109], v[172:175], v[196:199], v[106:109]
	v_mfma_f32_16x16x32_bf16 v[102:105], v[164:167], v[222:225], v[102:105]
	v_mfma_f32_16x16x32_bf16 v[98:101], v[172:175], v[222:225], v[98:101]
	v_mfma_f32_16x16x32_bf16 v[126:129], v[168:171], v[184:187], v[126:129]
	v_mfma_f32_16x16x32_bf16 v[122:125], v[176:179], v[184:187], v[122:125]
	v_mfma_f32_16x16x32_bf16 v[118:121], v[168:171], v[192:195], v[118:121]
	v_mfma_f32_16x16x32_bf16 v[114:117], v[176:179], v[192:195], v[114:117]
	v_mfma_f32_16x16x32_bf16 v[110:113], v[168:171], v[200:203], v[110:113]
	v_mfma_f32_16x16x32_bf16 v[106:109], v[176:179], v[200:203], v[106:109]
	v_mfma_f32_16x16x32_bf16 v[102:105], v[168:171], v[232:235], v[102:105]
	v_mfma_f32_16x16x32_bf16 v[98:101], v[176:179], v[232:235], v[98:101]
	s_setprio 0
	s_barrier
	s_add_i32 m0, s1, 0x17e80
	ds_read_b128 v[236:239], v151 offset:49152
	ds_read_b128 v[240:243], v151 offset:50176
	ds_read_b128 v[244:247], v151 offset:51200
	ds_read_b128 v[248:251], v151 offset:52224
	global_load_lds_dwordx4 v[216:217], off offset:384
	s_add_i32 m0, s1, 0x19e80
	s_nop 0
	global_load_lds_dwordx4 v[218:219], off offset:384
	s_barrier
	s_waitcnt lgkmcnt(0)
	s_setprio 1
	v_mfma_f32_16x16x32_bf16 v[94:97], v[236:239], v[180:183], v[94:97]
	v_mfma_f32_16x16x32_bf16 v[90:93], v[244:247], v[180:183], v[90:93]
	v_mfma_f32_16x16x32_bf16 v[86:89], v[236:239], v[188:191], v[86:89]
	v_mfma_f32_16x16x32_bf16 v[82:85], v[244:247], v[188:191], v[82:85]
	v_mfma_f32_16x16x32_bf16 v[78:81], v[236:239], v[196:199], v[78:81]
	v_mfma_f32_16x16x32_bf16 v[74:77], v[244:247], v[196:199], v[74:77]
	v_mfma_f32_16x16x32_bf16 v[70:73], v[236:239], v[222:225], v[70:73]
	v_mfma_f32_16x16x32_bf16 v[66:69], v[244:247], v[222:225], v[66:69]
	v_mfma_f32_16x16x32_bf16 v[94:97], v[240:243], v[184:187], v[94:97]
	v_mfma_f32_16x16x32_bf16 v[90:93], v[248:251], v[184:187], v[90:93]
	v_mfma_f32_16x16x32_bf16 v[86:89], v[240:243], v[192:195], v[86:89]
	v_mfma_f32_16x16x32_bf16 v[82:85], v[248:251], v[192:195], v[82:85]
	v_mfma_f32_16x16x32_bf16 v[78:81], v[240:243], v[200:203], v[78:81]
	v_mfma_f32_16x16x32_bf16 v[74:77], v[248:251], v[200:203], v[74:77]
	v_mfma_f32_16x16x32_bf16 v[70:73], v[240:243], v[232:235], v[70:73]
	v_mfma_f32_16x16x32_bf16 v[66:69], v[248:251], v[232:235], v[66:69]
	s_setprio 0
	s_add_i32 m0, s1, 0x7e80
	s_barrier
	ds_read_b128 v[180:183], v0 offset:49152
	ds_read_b128 v[184:187], v0 offset:50176
	ds_read_b128 v[188:191], v0 offset:51200
	ds_read_b128 v[192:195], v0 offset:52224
	ds_read_b128 v[196:199], v0 offset:53248
	ds_read_b128 v[200:203], v0 offset:54272
	ds_read_b128 v[222:225], v0 offset:55296
	ds_read_b128 v[232:235], v0 offset:56320
	global_load_lds_dwordx4 v[204:205], off offset:384
	s_add_i32 m0, s1, 0x9e80
	s_nop 0
	global_load_lds_dwordx4 v[210:211], off offset:384
	s_barrier
	s_waitcnt lgkmcnt(0)
	s_setprio 1
	v_mfma_f32_16x16x32_bf16 v[62:65], v[164:167], v[180:183], v[62:65]
	v_mfma_f32_16x16x32_bf16 v[58:61], v[172:175], v[180:183], v[58:61]
	v_mfma_f32_16x16x32_bf16 v[54:57], v[164:167], v[188:191], v[54:57]
	v_mfma_f32_16x16x32_bf16 v[50:53], v[172:175], v[188:191], v[50:53]
	v_mfma_f32_16x16x32_bf16 v[46:49], v[164:167], v[196:199], v[46:49]
	v_mfma_f32_16x16x32_bf16 v[42:45], v[172:175], v[196:199], v[42:45]
	v_mfma_f32_16x16x32_bf16 v[38:41], v[164:167], v[222:225], v[38:41]
	v_mfma_f32_16x16x32_bf16 v[34:37], v[172:175], v[222:225], v[34:37]
	v_mfma_f32_16x16x32_bf16 v[62:65], v[168:171], v[184:187], v[62:65]
	v_mfma_f32_16x16x32_bf16 v[58:61], v[176:179], v[184:187], v[58:61]
	v_mfma_f32_16x16x32_bf16 v[54:57], v[168:171], v[192:195], v[54:57]
	v_mfma_f32_16x16x32_bf16 v[50:53], v[176:179], v[192:195], v[50:53]
	v_mfma_f32_16x16x32_bf16 v[46:49], v[168:171], v[200:203], v[46:49]
	v_mfma_f32_16x16x32_bf16 v[42:45], v[176:179], v[200:203], v[42:45]
	v_mfma_f32_16x16x32_bf16 v[38:41], v[168:171], v[232:235], v[38:41]
	v_mfma_f32_16x16x32_bf16 v[34:37], v[176:179], v[232:235], v[34:37]
	s_setprio 0
	s_barrier
	s_add_i32 m0, s1, 0x1bf80
	s_nop 0
	global_load_lds_dwordx4 v[154:155], off offset:128
	s_add_i32 m0, s1, 0x1df80
	s_nop 0
	global_load_lds_dwordx4 v[156:157], off offset:128
	s_waitcnt vmcnt(6)
	s_barrier
	s_setprio 1
	v_mfma_f32_16x16x32_bf16 v[30:33], v[236:239], v[180:183], v[30:33]
	v_mfma_f32_16x16x32_bf16 v[26:29], v[244:247], v[180:183], v[26:29]
	v_mfma_f32_16x16x32_bf16 v[22:25], v[236:239], v[188:191], v[22:25]
	v_mfma_f32_16x16x32_bf16 v[18:21], v[244:247], v[188:191], v[18:21]
	v_mfma_f32_16x16x32_bf16 v[14:17], v[236:239], v[196:199], v[14:17]
	v_mfma_f32_16x16x32_bf16 v[10:13], v[244:247], v[196:199], v[10:13]
	v_mfma_f32_16x16x32_bf16 v[6:9], v[236:239], v[222:225], v[6:9]
	v_mfma_f32_16x16x32_bf16 v[2:5], v[244:247], v[222:225], v[2:5]
	v_mfma_f32_16x16x32_bf16 v[30:33], v[240:243], v[184:187], v[30:33]
	v_mfma_f32_16x16x32_bf16 v[26:29], v[248:251], v[184:187], v[26:29]
	v_mfma_f32_16x16x32_bf16 v[22:25], v[240:243], v[192:195], v[22:25]
	v_mfma_f32_16x16x32_bf16 v[18:21], v[248:251], v[192:195], v[18:21]
	v_mfma_f32_16x16x32_bf16 v[14:17], v[240:243], v[200:203], v[14:17]
	v_mfma_f32_16x16x32_bf16 v[10:13], v[248:251], v[200:203], v[10:13]
	v_mfma_f32_16x16x32_bf16 v[6:9], v[240:243], v[232:235], v[6:9]
	v_mfma_f32_16x16x32_bf16 v[2:5], v[248:251], v[232:235], v[2:5]
	s_setprio 0
	s_add_i32 s0, s0, 2
	s_add_u32 s12, s12, 0x100
	s_addc_u32 s13, s13, 0
	s_cmp_lt_u32 s0, 28
	s_barrier
	s_cbranch_scc1 .LBB0_180
	s_add_i32 s1, s1, 0x1e000
	s_mov_b64 s[12:13], 0xf80
	v_readfirstlane_b32 s0, v162
	v_lshl_add_u64 v[132:133], v[132:133], 0, s[12:13]
	s_mov_b32 m0, s0
	v_readfirstlane_b32 s0, v163
	ds_read_b128 v[134:137], v151
	ds_read_b128 v[138:141], v151 offset:1024
	ds_read_b128 v[152:155], v151 offset:2048
	ds_read_b128 v[156:159], v151 offset:3072
	ds_read_b128 v[164:167], v0
	ds_read_b128 v[168:171], v0 offset:1024
	ds_read_b128 v[172:175], v0 offset:2048
	ds_read_b128 v[176:179], v0 offset:3072
	ds_read_b128 v[180:183], v0 offset:4096
	ds_read_b128 v[184:187], v0 offset:5120
	ds_read_b128 v[188:191], v0 offset:6144
	ds_read_b128 v[192:195], v0 offset:7168
	global_load_lds_dwordx4 v[132:133], off
	v_lshl_add_u64 v[130:131], v[130:131], 0, s[12:13]
	s_mov_b32 m0, s0
	s_nop 0
	global_load_lds_dwordx4 v[130:131], off
	s_barrier
	s_waitcnt lgkmcnt(0)
	s_setprio 1
	s_waitcnt lgkmcnt(0)
	v_mfma_f32_16x16x32_bf16 v[126:129], v[134:137], v[164:167], v[126:129]
	v_mfma_f32_16x16x32_bf16 v[122:125], v[152:155], v[164:167], v[122:125]
	v_mfma_f32_16x16x32_bf16 v[114:117], v[152:155], v[172:175], v[114:117]
	v_mfma_f32_16x16x32_bf16 v[106:109], v[152:155], v[180:183], v[106:109]
	v_mfma_f32_16x16x32_bf16 v[98:101], v[152:155], v[188:191], v[98:101]
	v_mfma_f32_16x16x32_bf16 v[126:129], v[138:141], v[168:171], v[126:129]
	v_mfma_f32_16x16x32_bf16 v[122:125], v[156:159], v[168:171], v[122:125]
	v_mfma_f32_16x16x32_bf16 v[118:121], v[134:137], v[172:175], v[118:121]
	v_mfma_f32_16x16x32_bf16 v[114:117], v[156:159], v[176:179], v[114:117]
	v_mfma_f32_16x16x32_bf16 v[110:113], v[134:137], v[180:183], v[110:113]
	v_mfma_f32_16x16x32_bf16 v[106:109], v[156:159], v[184:187], v[106:109]
	v_mfma_f32_16x16x32_bf16 v[102:105], v[134:137], v[188:191], v[102:105]
	v_mfma_f32_16x16x32_bf16 v[98:101], v[156:159], v[192:195], v[98:101]
	v_mfma_f32_16x16x32_bf16 v[130:133], v[138:141], v[176:179], v[118:121]
	v_mfma_f32_16x16x32_bf16 v[160:163], v[138:141], v[184:187], v[110:113]
	v_mfma_f32_16x16x32_bf16 v[196:199], v[138:141], v[192:195], v[102:105]
	s_setprio 0
	s_barrier
	s_nop 0
	ds_read_b128 v[102:105], v151 offset:16384
	ds_read_b128 v[110:113], v151 offset:17408
	ds_read_b128 v[118:121], v151 offset:18432
	ds_read_b128 v[200:203], v151 offset:19456
	s_barrier
	s_waitcnt lgkmcnt(0)
	s_setprio 1
	s_waitcnt lgkmcnt(1)
	v_mfma_f32_16x16x32_bf16 v[90:93], v[118:121], v[164:167], v[90:93]
	v_mfma_f32_16x16x32_bf16 v[82:85], v[118:121], v[172:175], v[82:85]
	v_mfma_f32_16x16x32_bf16 v[74:77], v[118:121], v[180:183], v[74:77]
	v_mfma_f32_16x16x32_bf16 v[66:69], v[118:121], v[188:191], v[66:69]
	v_mfma_f32_16x16x32_bf16 v[94:97], v[102:105], v[164:167], v[94:97]
	s_waitcnt lgkmcnt(0)
	v_mfma_f32_16x16x32_bf16 v[90:93], v[200:203], v[168:171], v[90:93]
	v_mfma_f32_16x16x32_bf16 v[86:89], v[102:105], v[172:175], v[86:89]
	v_mfma_f32_16x16x32_bf16 v[82:85], v[200:203], v[176:179], v[82:85]
	v_mfma_f32_16x16x32_bf16 v[78:81], v[102:105], v[180:183], v[78:81]
	v_mfma_f32_16x16x32_bf16 v[74:77], v[200:203], v[184:187], v[74:77]
	v_mfma_f32_16x16x32_bf16 v[70:73], v[102:105], v[188:191], v[70:73]
	v_mfma_f32_16x16x32_bf16 v[66:69], v[200:203], v[192:195], v[66:69]
	v_mfma_f32_16x16x32_bf16 v[222:225], v[110:113], v[168:171], v[94:97]
	v_mfma_f32_16x16x32_bf16 v[164:167], v[110:113], v[176:179], v[86:89]
	v_mfma_f32_16x16x32_bf16 v[168:171], v[110:113], v[184:187], v[78:81]
	v_mfma_f32_16x16x32_bf16 v[172:175], v[110:113], v[192:195], v[70:73]
	s_setprio 0
	s_barrier
	s_nop 0
	ds_read_b128 v[70:73], v0 offset:16384
	ds_read_b128 v[78:81], v0 offset:17408
	ds_read_b128 v[86:89], v0 offset:18432
	ds_read_b128 v[94:97], v0 offset:19456
	ds_read_b128 v[176:179], v0 offset:20480
	ds_read_b128 v[180:183], v0 offset:21504
	ds_read_b128 v[184:187], v0 offset:22528
	ds_read_b128 v[188:191], v0 offset:23552
	s_waitcnt vmcnt(4)
	s_barrier
	s_waitcnt lgkmcnt(0)
	s_setprio 1
	s_waitcnt lgkmcnt(7)
	v_mfma_f32_16x16x32_bf16 v[62:65], v[134:137], v[70:73], v[62:65]
	v_mfma_f32_16x16x32_bf16 v[58:61], v[152:155], v[70:73], v[58:61]
	s_waitcnt lgkmcnt(5)
	v_mfma_f32_16x16x32_bf16 v[50:53], v[152:155], v[86:89], v[50:53]
	s_waitcnt lgkmcnt(3)
	v_mfma_f32_16x16x32_bf16 v[42:45], v[152:155], v[176:179], v[42:45]
	s_waitcnt lgkmcnt(1)
	v_mfma_f32_16x16x32_bf16 v[34:37], v[152:155], v[184:187], v[34:37]
	v_mfma_f32_16x16x32_bf16 v[62:65], v[138:141], v[78:81], v[62:65]
	v_mfma_f32_16x16x32_bf16 v[58:61], v[156:159], v[78:81], v[58:61]
	v_mfma_f32_16x16x32_bf16 v[54:57], v[134:137], v[86:89], v[54:57]
	v_mfma_f32_16x16x32_bf16 v[50:53], v[156:159], v[94:97], v[50:53]
	v_mfma_f32_16x16x32_bf16 v[46:49], v[134:137], v[176:179], v[46:49]
	v_mfma_f32_16x16x32_bf16 v[42:45], v[156:159], v[180:183], v[42:45]
	v_mfma_f32_16x16x32_bf16 v[38:41], v[134:137], v[184:187], v[38:41]
	s_waitcnt lgkmcnt(0)
	v_mfma_f32_16x16x32_bf16 v[34:37], v[156:159], v[188:191], v[34:37]
	v_mfma_f32_16x16x32_bf16 v[192:195], v[138:141], v[94:97], v[54:57]
	v_mfma_f32_16x16x32_bf16 v[232:235], v[138:141], v[180:183], v[46:49]
	v_mfma_f32_16x16x32_bf16 v[134:137], v[138:141], v[188:191], v[38:41]
	s_setprio 0
	s_setprio 1
	v_mfma_f32_16x16x32_bf16 v[26:29], v[118:121], v[70:73], v[26:29]
	v_mfma_f32_16x16x32_bf16 v[18:21], v[118:121], v[86:89], v[18:21]
	v_mfma_f32_16x16x32_bf16 v[10:13], v[118:121], v[176:179], v[10:13]
	v_mfma_f32_16x16x32_bf16 v[2:5], v[118:121], v[184:187], v[2:5]
	v_mfma_f32_16x16x32_bf16 v[30:33], v[102:105], v[70:73], v[30:33]
	v_mfma_f32_16x16x32_bf16 v[26:29], v[200:203], v[78:81], v[26:29]
	v_mfma_f32_16x16x32_bf16 v[22:25], v[102:105], v[86:89], v[22:25]
	v_mfma_f32_16x16x32_bf16 v[18:21], v[200:203], v[94:97], v[18:21]
	v_mfma_f32_16x16x32_bf16 v[14:17], v[102:105], v[176:179], v[14:17]
	v_mfma_f32_16x16x32_bf16 v[10:13], v[200:203], v[180:183], v[10:13]
	v_mfma_f32_16x16x32_bf16 v[6:9], v[102:105], v[184:187], v[6:9]
	v_mfma_f32_16x16x32_bf16 v[2:5], v[200:203], v[188:191], v[2:5]
	v_mfma_f32_16x16x32_bf16 v[138:141], v[110:113], v[78:81], v[30:33]
	v_mfma_f32_16x16x32_bf16 v[152:155], v[110:113], v[94:97], v[22:25]
	v_mfma_f32_16x16x32_bf16 v[156:159], v[110:113], v[180:183], v[14:17]
	v_mfma_f32_16x16x32_bf16 v[176:179], v[110:113], v[188:191], v[6:9]
	s_setprio 0
	s_barrier
	s_nop 0
	ds_read_b128 v[6:9], v151 offset:32768
	ds_read_b128 v[14:17], v151 offset:33792
	ds_read_b128 v[180:183], v151 offset:34816
	ds_read_b128 v[184:187], v151 offset:35840
	ds_read_b128 v[22:25], v0 offset:32768
	ds_read_b128 v[30:33], v0 offset:33792
	ds_read_b128 v[38:41], v0 offset:34816
	ds_read_b128 v[46:49], v0 offset:35840
	ds_read_b128 v[54:57], v0 offset:36864
	ds_read_b128 v[188:191], v0 offset:37888
	ds_read_b128 v[200:203], v0 offset:38912
	ds_read_b128 v[236:239], v0 offset:39936
	s_waitcnt vmcnt(2)
	s_barrier
	s_waitcnt lgkmcnt(0)
	s_setprio 1
	s_waitcnt lgkmcnt(7)
	v_mfma_f32_16x16x32_bf16 v[70:73], v[6:9], v[22:25], v[126:129]
	s_waitcnt lgkmcnt(6)
	v_mfma_f32_16x16x32_bf16 v[126:129], v[14:17], v[30:33], v[70:73]
	v_mfma_f32_16x16x32_bf16 v[70:73], v[180:183], v[22:25], v[122:125]
	v_mfma_f32_16x16x32_bf16 v[118:121], v[184:187], v[30:33], v[70:73]
	s_waitcnt lgkmcnt(5)
	v_mfma_f32_16x16x32_bf16 v[70:73], v[6:9], v[38:41], v[130:133]
	s_waitcnt lgkmcnt(4)
	v_mfma_f32_16x16x32_bf16 v[110:113], v[14:17], v[46:49], v[70:73]
	v_mfma_f32_16x16x32_bf16 v[70:73], v[180:183], v[38:41], v[114:117]
	v_mfma_f32_16x16x32_bf16 v[102:105], v[184:187], v[46:49], v[70:73]
	s_waitcnt lgkmcnt(3)
	v_mfma_f32_16x16x32_bf16 v[70:73], v[6:9], v[54:57], v[160:163]
	s_waitcnt lgkmcnt(2)
	v_mfma_f32_16x16x32_bf16 v[94:97], v[14:17], v[188:191], v[70:73]
	v_mfma_f32_16x16x32_bf16 v[70:73], v[180:183], v[54:57], v[106:109]
	v_mfma_f32_16x16x32_bf16 v[86:89], v[184:187], v[188:191], v[70:73]
	s_waitcnt lgkmcnt(1)
	v_mfma_f32_16x16x32_bf16 v[70:73], v[6:9], v[200:203], v[196:199]
	s_waitcnt lgkmcnt(0)
	v_mfma_f32_16x16x32_bf16 v[78:81], v[14:17], v[236:239], v[70:73]
	v_mfma_f32_16x16x32_bf16 v[70:73], v[180:183], v[200:203], v[98:101]
	v_mfma_f32_16x16x32_bf16 v[70:73], v[184:187], v[236:239], v[70:73]
	s_setprio 0
	s_barrier
	ds_read_b128 v[130:133], v151 offset:49152
	ds_read_b128 v[160:163], v151 offset:50176
	ds_read_b128 v[196:199], v151 offset:51200
	ds_read_b128 v[148:151], v151 offset:52224
	s_waitcnt vmcnt(0)
	s_barrier
	s_waitcnt lgkmcnt(0)
	s_setprio 1
	s_waitcnt lgkmcnt(3)
	v_mfma_f32_16x16x32_bf16 v[98:101], v[130:133], v[22:25], v[222:225]
	s_waitcnt lgkmcnt(1)
	v_mfma_f32_16x16x32_bf16 v[22:25], v[196:199], v[22:25], v[90:93]
	s_waitcnt lgkmcnt(0)
	v_mfma_f32_16x16x32_bf16 v[114:117], v[148:151], v[30:33], v[22:25]
	v_mfma_f32_16x16x32_bf16 v[22:25], v[130:133], v[38:41], v[164:167]
	v_mfma_f32_16x16x32_bf16 v[106:109], v[160:163], v[46:49], v[22:25]
	v_mfma_f32_16x16x32_bf16 v[22:25], v[196:199], v[38:41], v[82:85]
	v_mfma_f32_16x16x32_bf16 v[122:125], v[160:163], v[30:33], v[98:101]
	v_mfma_f32_16x16x32_bf16 v[98:101], v[148:151], v[46:49], v[22:25]
	v_mfma_f32_16x16x32_bf16 v[22:25], v[130:133], v[54:57], v[168:171]
	v_mfma_f32_16x16x32_bf16 v[90:93], v[160:163], v[188:191], v[22:25]
	v_mfma_f32_16x16x32_bf16 v[22:25], v[196:199], v[54:57], v[74:77]
	v_mfma_f32_16x16x32_bf16 v[82:85], v[148:151], v[188:191], v[22:25]
	v_mfma_f32_16x16x32_bf16 v[22:25], v[130:133], v[200:203], v[172:175]
	v_mfma_f32_16x16x32_bf16 v[74:77], v[160:163], v[236:239], v[22:25]
	v_mfma_f32_16x16x32_bf16 v[22:25], v[196:199], v[200:203], v[66:69]
	v_mfma_f32_16x16x32_bf16 v[66:69], v[148:151], v[236:239], v[22:25]
	s_setprio 0
	s_barrier
	ds_read_b128 v[164:167], v0 offset:49152
	ds_read_b128 v[168:171], v0 offset:50176
	ds_read_b128 v[172:175], v0 offset:51200
	ds_read_b128 v[188:191], v0 offset:52224
	ds_read_b128 v[200:203], v0 offset:53248
	ds_read_b128 v[222:225], v0 offset:54272
	ds_read_b128 v[236:239], v0 offset:55296
	ds_read_b128 v[240:243], v0 offset:56320
	s_barrier
	s_waitcnt lgkmcnt(0)
	s_setprio 1
	s_waitcnt lgkmcnt(7)
	v_mfma_f32_16x16x32_bf16 v[22:25], v[6:9], v[164:167], v[62:65]
	s_waitcnt lgkmcnt(6)
	v_mfma_f32_16x16x32_bf16 v[62:65], v[14:17], v[168:171], v[22:25]
	v_mfma_f32_16x16x32_bf16 v[22:25], v[180:183], v[164:167], v[58:61]
	v_mfma_f32_16x16x32_bf16 v[54:57], v[184:187], v[168:171], v[22:25]
	s_waitcnt lgkmcnt(5)
	v_mfma_f32_16x16x32_bf16 v[22:25], v[6:9], v[172:175], v[192:195]
	s_waitcnt lgkmcnt(4)
	v_mfma_f32_16x16x32_bf16 v[46:49], v[14:17], v[188:191], v[22:25]
	v_mfma_f32_16x16x32_bf16 v[22:25], v[180:183], v[172:175], v[50:53]
	v_mfma_f32_16x16x32_bf16 v[38:41], v[184:187], v[188:191], v[22:25]
	s_waitcnt lgkmcnt(3)
	v_mfma_f32_16x16x32_bf16 v[22:25], v[6:9], v[200:203], v[232:235]
	s_waitcnt lgkmcnt(1)
	v_mfma_f32_16x16x32_bf16 v[6:9], v[6:9], v[236:239], v[134:137]
	v_mfma_f32_16x16x32_bf16 v[30:33], v[14:17], v[222:225], v[22:25]
	v_mfma_f32_16x16x32_bf16 v[22:25], v[180:183], v[200:203], v[42:45]
	s_waitcnt lgkmcnt(0)
	v_mfma_f32_16x16x32_bf16 v[14:17], v[14:17], v[240:243], v[6:9]
	v_mfma_f32_16x16x32_bf16 v[6:9], v[180:183], v[236:239], v[34:37]
	v_mfma_f32_16x16x32_bf16 v[22:25], v[184:187], v[222:225], v[22:25]
	v_mfma_f32_16x16x32_bf16 v[6:9], v[184:187], v[240:243], v[6:9]
	s_setprio 0
	s_setprio 1
	v_mfma_f32_16x16x32_bf16 v[34:37], v[130:133], v[164:167], v[138:141]
	v_mfma_f32_16x16x32_bf16 v[26:29], v[196:199], v[164:167], v[26:29]
	v_mfma_f32_16x16x32_bf16 v[18:21], v[196:199], v[172:175], v[18:21]
	v_mfma_f32_16x16x32_bf16 v[58:61], v[160:163], v[168:171], v[34:37]
	v_mfma_f32_16x16x32_bf16 v[50:53], v[148:151], v[168:171], v[26:29]
	v_mfma_f32_16x16x32_bf16 v[26:29], v[130:133], v[172:175], v[152:155]
	v_mfma_f32_16x16x32_bf16 v[34:37], v[148:151], v[188:191], v[18:21]
	v_mfma_f32_16x16x32_bf16 v[18:21], v[130:133], v[200:203], v[156:159]
	v_mfma_f32_16x16x32_bf16 v[10:13], v[196:199], v[200:203], v[10:13]
	v_mfma_f32_16x16x32_bf16 v[42:45], v[160:163], v[188:191], v[26:29]
	v_mfma_f32_16x16x32_bf16 v[26:29], v[160:163], v[222:225], v[18:21]
	v_mfma_f32_16x16x32_bf16 v[18:21], v[148:151], v[222:225], v[10:13]
	v_mfma_f32_16x16x32_bf16 v[10:13], v[130:133], v[236:239], v[176:179]
	v_mfma_f32_16x16x32_bf16 v[2:5], v[196:199], v[236:239], v[2:5]
	v_mfma_f32_16x16x32_bf16 v[10:13], v[160:163], v[240:243], v[10:13]
	v_mfma_f32_16x16x32_bf16 v[2:5], v[148:151], v[240:243], v[2:5]
	s_setprio 0
	s_movk_i32 s0, 0x100
	v_cmp_gt_u32_e32 vcc, s0, v142
	s_barrier
	s_and_saveexec_b64 s[0:1], vcc
	s_cbranch_execz .LBB0_183
	s_barrier

.LBB0_677:
	s_or_b64 exec, exec, s[16:17]
	v_mov_b32_e32 v3, v1
	v_lshl_add_u64 v[12:13], s[0:1], 0, v[2:3]
	v_lshl_add_u64 v[16:17], s[10:11], 0, v[2:3]
	v_lshl_add_u64 v[20:21], s[12:13], 0, v[2:3]
	v_lshl_add_u64 v[130:131], s[14:15], 0, v[2:3]
	v_and_b32_e32 v146, 15, v142
	v_bfe_u32 v145, v142, 4, 2
	v_lshlrev_b32_e32 v3, 2, v142
	v_add_u32_e32 v156, 0x18000, v147
	v_lshl_add_u64 v[10:11], s[0:1], 0, v[0:1]
	v_lshl_add_u64 v[14:15], s[10:11], 0, v[0:1]
	v_lshl_add_u64 v[18:19], s[12:13], 0, v[0:1]
	v_lshl_add_u64 v[132:133], s[14:15], 0, v[0:1]
	v_lshlrev_b32_e32 v0, 6, v146
	v_lshlrev_b32_e32 v2, 4, v145
	v_and_b32_e32 v3, 32, v3
	s_mov_b64 s[10:11], 0x80
	v_readfirstlane_b32 s0, v156
	v_add_u32_e32 v157, 0x1a000, v147
	v_bitop3_b32 v22, v2, v3, v0 bitop3:0x36
	v_lshl_add_u64 v[2:3], v[10:11], 0, s[10:11]
	s_mov_b32 m0, s0
	v_readfirstlane_b32 s0, v157
	v_add_u32_e32 v158, 0x8000, v147
	s_waitcnt vmcnt(4)
	s_barrier
	global_load_lds_dwordx4 v[2:3], off
	v_lshl_add_u64 v[2:3], v[12:13], 0, s[10:11]
	s_mov_b32 m0, s0
	v_readfirstlane_b32 s0, v158
	v_add_u32_e32 v159, 0xa000, v147
	global_load_lds_dwordx4 v[2:3], off
	v_lshl_add_u64 v[2:3], v[14:15], 0, s[10:11]
	s_mov_b32 m0, s0
	v_readfirstlane_b32 s0, v159
	v_add_u32_e32 v160, 0x1c000, v147
	global_load_lds_dwordx4 v[2:3], off
	v_lshl_add_u64 v[2:3], v[16:17], 0, s[10:11]
	s_mov_b32 m0, s0
	v_readfirstlane_b32 s0, v160
	v_add_u32_e32 v161, 0x1e000, v147
	global_load_lds_dwordx4 v[2:3], off
	v_lshl_add_u64 v[2:3], v[18:19], 0, s[10:11]
	s_mov_b32 m0, s0
	v_readfirstlane_b32 s0, v161
	global_load_lds_dwordx4 v[2:3], off
	v_lshl_add_u64 v[2:3], v[20:21], 0, s[10:11]
	s_mov_b32 m0, s0
	s_sub_i32 s1, s57, s64
	global_load_lds_dwordx4 v[2:3], off
	s_sub_i32 s1, s1, s63
	v_lshlrev_b32_e32 v0, 15, v4
	s_sext_i32_i16 s1, s1
	v_and_b32_e32 v0, 0xffff0000, v0
	s_lshl_b32 s0, s62, 10
	s_lshl_b32 s1, s1, 8
	v_lshl_add_u32 v0, v5, 12, v0
	v_and_b32_e32 v2, 1, v4
	s_add_i32 s0, s0, s1
	v_lshl_or_b32 v0, v2, 6, v0
	v_lshlrev_b32_e32 v2, 15, v6
	s_ashr_i32 s1, s0, 31
	v_and_b32_e32 v2, 0xffff0000, v2
	s_lshl_b64 s[0:1], s[0:1], 12
	v_lshl_add_u32 v2, v8, 12, v2
	v_and_b32_e32 v3, 1, v6
	s_add_u32 s0, s52, s0
	v_lshl_or_b32 v2, v3, 6, v2
	v_lshl_add_u32 v0, v7, 1, v0
	s_addc_u32 s1, s53, s1
	v_lshl_add_u32 v2, v9, 1, v2
	v_mov_b32_e32 v3, v1
	v_lshl_add_u64 v[134:135], s[0:1], 0, v[0:1]
	v_lshl_add_u64 v[136:137], s[0:1], 0, v[2:3]
	s_add_u32 s0, s88, s8
	v_bfe_u32 v144, v142, 6, 2
	s_waitcnt vmcnt(6)
	s_addc_u32 s1, s89, s9
	v_lshlrev_b32_e32 v23, 13, v143
	v_lshl_or_b32 v24, v144, 12, v212
	v_lshl_add_u64 v[140:141], s[0:1], 0, v[2:3]
	v_mov_b32_e32 v2, 0
	v_lshl_add_u64 v[138:139], s[0:1], 0, v[0:1]
	s_mov_b32 s0, -2
	s_mov_b64 s[8:9], 0
	v_add_u32_e32 v151, v24, v22
	v_add_u32_e32 v0, v23, v22
	v_mov_b32_e32 v3, v2
	v_mov_b32_e32 v4, v2
	v_mov_b32_e32 v5, v2
	v_mov_b32_e32 v6, v2
	v_mov_b32_e32 v7, v2
	v_mov_b32_e32 v8, v2
	v_mov_b32_e32 v9, v2
	v_mov_b32_e32 v10, v2
	v_mov_b32_e32 v11, v2
	v_mov_b32_e32 v12, v2
	v_mov_b32_e32 v13, v2
	v_mov_b32_e32 v14, v2
	v_mov_b32_e32 v15, v2
	v_mov_b32_e32 v16, v2
	v_mov_b32_e32 v17, v2
	v_mov_b32_e32 v18, v2
	v_mov_b32_e32 v19, v2
	v_mov_b32_e32 v20, v2
	v_mov_b32_e32 v21, v2
	v_mov_b32_e32 v22, v2
	v_mov_b32_e32 v23, v2
	v_mov_b32_e32 v24, v2
	v_mov_b32_e32 v25, v2
	v_mov_b32_e32 v26, v2
	v_mov_b32_e32 v27, v2
	v_mov_b32_e32 v28, v2
	v_mov_b32_e32 v29, v2
	v_mov_b32_e32 v30, v2
	v_mov_b32_e32 v31, v2
	v_mov_b32_e32 v32, v2
	v_mov_b32_e32 v33, v2
	v_mov_b32_e32 v34, v2
	v_mov_b32_e32 v35, v2
	v_mov_b32_e32 v36, v2
	v_mov_b32_e32 v37, v2
	v_mov_b32_e32 v38, v2
	v_mov_b32_e32 v39, v2
	v_mov_b32_e32 v40, v2
	v_mov_b32_e32 v41, v2
	v_mov_b32_e32 v42, v2
	v_mov_b32_e32 v43, v2
	v_mov_b32_e32 v44, v2
	v_mov_b32_e32 v45, v2
	v_mov_b32_e32 v46, v2
	v_mov_b32_e32 v47, v2
	v_mov_b32_e32 v48, v2
	v_mov_b32_e32 v49, v2
	v_mov_b32_e32 v50, v2
	v_mov_b32_e32 v51, v2
	v_mov_b32_e32 v52, v2
	v_mov_b32_e32 v53, v2
	v_mov_b32_e32 v54, v2
	v_mov_b32_e32 v55, v2
	v_mov_b32_e32 v56, v2
	v_mov_b32_e32 v57, v2
	v_mov_b32_e32 v58, v2
	v_mov_b32_e32 v59, v2
	v_mov_b32_e32 v60, v2
	v_mov_b32_e32 v61, v2
	v_mov_b32_e32 v62, v2
	v_mov_b32_e32 v63, v2
	v_mov_b32_e32 v64, v2
	v_mov_b32_e32 v65, v2
	v_mov_b32_e32 v66, v2
	v_mov_b32_e32 v67, v2
	v_mov_b32_e32 v68, v2
	v_mov_b32_e32 v69, v2
	v_mov_b32_e32 v70, v2
	v_mov_b32_e32 v71, v2
	v_mov_b32_e32 v72, v2
	v_mov_b32_e32 v73, v2
	v_mov_b32_e32 v74, v2
	v_mov_b32_e32 v75, v2
	v_mov_b32_e32 v76, v2
	v_mov_b32_e32 v77, v2
	v_mov_b32_e32 v78, v2
	v_mov_b32_e32 v79, v2
	v_mov_b32_e32 v80, v2
	v_mov_b32_e32 v81, v2
	v_mov_b32_e32 v82, v2
	v_mov_b32_e32 v83, v2
	v_mov_b32_e32 v84, v2
	v_mov_b32_e32 v85, v2
	v_mov_b32_e32 v86, v2
	v_mov_b32_e32 v87, v2
	v_mov_b32_e32 v88, v2
	v_mov_b32_e32 v89, v2
	v_mov_b32_e32 v90, v2
	v_mov_b32_e32 v91, v2
	v_mov_b32_e32 v92, v2
	v_mov_b32_e32 v93, v2
	v_mov_b32_e32 v94, v2
	v_mov_b32_e32 v95, v2
	v_mov_b32_e32 v96, v2
	v_mov_b32_e32 v97, v2
	v_mov_b32_e32 v98, v2
	v_mov_b32_e32 v99, v2
	v_mov_b32_e32 v100, v2
	v_mov_b32_e32 v101, v2
	v_mov_b32_e32 v102, v2
	v_mov_b32_e32 v103, v2
	v_mov_b32_e32 v104, v2
	v_mov_b32_e32 v105, v2
	v_mov_b32_e32 v106, v2
	v_mov_b32_e32 v107, v2
	v_mov_b32_e32 v108, v2
	v_mov_b32_e32 v109, v2
	v_mov_b32_e32 v110, v2
	v_mov_b32_e32 v111, v2
	v_mov_b32_e32 v112, v2
	v_mov_b32_e32 v113, v2
	v_mov_b32_e32 v114, v2
	v_mov_b32_e32 v115, v2
	v_mov_b32_e32 v116, v2
	v_mov_b32_e32 v117, v2
	v_mov_b32_e32 v118, v2
	v_mov_b32_e32 v119, v2
	v_mov_b32_e32 v120, v2
	v_mov_b32_e32 v121, v2
	v_mov_b32_e32 v122, v2
	v_mov_b32_e32 v123, v2
	v_mov_b32_e32 v124, v2
	v_mov_b32_e32 v125, v2
	v_mov_b32_e32 v126, v2
	v_mov_b32_e32 v127, v2
	v_mov_b32_e32 v128, v2
	v_mov_b32_e32 v129, v2
	s_barrier
	v_add_u32_e32 v162, 0xc000, v147
	v_add_u32_e32 v163, 0xe000, v147
	v_readfirstlane_b32 s1, v147
	s_nop 1
.LBB0_678:
	ds_read_b128 v[164:167], v151
	ds_read_b128 v[168:171], v151 offset:1024
	ds_read_b128 v[172:175], v151 offset:2048
	ds_read_b128 v[176:179], v151 offset:3072
	v_lshl_add_u64 v[204:205], v[138:139], 0, s[8:9]
	v_lshl_add_u64 v[218:219], v[204:205], 0, s[60:61]
	s_add_i32 m0, s1, 0xc000
	ds_read_b128 v[180:183], v0
	ds_read_b128 v[184:187], v0 offset:1024
	ds_read_b128 v[188:191], v0 offset:2048
	ds_read_b128 v[192:195], v0 offset:3072
	ds_read_b128 v[196:199], v0 offset:4096
	ds_read_b128 v[200:203], v0 offset:5120
	ds_read_b128 v[232:235], v0 offset:6144
	ds_read_b128 v[236:239], v0 offset:7168
	global_load_lds_dwordx4 v[218:219], off
	v_lshl_add_u64 v[216:217], v[140:141], 0, s[8:9]
	s_add_i32 m0, s1, 0xe000
	v_lshl_add_u64 v[152:153], v[216:217], 0, s[60:61]
	global_load_lds_dwordx4 v[152:153], off
	s_waitcnt lgkmcnt(8)
	s_barrier
	s_waitcnt lgkmcnt(0)
	s_setprio 1
	v_mfma_f32_16x16x32_bf16 v[126:129], v[164:167], v[180:183], v[126:129]
	v_mfma_f32_16x16x32_bf16 v[122:125], v[172:175], v[180:183], v[122:125]
	v_mfma_f32_16x16x32_bf16 v[118:121], v[164:167], v[188:191], v[118:121]
	v_mfma_f32_16x16x32_bf16 v[114:117], v[172:175], v[188:191], v[114:117]
	v_mfma_f32_16x16x32_bf16 v[110:113], v[164:167], v[196:199], v[110:113]
	v_mfma_f32_16x16x32_bf16 v[106:109], v[172:175], v[196:199], v[106:109]
	v_mfma_f32_16x16x32_bf16 v[102:105], v[164:167], v[232:235], v[102:105]
	v_mfma_f32_16x16x32_bf16 v[98:101], v[172:175], v[232:235], v[98:101]
	v_mfma_f32_16x16x32_bf16 v[126:129], v[168:171], v[184:187], v[126:129]
	v_mfma_f32_16x16x32_bf16 v[122:125], v[176:179], v[184:187], v[122:125]
	v_mfma_f32_16x16x32_bf16 v[118:121], v[168:171], v[192:195], v[118:121]
	v_mfma_f32_16x16x32_bf16 v[114:117], v[176:179], v[192:195], v[114:117]
	v_mfma_f32_16x16x32_bf16 v[110:113], v[168:171], v[200:203], v[110:113]
	v_mfma_f32_16x16x32_bf16 v[106:109], v[176:179], v[200:203], v[106:109]
	v_mfma_f32_16x16x32_bf16 v[102:105], v[168:171], v[236:239], v[102:105]
	v_mfma_f32_16x16x32_bf16 v[98:101], v[176:179], v[236:239], v[98:101]
	s_setprio 0
	s_barrier
	v_lshl_add_u64 v[210:211], v[134:135], 0, s[8:9]
	s_add_i32 m0, s1, 0xff00
	ds_read_b128 v[240:243], v151 offset:16384
	ds_read_b128 v[244:247], v151 offset:17408
	ds_read_b128 v[248:251], v151 offset:18432
	ds_read_b128 v[222:225], v151 offset:19456
	global_load_lds_dwordx4 v[210:211], off offset:256
	s_add_i32 m0, s1, 0x11f00
	v_lshl_add_u64 v[228:229], v[136:137], 0, s[8:9]
	global_load_lds_dwordx4 v[228:229], off offset:256
	s_barrier
	s_waitcnt lgkmcnt(0)
	s_setprio 1
	v_mfma_f32_16x16x32_bf16 v[94:97], v[240:243], v[180:183], v[94:97]
	v_mfma_f32_16x16x32_bf16 v[90:93], v[248:251], v[180:183], v[90:93]
	v_mfma_f32_16x16x32_bf16 v[86:89], v[240:243], v[188:191], v[86:89]
	v_mfma_f32_16x16x32_bf16 v[82:85], v[248:251], v[188:191], v[82:85]
	v_mfma_f32_16x16x32_bf16 v[78:81], v[240:243], v[196:199], v[78:81]
	v_mfma_f32_16x16x32_bf16 v[74:77], v[248:251], v[196:199], v[74:77]
	v_mfma_f32_16x16x32_bf16 v[70:73], v[240:243], v[232:235], v[70:73]
	v_mfma_f32_16x16x32_bf16 v[66:69], v[248:251], v[232:235], v[66:69]
	v_mfma_f32_16x16x32_bf16 v[94:97], v[244:247], v[184:187], v[94:97]
	v_mfma_f32_16x16x32_bf16 v[90:93], v[222:225], v[184:187], v[90:93]
	v_mfma_f32_16x16x32_bf16 v[86:89], v[244:247], v[192:195], v[86:89]
	v_mfma_f32_16x16x32_bf16 v[82:85], v[222:225], v[192:195], v[82:85]
	v_mfma_f32_16x16x32_bf16 v[78:81], v[244:247], v[200:203], v[78:81]
	v_mfma_f32_16x16x32_bf16 v[74:77], v[222:225], v[200:203], v[74:77]
	v_mfma_f32_16x16x32_bf16 v[70:73], v[244:247], v[236:239], v[70:73]
	v_mfma_f32_16x16x32_bf16 v[66:69], v[222:225], v[236:239], v[66:69]
	s_setprio 0
	v_lshl_add_u64 v[158:159], v[204:205], 0, s[74:75]
	s_mov_b32 m0, s1
	s_barrier
	ds_read_b128 v[180:183], v0 offset:16384
	ds_read_b128 v[184:187], v0 offset:17408
	ds_read_b128 v[188:191], v0 offset:18432
	ds_read_b128 v[192:195], v0 offset:19456
	ds_read_b128 v[196:199], v0 offset:20480
	ds_read_b128 v[200:203], v0 offset:21504
	ds_read_b128 v[232:235], v0 offset:22528
	ds_read_b128 v[236:239], v0 offset:23552
	global_load_lds_dwordx4 v[158:159], off
	s_add_i32 m0, s1, 0x1f00
	s_nop 0
	global_load_lds_dwordx4 v[216:217], off offset:256
	s_barrier
	s_waitcnt lgkmcnt(0)
	s_setprio 1
	v_mfma_f32_16x16x32_bf16 v[62:65], v[164:167], v[180:183], v[62:65]
	v_mfma_f32_16x16x32_bf16 v[58:61], v[172:175], v[180:183], v[58:61]
	v_mfma_f32_16x16x32_bf16 v[54:57], v[164:167], v[188:191], v[54:57]
	v_mfma_f32_16x16x32_bf16 v[50:53], v[172:175], v[188:191], v[50:53]
	v_mfma_f32_16x16x32_bf16 v[46:49], v[164:167], v[196:199], v[46:49]
	v_mfma_f32_16x16x32_bf16 v[42:45], v[172:175], v[196:199], v[42:45]
	v_mfma_f32_16x16x32_bf16 v[38:41], v[164:167], v[232:235], v[38:41]
	v_mfma_f32_16x16x32_bf16 v[34:37], v[172:175], v[232:235], v[34:37]
	v_mfma_f32_16x16x32_bf16 v[62:65], v[168:171], v[184:187], v[62:65]
	v_mfma_f32_16x16x32_bf16 v[58:61], v[176:179], v[184:187], v[58:61]
	v_mfma_f32_16x16x32_bf16 v[54:57], v[168:171], v[192:195], v[54:57]
	v_mfma_f32_16x16x32_bf16 v[50:53], v[176:179], v[192:195], v[50:53]
	v_mfma_f32_16x16x32_bf16 v[46:49], v[168:171], v[200:203], v[46:49]
	v_mfma_f32_16x16x32_bf16 v[42:45], v[176:179], v[200:203], v[42:45]
	v_mfma_f32_16x16x32_bf16 v[38:41], v[168:171], v[236:239], v[38:41]
	v_mfma_f32_16x16x32_bf16 v[34:37], v[176:179], v[236:239], v[34:37]
	s_setprio 0
	s_barrier
	s_add_i32 m0, s1, 0x14000
	v_lshl_add_u64 v[154:155], v[210:211], 0, s[18:19]
	global_load_lds_dwordx4 v[154:155], off
	s_add_i32 m0, s1, 0x16000
	v_lshl_add_u64 v[156:157], v[228:229], 0, s[18:19]
	global_load_lds_dwordx4 v[156:157], off
	s_waitcnt vmcnt(6)
	s_barrier
	s_setprio 1
	v_mfma_f32_16x16x32_bf16 v[30:33], v[240:243], v[180:183], v[30:33]
	v_mfma_f32_16x16x32_bf16 v[26:29], v[248:251], v[180:183], v[26:29]
	v_mfma_f32_16x16x32_bf16 v[22:25], v[240:243], v[188:191], v[22:25]
	v_mfma_f32_16x16x32_bf16 v[18:21], v[248:251], v[188:191], v[18:21]
	v_mfma_f32_16x16x32_bf16 v[14:17], v[240:243], v[196:199], v[14:17]
	v_mfma_f32_16x16x32_bf16 v[10:13], v[248:251], v[196:199], v[10:13]
	v_mfma_f32_16x16x32_bf16 v[6:9], v[240:243], v[232:235], v[6:9]
	v_mfma_f32_16x16x32_bf16 v[2:5], v[248:251], v[232:235], v[2:5]
	v_mfma_f32_16x16x32_bf16 v[30:33], v[244:247], v[184:187], v[30:33]
	v_mfma_f32_16x16x32_bf16 v[26:29], v[222:225], v[184:187], v[26:29]
	v_mfma_f32_16x16x32_bf16 v[22:25], v[244:247], v[192:195], v[22:25]
	v_mfma_f32_16x16x32_bf16 v[18:21], v[222:225], v[192:195], v[18:21]
	v_mfma_f32_16x16x32_bf16 v[14:17], v[244:247], v[200:203], v[14:17]
	v_mfma_f32_16x16x32_bf16 v[10:13], v[222:225], v[200:203], v[10:13]
	v_mfma_f32_16x16x32_bf16 v[6:9], v[244:247], v[236:239], v[6:9]
	v_mfma_f32_16x16x32_bf16 v[2:5], v[222:225], v[236:239], v[2:5]
	s_setprio 0
	s_barrier
	ds_read_b128 v[164:167], v151 offset:32768
	ds_read_b128 v[168:171], v151 offset:33792
	ds_read_b128 v[172:175], v151 offset:34816
	ds_read_b128 v[176:179], v151 offset:35840
	s_add_i32 m0, s1, 0x3f80
	ds_read_b128 v[180:183], v0 offset:32768
	ds_read_b128 v[184:187], v0 offset:33792
	ds_read_b128 v[188:191], v0 offset:34816
	ds_read_b128 v[192:195], v0 offset:35840
	ds_read_b128 v[196:199], v0 offset:36864
	ds_read_b128 v[200:203], v0 offset:37888
	ds_read_b128 v[222:225], v0 offset:38912
	ds_read_b128 v[232:235], v0 offset:39936
	global_load_lds_dwordx4 v[218:219], off offset:128
	s_add_i32 m0, s1, 0x5f80
	s_nop 0
	global_load_lds_dwordx4 v[152:153], off offset:128
	s_waitcnt lgkmcnt(8)
	s_barrier
	s_waitcnt lgkmcnt(0)
	s_setprio 1
	v_mfma_f32_16x16x32_bf16 v[126:129], v[164:167], v[180:183], v[126:129]
	v_mfma_f32_16x16x32_bf16 v[122:125], v[172:175], v[180:183], v[122:125]
	v_mfma_f32_16x16x32_bf16 v[118:121], v[164:167], v[188:191], v[118:121]
	v_mfma_f32_16x16x32_bf16 v[114:117], v[172:175], v[188:191], v[114:117]
	v_mfma_f32_16x16x32_bf16 v[110:113], v[164:167], v[196:199], v[110:113]
	v_mfma_f32_16x16x32_bf16 v[106:109], v[172:175], v[196:199], v[106:109]
	v_mfma_f32_16x16x32_bf16 v[102:105], v[164:167], v[222:225], v[102:105]
	v_mfma_f32_16x16x32_bf16 v[98:101], v[172:175], v[222:225], v[98:101]
	v_mfma_f32_16x16x32_bf16 v[126:129], v[168:171], v[184:187], v[126:129]
	v_mfma_f32_16x16x32_bf16 v[122:125], v[176:179], v[184:187], v[122:125]
	v_mfma_f32_16x16x32_bf16 v[118:121], v[168:171], v[192:195], v[118:121]
	v_mfma_f32_16x16x32_bf16 v[114:117], v[176:179], v[192:195], v[114:117]
	v_mfma_f32_16x16x32_bf16 v[110:113], v[168:171], v[200:203], v[110:113]
	v_mfma_f32_16x16x32_bf16 v[106:109], v[176:179], v[200:203], v[106:109]
	v_mfma_f32_16x16x32_bf16 v[102:105], v[168:171], v[232:235], v[102:105]
	v_mfma_f32_16x16x32_bf16 v[98:101], v[176:179], v[232:235], v[98:101]
	s_setprio 0
	s_barrier
	s_add_i32 m0, s1, 0x17e80
	ds_read_b128 v[236:239], v151 offset:49152
	ds_read_b128 v[240:243], v151 offset:50176
	ds_read_b128 v[244:247], v151 offset:51200
	ds_read_b128 v[248:251], v151 offset:52224
	global_load_lds_dwordx4 v[210:211], off offset:384
	s_add_i32 m0, s1, 0x19e80
	s_nop 0
	global_load_lds_dwordx4 v[228:229], off offset:384
	s_barrier
	s_waitcnt lgkmcnt(0)
	s_setprio 1
	v_mfma_f32_16x16x32_bf16 v[94:97], v[236:239], v[180:183], v[94:97]
	v_mfma_f32_16x16x32_bf16 v[90:93], v[244:247], v[180:183], v[90:93]
	v_mfma_f32_16x16x32_bf16 v[86:89], v[236:239], v[188:191], v[86:89]
	v_mfma_f32_16x16x32_bf16 v[82:85], v[244:247], v[188:191], v[82:85]
	v_mfma_f32_16x16x32_bf16 v[78:81], v[236:239], v[196:199], v[78:81]
	v_mfma_f32_16x16x32_bf16 v[74:77], v[244:247], v[196:199], v[74:77]
	v_mfma_f32_16x16x32_bf16 v[70:73], v[236:239], v[222:225], v[70:73]
	v_mfma_f32_16x16x32_bf16 v[66:69], v[244:247], v[222:225], v[66:69]
	v_mfma_f32_16x16x32_bf16 v[94:97], v[240:243], v[184:187], v[94:97]
	v_mfma_f32_16x16x32_bf16 v[90:93], v[248:251], v[184:187], v[90:93]
	v_mfma_f32_16x16x32_bf16 v[86:89], v[240:243], v[192:195], v[86:89]
	v_mfma_f32_16x16x32_bf16 v[82:85], v[248:251], v[192:195], v[82:85]
	v_mfma_f32_16x16x32_bf16 v[78:81], v[240:243], v[200:203], v[78:81]
	v_mfma_f32_16x16x32_bf16 v[74:77], v[248:251], v[200:203], v[74:77]
	v_mfma_f32_16x16x32_bf16 v[70:73], v[240:243], v[232:235], v[70:73]
	v_mfma_f32_16x16x32_bf16 v[66:69], v[248:251], v[232:235], v[66:69]
	s_setprio 0
	s_add_i32 m0, s1, 0x7e80
	s_barrier
	ds_read_b128 v[180:183], v0 offset:49152
	ds_read_b128 v[184:187], v0 offset:50176
	ds_read_b128 v[188:191], v0 offset:51200
	ds_read_b128 v[192:195], v0 offset:52224
	ds_read_b128 v[196:199], v0 offset:53248
	ds_read_b128 v[200:203], v0 offset:54272
	ds_read_b128 v[222:225], v0 offset:55296
	ds_read_b128 v[232:235], v0 offset:56320
	global_load_lds_dwordx4 v[204:205], off offset:384
	s_add_i32 m0, s1, 0x9e80
	s_nop 0
	global_load_lds_dwordx4 v[216:217], off offset:384
	s_barrier
	s_waitcnt lgkmcnt(0)
	s_setprio 1
	v_mfma_f32_16x16x32_bf16 v[62:65], v[164:167], v[180:183], v[62:65]
	v_mfma_f32_16x16x32_bf16 v[58:61], v[172:175], v[180:183], v[58:61]
	v_mfma_f32_16x16x32_bf16 v[54:57], v[164:167], v[188:191], v[54:57]
	v_mfma_f32_16x16x32_bf16 v[50:53], v[172:175], v[188:191], v[50:53]
	v_mfma_f32_16x16x32_bf16 v[46:49], v[164:167], v[196:199], v[46:49]
	v_mfma_f32_16x16x32_bf16 v[42:45], v[172:175], v[196:199], v[42:45]
	v_mfma_f32_16x16x32_bf16 v[38:41], v[164:167], v[222:225], v[38:41]
	v_mfma_f32_16x16x32_bf16 v[34:37], v[172:175], v[222:225], v[34:37]
	v_mfma_f32_16x16x32_bf16 v[62:65], v[168:171], v[184:187], v[62:65]
	v_mfma_f32_16x16x32_bf16 v[58:61], v[176:179], v[184:187], v[58:61]
	v_mfma_f32_16x16x32_bf16 v[54:57], v[168:171], v[192:195], v[54:57]
	v_mfma_f32_16x16x32_bf16 v[50:53], v[176:179], v[192:195], v[50:53]
	v_mfma_f32_16x16x32_bf16 v[46:49], v[168:171], v[200:203], v[46:49]
	v_mfma_f32_16x16x32_bf16 v[42:45], v[176:179], v[200:203], v[42:45]
	v_mfma_f32_16x16x32_bf16 v[38:41], v[168:171], v[232:235], v[38:41]
	v_mfma_f32_16x16x32_bf16 v[34:37], v[176:179], v[232:235], v[34:37]
	s_setprio 0
	s_barrier
	s_add_i32 m0, s1, 0x1bf80
	s_nop 0
	global_load_lds_dwordx4 v[154:155], off offset:128
	s_add_i32 m0, s1, 0x1df80
	s_nop 0
	global_load_lds_dwordx4 v[156:157], off offset:128
	s_waitcnt vmcnt(6)
	s_barrier
	s_setprio 1
	v_mfma_f32_16x16x32_bf16 v[30:33], v[236:239], v[180:183], v[30:33]
	v_mfma_f32_16x16x32_bf16 v[26:29], v[244:247], v[180:183], v[26:29]
	v_mfma_f32_16x16x32_bf16 v[22:25], v[236:239], v[188:191], v[22:25]
	v_mfma_f32_16x16x32_bf16 v[18:21], v[244:247], v[188:191], v[18:21]
	v_mfma_f32_16x16x32_bf16 v[14:17], v[236:239], v[196:199], v[14:17]
	v_mfma_f32_16x16x32_bf16 v[10:13], v[244:247], v[196:199], v[10:13]
	v_mfma_f32_16x16x32_bf16 v[6:9], v[236:239], v[222:225], v[6:9]
	v_mfma_f32_16x16x32_bf16 v[2:5], v[244:247], v[222:225], v[2:5]
	v_mfma_f32_16x16x32_bf16 v[30:33], v[240:243], v[184:187], v[30:33]
	v_mfma_f32_16x16x32_bf16 v[26:29], v[248:251], v[184:187], v[26:29]
	v_mfma_f32_16x16x32_bf16 v[22:25], v[240:243], v[192:195], v[22:25]
	v_mfma_f32_16x16x32_bf16 v[18:21], v[248:251], v[192:195], v[18:21]
	v_mfma_f32_16x16x32_bf16 v[14:17], v[240:243], v[200:203], v[14:17]
	v_mfma_f32_16x16x32_bf16 v[10:13], v[248:251], v[200:203], v[10:13]
	v_mfma_f32_16x16x32_bf16 v[6:9], v[240:243], v[232:235], v[6:9]
	v_mfma_f32_16x16x32_bf16 v[2:5], v[248:251], v[232:235], v[2:5]
	s_setprio 0
	s_add_i32 s0, s0, 2
	s_add_u32 s8, s8, 0x100
	s_addc_u32 s9, s9, 0
	s_cmp_lt_u32 s0, 28
	s_barrier
	s_cbranch_scc1 .LBB0_678
	s_add_i32 s1, s1, 0x1e000
	s_mov_b64 s[8:9], 0xf80
	v_readfirstlane_b32 s0, v162
	v_lshl_add_u64 v[132:133], v[132:133], 0, s[8:9]
	s_mov_b32 m0, s0
	v_readfirstlane_b32 s0, v163
	ds_read_b128 v[134:137], v151
	ds_read_b128 v[138:141], v151 offset:1024
	ds_read_b128 v[152:155], v151 offset:2048
	ds_read_b128 v[156:159], v151 offset:3072
	ds_read_b128 v[164:167], v0
	ds_read_b128 v[168:171], v0 offset:1024
	ds_read_b128 v[172:175], v0 offset:2048
	ds_read_b128 v[176:179], v0 offset:3072
	ds_read_b128 v[180:183], v0 offset:4096
	ds_read_b128 v[184:187], v0 offset:5120
	ds_read_b128 v[188:191], v0 offset:6144
	ds_read_b128 v[192:195], v0 offset:7168
	global_load_lds_dwordx4 v[132:133], off
	v_lshl_add_u64 v[130:131], v[130:131], 0, s[8:9]
	s_mov_b32 m0, s0
	s_nop 0
	global_load_lds_dwordx4 v[130:131], off
	s_barrier
	s_waitcnt lgkmcnt(0)
	s_setprio 1
	s_waitcnt lgkmcnt(0)
	v_mfma_f32_16x16x32_bf16 v[126:129], v[134:137], v[164:167], v[126:129]
	v_mfma_f32_16x16x32_bf16 v[122:125], v[152:155], v[164:167], v[122:125]
	v_mfma_f32_16x16x32_bf16 v[114:117], v[152:155], v[172:175], v[114:117]
	v_mfma_f32_16x16x32_bf16 v[106:109], v[152:155], v[180:183], v[106:109]
	v_mfma_f32_16x16x32_bf16 v[98:101], v[152:155], v[188:191], v[98:101]
	v_mfma_f32_16x16x32_bf16 v[126:129], v[138:141], v[168:171], v[126:129]
	v_mfma_f32_16x16x32_bf16 v[122:125], v[156:159], v[168:171], v[122:125]
	v_mfma_f32_16x16x32_bf16 v[118:121], v[134:137], v[172:175], v[118:121]
	v_mfma_f32_16x16x32_bf16 v[114:117], v[156:159], v[176:179], v[114:117]
	v_mfma_f32_16x16x32_bf16 v[110:113], v[134:137], v[180:183], v[110:113]
	v_mfma_f32_16x16x32_bf16 v[106:109], v[156:159], v[184:187], v[106:109]
	v_mfma_f32_16x16x32_bf16 v[102:105], v[134:137], v[188:191], v[102:105]
	v_mfma_f32_16x16x32_bf16 v[98:101], v[156:159], v[192:195], v[98:101]
	v_mfma_f32_16x16x32_bf16 v[130:133], v[138:141], v[176:179], v[118:121]
	v_mfma_f32_16x16x32_bf16 v[160:163], v[138:141], v[184:187], v[110:113]
	v_mfma_f32_16x16x32_bf16 v[196:199], v[138:141], v[192:195], v[102:105]
	s_setprio 0
	s_barrier
	s_nop 0
	ds_read_b128 v[102:105], v151 offset:16384
	ds_read_b128 v[110:113], v151 offset:17408
	ds_read_b128 v[118:121], v151 offset:18432
	ds_read_b128 v[200:203], v151 offset:19456
	s_barrier
	s_waitcnt lgkmcnt(0)
	s_setprio 1
	s_waitcnt lgkmcnt(1)
	v_mfma_f32_16x16x32_bf16 v[90:93], v[118:121], v[164:167], v[90:93]
	v_mfma_f32_16x16x32_bf16 v[86:89], v[102:105], v[172:175], v[86:89]
	v_mfma_f32_16x16x32_bf16 v[82:85], v[118:121], v[172:175], v[82:85]
	v_mfma_f32_16x16x32_bf16 v[78:81], v[102:105], v[180:183], v[78:81]
	v_mfma_f32_16x16x32_bf16 v[70:73], v[102:105], v[188:191], v[70:73]
	v_mfma_f32_16x16x32_bf16 v[94:97], v[102:105], v[164:167], v[94:97]
	s_waitcnt lgkmcnt(0)
	v_mfma_f32_16x16x32_bf16 v[90:93], v[200:203], v[168:171], v[90:93]
	v_mfma_f32_16x16x32_bf16 v[86:89], v[110:113], v[176:179], v[86:89]
	v_mfma_f32_16x16x32_bf16 v[82:85], v[200:203], v[176:179], v[82:85]
	v_mfma_f32_16x16x32_bf16 v[78:81], v[110:113], v[184:187], v[78:81]
	v_mfma_f32_16x16x32_bf16 v[74:77], v[118:121], v[180:183], v[74:77]
	v_mfma_f32_16x16x32_bf16 v[70:73], v[110:113], v[192:195], v[70:73]
	v_mfma_f32_16x16x32_bf16 v[66:69], v[118:121], v[188:191], v[66:69]
	v_mfma_f32_16x16x32_bf16 v[222:225], v[110:113], v[168:171], v[94:97]
	v_mfma_f32_16x16x32_bf16 v[164:167], v[200:203], v[184:187], v[74:77]
	v_mfma_f32_16x16x32_bf16 v[168:171], v[200:203], v[192:195], v[66:69]
	s_setprio 0
	s_barrier
	s_nop 2
	ds_read_b128 v[66:69], v0 offset:16384
	ds_read_b128 v[74:77], v0 offset:17408
	ds_read_b128 v[94:97], v0 offset:18432
	ds_read_b128 v[172:175], v0 offset:19456
	ds_read_b128 v[176:179], v0 offset:20480
	ds_read_b128 v[180:183], v0 offset:21504
	ds_read_b128 v[184:187], v0 offset:22528
	ds_read_b128 v[188:191], v0 offset:23552
	s_waitcnt vmcnt(4)
	s_barrier
	s_waitcnt lgkmcnt(0)
	s_setprio 1
	s_waitcnt lgkmcnt(5)
	v_mfma_f32_16x16x32_bf16 v[54:57], v[134:137], v[94:97], v[54:57]
	v_mfma_f32_16x16x32_bf16 v[50:53], v[152:155], v[94:97], v[50:53]
	v_mfma_f32_16x16x32_bf16 v[62:65], v[134:137], v[66:69], v[62:65]
	v_mfma_f32_16x16x32_bf16 v[58:61], v[152:155], v[66:69], v[58:61]
	s_waitcnt lgkmcnt(4)
	v_mfma_f32_16x16x32_bf16 v[54:57], v[138:141], v[172:175], v[54:57]
	v_mfma_f32_16x16x32_bf16 v[50:53], v[156:159], v[172:175], v[50:53]
	s_waitcnt lgkmcnt(3)
	v_mfma_f32_16x16x32_bf16 v[46:49], v[134:137], v[176:179], v[46:49]
	v_mfma_f32_16x16x32_bf16 v[42:45], v[152:155], v[176:179], v[42:45]
	s_waitcnt lgkmcnt(1)
	v_mfma_f32_16x16x32_bf16 v[38:41], v[134:137], v[184:187], v[38:41]
	v_mfma_f32_16x16x32_bf16 v[34:37], v[152:155], v[184:187], v[34:37]
	v_mfma_f32_16x16x32_bf16 v[192:195], v[138:141], v[74:77], v[62:65]
	v_mfma_f32_16x16x32_bf16 v[232:235], v[156:159], v[74:77], v[58:61]
	v_mfma_f32_16x16x32_bf16 v[236:239], v[138:141], v[180:183], v[46:49]
	v_mfma_f32_16x16x32_bf16 v[240:243], v[156:159], v[180:183], v[42:45]
	s_waitcnt lgkmcnt(0)
	v_mfma_f32_16x16x32_bf16 v[134:137], v[138:141], v[188:191], v[38:41]
	v_mfma_f32_16x16x32_bf16 v[138:141], v[156:159], v[188:191], v[34:37]
	s_setprio 0
	s_setprio 1
	v_mfma_f32_16x16x32_bf16 v[30:33], v[102:105], v[66:69], v[30:33]
	v_mfma_f32_16x16x32_bf16 v[26:29], v[118:121], v[66:69], v[26:29]
	v_mfma_f32_16x16x32_bf16 v[14:17], v[102:105], v[176:179], v[14:17]
	v_mfma_f32_16x16x32_bf16 v[10:13], v[118:121], v[176:179], v[10:13]
	v_mfma_f32_16x16x32_bf16 v[30:33], v[110:113], v[74:77], v[30:33]
	v_mfma_f32_16x16x32_bf16 v[26:29], v[200:203], v[74:77], v[26:29]
	v_mfma_f32_16x16x32_bf16 v[22:25], v[102:105], v[94:97], v[22:25]
	v_mfma_f32_16x16x32_bf16 v[18:21], v[118:121], v[94:97], v[18:21]
	v_mfma_f32_16x16x32_bf16 v[14:17], v[110:113], v[180:183], v[14:17]
	v_mfma_f32_16x16x32_bf16 v[10:13], v[200:203], v[180:183], v[10:13]
	v_mfma_f32_16x16x32_bf16 v[6:9], v[102:105], v[184:187], v[6:9]
	v_mfma_f32_16x16x32_bf16 v[2:5], v[118:121], v[184:187], v[2:5]
	v_mfma_f32_16x16x32_bf16 v[152:155], v[110:113], v[172:175], v[22:25]
	v_mfma_f32_16x16x32_bf16 v[156:159], v[200:203], v[172:175], v[18:21]
	v_mfma_f32_16x16x32_bf16 v[172:175], v[110:113], v[188:191], v[6:9]
	v_mfma_f32_16x16x32_bf16 v[176:179], v[200:203], v[188:191], v[2:5]
	s_setprio 0
	s_barrier
	s_nop 1
	ds_read_b128 v[2:5], v151 offset:32768
	ds_read_b128 v[6:9], v151 offset:33792
	ds_read_b128 v[180:183], v151 offset:34816
	ds_read_b128 v[184:187], v151 offset:35840
	ds_read_b128 v[18:21], v0 offset:32768
	ds_read_b128 v[22:25], v0 offset:33792
	ds_read_b128 v[38:41], v0 offset:34816
	ds_read_b128 v[46:49], v0 offset:35840
	ds_read_b128 v[58:61], v0 offset:36864
	ds_read_b128 v[66:69], v0 offset:37888
	ds_read_b128 v[188:191], v0 offset:38912
	ds_read_b128 v[200:203], v0 offset:39936
	s_waitcnt vmcnt(2)
	s_barrier
	s_waitcnt lgkmcnt(0)
	s_setprio 1
	s_waitcnt lgkmcnt(7)
	v_mfma_f32_16x16x32_bf16 v[34:37], v[2:5], v[18:21], v[126:129]
	s_waitcnt lgkmcnt(6)
	v_mfma_f32_16x16x32_bf16 v[118:121], v[6:9], v[22:25], v[34:37]
	v_mfma_f32_16x16x32_bf16 v[34:37], v[180:183], v[18:21], v[122:125]
	v_mfma_f32_16x16x32_bf16 v[110:113], v[184:187], v[22:25], v[34:37]
	s_waitcnt lgkmcnt(5)
	v_mfma_f32_16x16x32_bf16 v[34:37], v[2:5], v[38:41], v[130:133]
	s_waitcnt lgkmcnt(4)
	v_mfma_f32_16x16x32_bf16 v[102:105], v[6:9], v[46:49], v[34:37]
	v_mfma_f32_16x16x32_bf16 v[34:37], v[180:183], v[38:41], v[114:117]
	v_mfma_f32_16x16x32_bf16 v[94:97], v[184:187], v[46:49], v[34:37]
	s_waitcnt lgkmcnt(3)
	v_mfma_f32_16x16x32_bf16 v[34:37], v[2:5], v[58:61], v[160:163]
	s_waitcnt lgkmcnt(2)
	v_mfma_f32_16x16x32_bf16 v[74:77], v[6:9], v[66:69], v[34:37]
	v_mfma_f32_16x16x32_bf16 v[34:37], v[180:183], v[58:61], v[106:109]
	v_mfma_f32_16x16x32_bf16 v[62:65], v[184:187], v[66:69], v[34:37]
	s_waitcnt lgkmcnt(1)
	v_mfma_f32_16x16x32_bf16 v[34:37], v[2:5], v[188:191], v[196:199]
	s_waitcnt lgkmcnt(0)
	v_mfma_f32_16x16x32_bf16 v[42:45], v[6:9], v[200:203], v[34:37]
	v_mfma_f32_16x16x32_bf16 v[34:37], v[180:183], v[188:191], v[98:101]
	v_mfma_f32_16x16x32_bf16 v[34:37], v[184:187], v[200:203], v[34:37]
	s_setprio 0
	s_barrier
	ds_read_b128 v[130:133], v151 offset:49152
	ds_read_b128 v[160:163], v151 offset:50176
	ds_read_b128 v[196:199], v151 offset:51200
	ds_read_b128 v[148:151], v151 offset:52224
	s_waitcnt vmcnt(0)
	s_barrier
	s_waitcnt lgkmcnt(0)
	s_setprio 1
	s_waitcnt lgkmcnt(3)
	v_mfma_f32_16x16x32_bf16 v[98:101], v[130:133], v[18:21], v[222:225]
	s_waitcnt lgkmcnt(1)
	v_mfma_f32_16x16x32_bf16 v[18:21], v[196:199], v[18:21], v[90:93]
	s_waitcnt lgkmcnt(0)
	v_mfma_f32_16x16x32_bf16 v[122:125], v[148:151], v[22:25], v[18:21]
	v_mfma_f32_16x16x32_bf16 v[18:21], v[130:133], v[38:41], v[86:89]
	v_mfma_f32_16x16x32_bf16 v[114:117], v[160:163], v[46:49], v[18:21]
	v_mfma_f32_16x16x32_bf16 v[18:21], v[196:199], v[38:41], v[82:85]
	v_mfma_f32_16x16x32_bf16 v[106:109], v[148:151], v[46:49], v[18:21]
	v_mfma_f32_16x16x32_bf16 v[18:21], v[130:133], v[58:61], v[78:81]
	v_mfma_f32_16x16x32_bf16 v[126:129], v[160:163], v[22:25], v[98:101]
	v_mfma_f32_16x16x32_bf16 v[98:101], v[160:163], v[66:69], v[18:21]
	v_mfma_f32_16x16x32_bf16 v[18:21], v[196:199], v[58:61], v[164:167]
	v_mfma_f32_16x16x32_bf16 v[90:93], v[148:151], v[66:69], v[18:21]
	v_mfma_f32_16x16x32_bf16 v[18:21], v[130:133], v[188:191], v[70:73]
	v_mfma_f32_16x16x32_bf16 v[66:69], v[160:163], v[200:203], v[18:21]
	v_mfma_f32_16x16x32_bf16 v[18:21], v[196:199], v[188:191], v[168:171]
	v_mfma_f32_16x16x32_bf16 v[58:61], v[148:151], v[200:203], v[18:21]
	s_setprio 0
	s_barrier
	ds_read_b128 v[82:85], v0 offset:49152
	ds_read_b128 v[164:167], v0 offset:50176
	ds_read_b128 v[168:171], v0 offset:51200
	ds_read_b128 v[188:191], v0 offset:52224
	ds_read_b128 v[200:203], v0 offset:53248
	ds_read_b128 v[222:225], v0 offset:54272
	ds_read_b128 v[244:247], v0 offset:55296
	ds_read_b128 v[248:251], v0 offset:56320
	s_barrier
	s_waitcnt lgkmcnt(0)
	s_setprio 1
	s_waitcnt lgkmcnt(7)
	v_mfma_f32_16x16x32_bf16 v[18:21], v[2:5], v[82:85], v[192:195]
	s_waitcnt lgkmcnt(6)
	v_mfma_f32_16x16x32_bf16 v[78:81], v[6:9], v[164:167], v[18:21]
	v_mfma_f32_16x16x32_bf16 v[18:21], v[180:183], v[82:85], v[232:235]
	v_mfma_f32_16x16x32_bf16 v[70:73], v[184:187], v[164:167], v[18:21]
	s_waitcnt lgkmcnt(5)
	v_mfma_f32_16x16x32_bf16 v[18:21], v[2:5], v[168:171], v[54:57]
	s_waitcnt lgkmcnt(4)
	v_mfma_f32_16x16x32_bf16 v[46:49], v[6:9], v[188:191], v[18:21]
	v_mfma_f32_16x16x32_bf16 v[18:21], v[180:183], v[168:171], v[50:53]
	v_mfma_f32_16x16x32_bf16 v[38:41], v[184:187], v[188:191], v[18:21]
	s_waitcnt lgkmcnt(3)
	v_mfma_f32_16x16x32_bf16 v[18:21], v[2:5], v[200:203], v[236:239]
	s_waitcnt lgkmcnt(1)
	v_mfma_f32_16x16x32_bf16 v[2:5], v[2:5], v[244:247], v[134:137]
	v_mfma_f32_16x16x32_bf16 v[22:25], v[6:9], v[222:225], v[18:21]
	v_mfma_f32_16x16x32_bf16 v[18:21], v[180:183], v[200:203], v[240:243]
	s_waitcnt lgkmcnt(0)
	v_mfma_f32_16x16x32_bf16 v[6:9], v[6:9], v[248:251], v[2:5]
	v_mfma_f32_16x16x32_bf16 v[2:5], v[180:183], v[244:247], v[138:141]
	v_mfma_f32_16x16x32_bf16 v[18:21], v[184:187], v[222:225], v[18:21]
	v_mfma_f32_16x16x32_bf16 v[2:5], v[184:187], v[248:251], v[2:5]
	s_setprio 0
	s_setprio 1
	v_mfma_f32_16x16x32_bf16 v[26:29], v[196:199], v[82:85], v[26:29]
	v_mfma_f32_16x16x32_bf16 v[30:33], v[130:133], v[82:85], v[30:33]
	v_mfma_f32_16x16x32_bf16 v[82:85], v[148:151], v[164:167], v[26:29]
	v_mfma_f32_16x16x32_bf16 v[26:29], v[130:133], v[168:171], v[152:155]
	v_mfma_f32_16x16x32_bf16 v[54:57], v[160:163], v[188:191], v[26:29]
	v_mfma_f32_16x16x32_bf16 v[26:29], v[196:199], v[168:171], v[156:159]
	v_mfma_f32_16x16x32_bf16 v[10:13], v[196:199], v[200:203], v[10:13]
	v_mfma_f32_16x16x32_bf16 v[50:53], v[148:151], v[188:191], v[26:29]
	v_mfma_f32_16x16x32_bf16 v[14:17], v[130:133], v[200:203], v[14:17]
	v_mfma_f32_16x16x32_bf16 v[26:29], v[148:151], v[222:225], v[10:13]
	v_mfma_f32_16x16x32_bf16 v[10:13], v[130:133], v[244:247], v[172:175]
	v_mfma_f32_16x16x32_bf16 v[86:89], v[160:163], v[164:167], v[30:33]
	v_mfma_f32_16x16x32_bf16 v[30:33], v[160:163], v[222:225], v[14:17]
	v_mfma_f32_16x16x32_bf16 v[14:17], v[160:163], v[248:251], v[10:13]
	v_mfma_f32_16x16x32_bf16 v[10:13], v[196:199], v[244:247], v[176:179]
	v_mfma_f32_16x16x32_bf16 v[10:13], v[148:151], v[248:251], v[10:13]
	s_setprio 0
	s_movk_i32 s0, 0x100
	v_cmp_gt_u32_e32 vcc, s0, v142
	s_barrier
	s_and_saveexec_b64 s[0:1], vcc
	s_cbranch_execz .LBB0_674
	s_barrier
	s_branch .LBB0_674

.LBB0_760:
	s_or_b64 exec, exec, s[14:15]
	v_mov_b32_e32 v131, v1
	v_add_u32_e32 v155, 0x18000, v145
	v_lshl_add_u64 v[10:11], s[0:1], 0, v[0:1]
	v_lshl_add_u64 v[12:13], s[0:1], 0, v[130:131]
	v_lshl_add_u64 v[18:19], s[12:13], 0, v[0:1]
	v_lshl_add_u64 v[20:21], s[12:13], 0, v[130:131]
	s_mov_b64 s[12:13], 0x80
	v_readfirstlane_b32 s0, v155
	v_add_u32_e32 v156, 0x1a000, v145
	v_lshl_add_u64 v[10:11], v[10:11], 0, s[12:13]
	s_mov_b32 m0, s0
	v_readfirstlane_b32 s0, v156
	v_add_u32_e32 v157, 0x8000, v145
	v_lshl_add_u64 v[14:15], s[8:9], 0, v[0:1]
	s_waitcnt vmcnt(4)
	s_barrier
	global_load_lds_dwordx4 v[10:11], off
	v_lshl_add_u64 v[10:11], v[12:13], 0, s[12:13]
	s_mov_b32 m0, s0
	v_readfirstlane_b32 s0, v157
	v_add_u32_e32 v158, 0xa000, v145
	v_lshl_add_u64 v[16:17], s[8:9], 0, v[130:131]
	global_load_lds_dwordx4 v[10:11], off
	v_lshl_add_u64 v[10:11], v[14:15], 0, s[12:13]
	s_mov_b32 m0, s0
	v_readfirstlane_b32 s0, v158
	v_add_u32_e32 v159, 0x1c000, v145
	global_load_lds_dwordx4 v[10:11], off
	v_lshl_add_u64 v[10:11], v[16:17], 0, s[12:13]
	s_mov_b32 m0, s0
	v_readfirstlane_b32 s0, v159
	v_add_u32_e32 v160, 0x1e000, v145
	global_load_lds_dwordx4 v[10:11], off
	v_lshl_add_u64 v[10:11], v[18:19], 0, s[12:13]
	s_mov_b32 m0, s0
	v_readfirstlane_b32 s0, v160
	global_load_lds_dwordx4 v[10:11], off
	v_lshl_add_u64 v[10:11], v[20:21], 0, s[12:13]
	s_mov_b32 m0, s0
	s_movk_i32 s13, 0x1600
	global_load_lds_dwordx4 v[10:11], off
	v_lshrrev_b32_e32 v10, 1, v2
	v_mul_lo_u32 v2, v4, s13
	s_mov_b32 s12, 0x16000
	v_mad_u64_u32 v[10:11], s[0:1], v10, s12, v[2:3]
	v_or_b32_e32 v2, v10, v3
	v_add_lshl_u32 v2, v2, v5, 1
	v_lshrrev_b32_e32 v5, 1, v6
	v_mul_lo_u32 v4, v8, s13
	v_mad_u64_u32 v[4:5], s[12:13], v5, s12, v[4:5]
	s_add_u32 s0, s16, s57
	v_or_b32_e32 v4, v4, v7
	v_mov_b32_e32 v3, v1
	s_addc_u32 s1, s17, s54
	v_add_lshl_u32 v4, v4, v9, 1
	v_mov_b32_e32 v5, v1
	v_and_b32_e32 v144, 15, v140
	v_bfe_u32 v143, v140, 4, 2
	v_lshlrev_b32_e32 v24, 2, v140
	v_lshl_add_u64 v[132:133], s[0:1], 0, v[2:3]
	v_lshl_add_u64 v[134:135], s[0:1], 0, v[4:5]
	s_add_u32 s0, s20, s10
	v_bfe_u32 v142, v140, 6, 2
	v_lshlrev_b32_e32 v22, 6, v144
	v_lshlrev_b32_e32 v23, 4, v143
	v_and_b32_e32 v24, 32, v24
	s_waitcnt vmcnt(6)
	s_addc_u32 s1, s21, s11
	v_bitop3_b32 v22, v23, v24, v22 bitop3:0x36
	v_lshlrev_b32_e32 v23, 13, v141
	v_lshl_or_b32 v24, v142, 12, v212
	v_lshl_add_u64 v[136:137], s[0:1], 0, v[2:3]
	v_mov_b32_e32 v2, 0
	v_lshl_add_u64 v[138:139], s[0:1], 0, v[4:5]
	s_mov_b32 s0, -2
	s_mov_b64 s[10:11], 0
	v_add_u32_e32 v148, v24, v22
	v_add_u32_e32 v147, v23, v22
	v_mov_b32_e32 v3, v2
	v_mov_b32_e32 v4, v2
	v_mov_b32_e32 v5, v2
	v_mov_b32_e32 v6, v2
	v_mov_b32_e32 v7, v2
	v_mov_b32_e32 v8, v2
	v_mov_b32_e32 v9, v2
	v_mov_b32_e32 v10, v2
	v_mov_b32_e32 v11, v2
	v_mov_b32_e32 v12, v2
	v_mov_b32_e32 v13, v2
	v_mov_b32_e32 v14, v2
	v_mov_b32_e32 v15, v2
	v_mov_b32_e32 v16, v2
	v_mov_b32_e32 v17, v2
	v_mov_b32_e32 v18, v2
	v_mov_b32_e32 v19, v2
	v_mov_b32_e32 v20, v2
	v_mov_b32_e32 v21, v2
	v_mov_b32_e32 v22, v2
	v_mov_b32_e32 v23, v2
	v_mov_b32_e32 v24, v2
	v_mov_b32_e32 v25, v2
	v_mov_b32_e32 v26, v2
	v_mov_b32_e32 v27, v2
	v_mov_b32_e32 v28, v2
	v_mov_b32_e32 v29, v2
	v_mov_b32_e32 v30, v2
	v_mov_b32_e32 v31, v2
	v_mov_b32_e32 v32, v2
	v_mov_b32_e32 v33, v2
	v_mov_b32_e32 v34, v2
	v_mov_b32_e32 v35, v2
	v_mov_b32_e32 v36, v2
	v_mov_b32_e32 v37, v2
	v_mov_b32_e32 v38, v2
	v_mov_b32_e32 v39, v2
	v_mov_b32_e32 v40, v2
	v_mov_b32_e32 v41, v2
	v_mov_b32_e32 v42, v2
	v_mov_b32_e32 v43, v2
	v_mov_b32_e32 v44, v2
	v_mov_b32_e32 v45, v2
	v_mov_b32_e32 v46, v2
	v_mov_b32_e32 v47, v2
	v_mov_b32_e32 v48, v2
	v_mov_b32_e32 v49, v2
	v_mov_b32_e32 v50, v2
	v_mov_b32_e32 v51, v2
	v_mov_b32_e32 v52, v2
	v_mov_b32_e32 v53, v2
	v_mov_b32_e32 v54, v2
	v_mov_b32_e32 v55, v2
	v_mov_b32_e32 v56, v2
	v_mov_b32_e32 v57, v2
	v_mov_b32_e32 v58, v2
	v_mov_b32_e32 v59, v2
	v_mov_b32_e32 v60, v2
	v_mov_b32_e32 v61, v2
	v_mov_b32_e32 v62, v2
	v_mov_b32_e32 v63, v2
	v_mov_b32_e32 v64, v2
	v_mov_b32_e32 v65, v2
	v_mov_b32_e32 v66, v2
	v_mov_b32_e32 v67, v2
	v_mov_b32_e32 v68, v2
	v_mov_b32_e32 v69, v2
	v_mov_b32_e32 v70, v2
	v_mov_b32_e32 v71, v2
	v_mov_b32_e32 v72, v2
	v_mov_b32_e32 v73, v2
	v_mov_b32_e32 v74, v2
	v_mov_b32_e32 v75, v2
	v_mov_b32_e32 v76, v2
	v_mov_b32_e32 v77, v2
	v_mov_b32_e32 v78, v2
	v_mov_b32_e32 v79, v2
	v_mov_b32_e32 v80, v2
	v_mov_b32_e32 v81, v2
	v_mov_b32_e32 v82, v2
	v_mov_b32_e32 v83, v2
	v_mov_b32_e32 v84, v2
	v_mov_b32_e32 v85, v2
	v_mov_b32_e32 v86, v2
	v_mov_b32_e32 v87, v2
	v_mov_b32_e32 v88, v2
	v_mov_b32_e32 v89, v2
	v_mov_b32_e32 v90, v2
	v_mov_b32_e32 v91, v2
	v_mov_b32_e32 v92, v2
	v_mov_b32_e32 v93, v2
	v_mov_b32_e32 v94, v2
	v_mov_b32_e32 v95, v2
	v_mov_b32_e32 v96, v2
	v_mov_b32_e32 v97, v2
	v_mov_b32_e32 v98, v2
	v_mov_b32_e32 v99, v2
	v_mov_b32_e32 v100, v2
	v_mov_b32_e32 v101, v2
	v_mov_b32_e32 v102, v2
	v_mov_b32_e32 v103, v2
	v_mov_b32_e32 v104, v2
	v_mov_b32_e32 v105, v2
	v_mov_b32_e32 v106, v2
	v_mov_b32_e32 v107, v2
	v_mov_b32_e32 v108, v2
	v_mov_b32_e32 v109, v2
	v_mov_b32_e32 v110, v2
	v_mov_b32_e32 v111, v2
	v_mov_b32_e32 v112, v2
	v_mov_b32_e32 v113, v2
	v_mov_b32_e32 v114, v2
	v_mov_b32_e32 v115, v2
	v_mov_b32_e32 v116, v2
	v_mov_b32_e32 v117, v2
	v_mov_b32_e32 v118, v2
	v_mov_b32_e32 v119, v2
	v_mov_b32_e32 v120, v2
	v_mov_b32_e32 v121, v2
	v_mov_b32_e32 v122, v2
	v_mov_b32_e32 v123, v2
	v_mov_b32_e32 v124, v2
	v_mov_b32_e32 v125, v2
	v_mov_b32_e32 v126, v2
	v_mov_b32_e32 v127, v2
	v_mov_b32_e32 v128, v2
	v_mov_b32_e32 v129, v2
	s_barrier
	v_add_u32_e32 v161, 0xc000, v145
	v_add_u32_e32 v162, 0xe000, v145
	v_readfirstlane_b32 s1, v145
	s_nop 1
.LBB0_761:
	ds_read_b128 v[164:167], v148
	ds_read_b128 v[168:171], v148 offset:1024
	ds_read_b128 v[172:175], v148 offset:2048
	ds_read_b128 v[176:179], v148 offset:3072
	v_lshl_add_u64 v[204:205], v[136:137], 0, s[10:11]
	v_lshl_add_u64 v[228:229], v[204:205], 0, s[34:35]
	s_add_i32 m0, s1, 0xc000
	ds_read_b128 v[180:183], v147
	ds_read_b128 v[184:187], v147 offset:1024
	ds_read_b128 v[188:191], v147 offset:2048
	ds_read_b128 v[192:195], v147 offset:3072
	ds_read_b128 v[196:199], v147 offset:4096
	ds_read_b128 v[200:203], v147 offset:5120
	ds_read_b128 v[222:225], v147 offset:6144
	ds_read_b128 v[232:235], v147 offset:7168
	global_load_lds_dwordx4 v[228:229], off
	v_lshl_add_u64 v[210:211], v[138:139], 0, s[10:11]
	s_add_i32 m0, s1, 0xe000
	v_lshl_add_u64 v[152:153], v[210:211], 0, s[34:35]
	global_load_lds_dwordx4 v[152:153], off
	s_waitcnt lgkmcnt(8)
	s_barrier
	s_waitcnt lgkmcnt(0)
	s_setprio 1
	v_mfma_f32_16x16x32_bf16 v[126:129], v[164:167], v[180:183], v[126:129]
	v_mfma_f32_16x16x32_bf16 v[122:125], v[172:175], v[180:183], v[122:125]
	v_mfma_f32_16x16x32_bf16 v[118:121], v[164:167], v[188:191], v[118:121]
	v_mfma_f32_16x16x32_bf16 v[114:117], v[172:175], v[188:191], v[114:117]
	v_mfma_f32_16x16x32_bf16 v[110:113], v[164:167], v[196:199], v[110:113]
	v_mfma_f32_16x16x32_bf16 v[106:109], v[172:175], v[196:199], v[106:109]
	v_mfma_f32_16x16x32_bf16 v[102:105], v[164:167], v[222:225], v[102:105]
	v_mfma_f32_16x16x32_bf16 v[98:101], v[172:175], v[222:225], v[98:101]
	v_mfma_f32_16x16x32_bf16 v[126:129], v[168:171], v[184:187], v[126:129]
	v_mfma_f32_16x16x32_bf16 v[122:125], v[176:179], v[184:187], v[122:125]
	v_mfma_f32_16x16x32_bf16 v[118:121], v[168:171], v[192:195], v[118:121]
	v_mfma_f32_16x16x32_bf16 v[114:117], v[176:179], v[192:195], v[114:117]
	v_mfma_f32_16x16x32_bf16 v[110:113], v[168:171], v[200:203], v[110:113]
	v_mfma_f32_16x16x32_bf16 v[106:109], v[176:179], v[200:203], v[106:109]
	v_mfma_f32_16x16x32_bf16 v[102:105], v[168:171], v[232:235], v[102:105]
	v_mfma_f32_16x16x32_bf16 v[98:101], v[176:179], v[232:235], v[98:101]
	s_setprio 0
	s_barrier
	v_lshl_add_u64 v[216:217], v[132:133], 0, s[10:11]
	s_add_i32 m0, s1, 0xff00
	ds_read_b128 v[236:239], v148 offset:16384
	ds_read_b128 v[240:243], v148 offset:17408
	ds_read_b128 v[244:247], v148 offset:18432
	ds_read_b128 v[248:251], v148 offset:19456
	global_load_lds_dwordx4 v[216:217], off offset:256
	s_add_i32 m0, s1, 0x11f00
	v_lshl_add_u64 v[218:219], v[134:135], 0, s[10:11]
	global_load_lds_dwordx4 v[218:219], off offset:256
	s_barrier
	s_waitcnt lgkmcnt(0)
	s_setprio 1
	v_mfma_f32_16x16x32_bf16 v[94:97], v[236:239], v[180:183], v[94:97]
	v_mfma_f32_16x16x32_bf16 v[90:93], v[244:247], v[180:183], v[90:93]
	v_mfma_f32_16x16x32_bf16 v[86:89], v[236:239], v[188:191], v[86:89]
	v_mfma_f32_16x16x32_bf16 v[82:85], v[244:247], v[188:191], v[82:85]
	v_mfma_f32_16x16x32_bf16 v[78:81], v[236:239], v[196:199], v[78:81]
	v_mfma_f32_16x16x32_bf16 v[74:77], v[244:247], v[196:199], v[74:77]
	v_mfma_f32_16x16x32_bf16 v[70:73], v[236:239], v[222:225], v[70:73]
	v_mfma_f32_16x16x32_bf16 v[66:69], v[244:247], v[222:225], v[66:69]
	v_mfma_f32_16x16x32_bf16 v[94:97], v[240:243], v[184:187], v[94:97]
	v_mfma_f32_16x16x32_bf16 v[90:93], v[248:251], v[184:187], v[90:93]
	v_mfma_f32_16x16x32_bf16 v[86:89], v[240:243], v[192:195], v[86:89]
	v_mfma_f32_16x16x32_bf16 v[82:85], v[248:251], v[192:195], v[82:85]
	v_mfma_f32_16x16x32_bf16 v[78:81], v[240:243], v[200:203], v[78:81]
	v_mfma_f32_16x16x32_bf16 v[74:77], v[248:251], v[200:203], v[74:77]
	v_mfma_f32_16x16x32_bf16 v[70:73], v[240:243], v[232:235], v[70:73]
	v_mfma_f32_16x16x32_bf16 v[66:69], v[248:251], v[232:235], v[66:69]
	s_setprio 0
	v_lshl_add_u64 v[158:159], v[204:205], 0, s[74:75]
	s_mov_b32 m0, s1
	s_barrier
	ds_read_b128 v[180:183], v147 offset:16384
	ds_read_b128 v[184:187], v147 offset:17408
	ds_read_b128 v[188:191], v147 offset:18432
	ds_read_b128 v[192:195], v147 offset:19456
	ds_read_b128 v[196:199], v147 offset:20480
	ds_read_b128 v[200:203], v147 offset:21504
	ds_read_b128 v[222:225], v147 offset:22528
	ds_read_b128 v[232:235], v147 offset:23552
	global_load_lds_dwordx4 v[158:159], off
	s_add_i32 m0, s1, 0x1f00
	s_nop 0
	global_load_lds_dwordx4 v[210:211], off offset:256
	s_barrier
	s_waitcnt lgkmcnt(0)
	s_setprio 1
	v_mfma_f32_16x16x32_bf16 v[62:65], v[164:167], v[180:183], v[62:65]
	v_mfma_f32_16x16x32_bf16 v[58:61], v[172:175], v[180:183], v[58:61]
	v_mfma_f32_16x16x32_bf16 v[54:57], v[164:167], v[188:191], v[54:57]
	v_mfma_f32_16x16x32_bf16 v[50:53], v[172:175], v[188:191], v[50:53]
	v_mfma_f32_16x16x32_bf16 v[46:49], v[164:167], v[196:199], v[46:49]
	v_mfma_f32_16x16x32_bf16 v[42:45], v[172:175], v[196:199], v[42:45]
	v_mfma_f32_16x16x32_bf16 v[38:41], v[164:167], v[222:225], v[38:41]
	v_mfma_f32_16x16x32_bf16 v[34:37], v[172:175], v[222:225], v[34:37]
	v_mfma_f32_16x16x32_bf16 v[62:65], v[168:171], v[184:187], v[62:65]
	v_mfma_f32_16x16x32_bf16 v[58:61], v[176:179], v[184:187], v[58:61]
	v_mfma_f32_16x16x32_bf16 v[54:57], v[168:171], v[192:195], v[54:57]
	v_mfma_f32_16x16x32_bf16 v[50:53], v[176:179], v[192:195], v[50:53]
	v_mfma_f32_16x16x32_bf16 v[46:49], v[168:171], v[200:203], v[46:49]
	v_mfma_f32_16x16x32_bf16 v[42:45], v[176:179], v[200:203], v[42:45]
	v_mfma_f32_16x16x32_bf16 v[38:41], v[168:171], v[232:235], v[38:41]
	v_mfma_f32_16x16x32_bf16 v[34:37], v[176:179], v[232:235], v[34:37]
	s_setprio 0
	s_barrier
	s_add_i32 m0, s1, 0x14000
	v_lshl_add_u64 v[154:155], v[216:217], 0, s[78:79]
	global_load_lds_dwordx4 v[154:155], off
	s_add_i32 m0, s1, 0x16000
	v_lshl_add_u64 v[156:157], v[218:219], 0, s[78:79]
	global_load_lds_dwordx4 v[156:157], off
	s_waitcnt vmcnt(6)
	s_barrier
	s_setprio 1
	v_mfma_f32_16x16x32_bf16 v[30:33], v[236:239], v[180:183], v[30:33]
	v_mfma_f32_16x16x32_bf16 v[26:29], v[244:247], v[180:183], v[26:29]
	v_mfma_f32_16x16x32_bf16 v[22:25], v[236:239], v[188:191], v[22:25]
	v_mfma_f32_16x16x32_bf16 v[18:21], v[244:247], v[188:191], v[18:21]
	v_mfma_f32_16x16x32_bf16 v[14:17], v[236:239], v[196:199], v[14:17]
	v_mfma_f32_16x16x32_bf16 v[10:13], v[244:247], v[196:199], v[10:13]
	v_mfma_f32_16x16x32_bf16 v[6:9], v[236:239], v[222:225], v[6:9]
	v_mfma_f32_16x16x32_bf16 v[2:5], v[244:247], v[222:225], v[2:5]
	v_mfma_f32_16x16x32_bf16 v[30:33], v[240:243], v[184:187], v[30:33]
	v_mfma_f32_16x16x32_bf16 v[26:29], v[248:251], v[184:187], v[26:29]
	v_mfma_f32_16x16x32_bf16 v[22:25], v[240:243], v[192:195], v[22:25]
	v_mfma_f32_16x16x32_bf16 v[18:21], v[248:251], v[192:195], v[18:21]
	v_mfma_f32_16x16x32_bf16 v[14:17], v[240:243], v[200:203], v[14:17]
	v_mfma_f32_16x16x32_bf16 v[10:13], v[248:251], v[200:203], v[10:13]
	v_mfma_f32_16x16x32_bf16 v[6:9], v[240:243], v[232:235], v[6:9]
	v_mfma_f32_16x16x32_bf16 v[2:5], v[248:251], v[232:235], v[2:5]
	s_setprio 0
	s_barrier
	ds_read_b128 v[164:167], v148 offset:32768
	ds_read_b128 v[168:171], v148 offset:33792
	ds_read_b128 v[172:175], v148 offset:34816
	ds_read_b128 v[176:179], v148 offset:35840
	s_add_i32 m0, s1, 0x3f80
	ds_read_b128 v[180:183], v147 offset:32768
	ds_read_b128 v[184:187], v147 offset:33792
	ds_read_b128 v[188:191], v147 offset:34816
	ds_read_b128 v[192:195], v147 offset:35840
	ds_read_b128 v[196:199], v147 offset:36864
	ds_read_b128 v[200:203], v147 offset:37888
	ds_read_b128 v[222:225], v147 offset:38912
	ds_read_b128 v[232:235], v147 offset:39936
	global_load_lds_dwordx4 v[228:229], off offset:128
	s_add_i32 m0, s1, 0x5f80
	s_nop 0
	global_load_lds_dwordx4 v[152:153], off offset:128
	s_waitcnt lgkmcnt(8)
	s_barrier
	s_waitcnt lgkmcnt(0)
	s_setprio 1
	v_mfma_f32_16x16x32_bf16 v[126:129], v[164:167], v[180:183], v[126:129]
	v_mfma_f32_16x16x32_bf16 v[122:125], v[172:175], v[180:183], v[122:125]
	v_mfma_f32_16x16x32_bf16 v[118:121], v[164:167], v[188:191], v[118:121]
	v_mfma_f32_16x16x32_bf16 v[114:117], v[172:175], v[188:191], v[114:117]
	v_mfma_f32_16x16x32_bf16 v[110:113], v[164:167], v[196:199], v[110:113]
	v_mfma_f32_16x16x32_bf16 v[106:109], v[172:175], v[196:199], v[106:109]
	v_mfma_f32_16x16x32_bf16 v[102:105], v[164:167], v[222:225], v[102:105]
	v_mfma_f32_16x16x32_bf16 v[98:101], v[172:175], v[222:225], v[98:101]
	v_mfma_f32_16x16x32_bf16 v[126:129], v[168:171], v[184:187], v[126:129]
	v_mfma_f32_16x16x32_bf16 v[122:125], v[176:179], v[184:187], v[122:125]
	v_mfma_f32_16x16x32_bf16 v[118:121], v[168:171], v[192:195], v[118:121]
	v_mfma_f32_16x16x32_bf16 v[114:117], v[176:179], v[192:195], v[114:117]
	v_mfma_f32_16x16x32_bf16 v[110:113], v[168:171], v[200:203], v[110:113]
	v_mfma_f32_16x16x32_bf16 v[106:109], v[176:179], v[200:203], v[106:109]
	v_mfma_f32_16x16x32_bf16 v[102:105], v[168:171], v[232:235], v[102:105]
	v_mfma_f32_16x16x32_bf16 v[98:101], v[176:179], v[232:235], v[98:101]
	s_setprio 0
	s_barrier
	s_add_i32 m0, s1, 0x17e80
	ds_read_b128 v[236:239], v148 offset:49152
	ds_read_b128 v[240:243], v148 offset:50176
	ds_read_b128 v[244:247], v148 offset:51200
	ds_read_b128 v[248:251], v148 offset:52224
	global_load_lds_dwordx4 v[216:217], off offset:384
	s_add_i32 m0, s1, 0x19e80
	s_nop 0
	global_load_lds_dwordx4 v[218:219], off offset:384
	s_barrier
	s_waitcnt lgkmcnt(0)
	s_setprio 1
	v_mfma_f32_16x16x32_bf16 v[94:97], v[236:239], v[180:183], v[94:97]
	v_mfma_f32_16x16x32_bf16 v[90:93], v[244:247], v[180:183], v[90:93]
	v_mfma_f32_16x16x32_bf16 v[86:89], v[236:239], v[188:191], v[86:89]
	v_mfma_f32_16x16x32_bf16 v[82:85], v[244:247], v[188:191], v[82:85]
	v_mfma_f32_16x16x32_bf16 v[78:81], v[236:239], v[196:199], v[78:81]
	v_mfma_f32_16x16x32_bf16 v[74:77], v[244:247], v[196:199], v[74:77]
	v_mfma_f32_16x16x32_bf16 v[70:73], v[236:239], v[222:225], v[70:73]
	v_mfma_f32_16x16x32_bf16 v[66:69], v[244:247], v[222:225], v[66:69]
	v_mfma_f32_16x16x32_bf16 v[94:97], v[240:243], v[184:187], v[94:97]
	v_mfma_f32_16x16x32_bf16 v[90:93], v[248:251], v[184:187], v[90:93]
	v_mfma_f32_16x16x32_bf16 v[86:89], v[240:243], v[192:195], v[86:89]
	v_mfma_f32_16x16x32_bf16 v[82:85], v[248:251], v[192:195], v[82:85]
	v_mfma_f32_16x16x32_bf16 v[78:81], v[240:243], v[200:203], v[78:81]
	v_mfma_f32_16x16x32_bf16 v[74:77], v[248:251], v[200:203], v[74:77]
	v_mfma_f32_16x16x32_bf16 v[70:73], v[240:243], v[232:235], v[70:73]
	v_mfma_f32_16x16x32_bf16 v[66:69], v[248:251], v[232:235], v[66:69]
	s_setprio 0
	s_add_i32 m0, s1, 0x7e80
	s_barrier
	ds_read_b128 v[180:183], v147 offset:49152
	ds_read_b128 v[184:187], v147 offset:50176
	ds_read_b128 v[188:191], v147 offset:51200
	ds_read_b128 v[192:195], v147 offset:52224
	ds_read_b128 v[196:199], v147 offset:53248
	ds_read_b128 v[200:203], v147 offset:54272
	ds_read_b128 v[222:225], v147 offset:55296
	ds_read_b128 v[232:235], v147 offset:56320
	global_load_lds_dwordx4 v[204:205], off offset:384
	s_add_i32 m0, s1, 0x9e80
	s_nop 0
	global_load_lds_dwordx4 v[210:211], off offset:384
	s_barrier
	s_waitcnt lgkmcnt(0)
	s_setprio 1
	v_mfma_f32_16x16x32_bf16 v[62:65], v[164:167], v[180:183], v[62:65]
	v_mfma_f32_16x16x32_bf16 v[58:61], v[172:175], v[180:183], v[58:61]
	v_mfma_f32_16x16x32_bf16 v[54:57], v[164:167], v[188:191], v[54:57]
	v_mfma_f32_16x16x32_bf16 v[50:53], v[172:175], v[188:191], v[50:53]
	v_mfma_f32_16x16x32_bf16 v[46:49], v[164:167], v[196:199], v[46:49]
	v_mfma_f32_16x16x32_bf16 v[42:45], v[172:175], v[196:199], v[42:45]
	v_mfma_f32_16x16x32_bf16 v[38:41], v[164:167], v[222:225], v[38:41]
	v_mfma_f32_16x16x32_bf16 v[34:37], v[172:175], v[222:225], v[34:37]
	v_mfma_f32_16x16x32_bf16 v[62:65], v[168:171], v[184:187], v[62:65]
	v_mfma_f32_16x16x32_bf16 v[58:61], v[176:179], v[184:187], v[58:61]
	v_mfma_f32_16x16x32_bf16 v[54:57], v[168:171], v[192:195], v[54:57]
	v_mfma_f32_16x16x32_bf16 v[50:53], v[176:179], v[192:195], v[50:53]
	v_mfma_f32_16x16x32_bf16 v[46:49], v[168:171], v[200:203], v[46:49]
	v_mfma_f32_16x16x32_bf16 v[42:45], v[176:179], v[200:203], v[42:45]
	v_mfma_f32_16x16x32_bf16 v[38:41], v[168:171], v[232:235], v[38:41]
	v_mfma_f32_16x16x32_bf16 v[34:37], v[176:179], v[232:235], v[34:37]
	s_setprio 0
	s_barrier
	s_add_i32 m0, s1, 0x1bf80
	s_nop 0
	global_load_lds_dwordx4 v[154:155], off offset:128
	s_add_i32 m0, s1, 0x1df80
	s_nop 0
	global_load_lds_dwordx4 v[156:157], off offset:128
	s_waitcnt vmcnt(6)
	s_barrier
	s_setprio 1
	v_mfma_f32_16x16x32_bf16 v[30:33], v[236:239], v[180:183], v[30:33]
	v_mfma_f32_16x16x32_bf16 v[26:29], v[244:247], v[180:183], v[26:29]
	v_mfma_f32_16x16x32_bf16 v[22:25], v[236:239], v[188:191], v[22:25]
	v_mfma_f32_16x16x32_bf16 v[18:21], v[244:247], v[188:191], v[18:21]
	v_mfma_f32_16x16x32_bf16 v[14:17], v[236:239], v[196:199], v[14:17]
	v_mfma_f32_16x16x32_bf16 v[10:13], v[244:247], v[196:199], v[10:13]
	v_mfma_f32_16x16x32_bf16 v[6:9], v[236:239], v[222:225], v[6:9]
	v_mfma_f32_16x16x32_bf16 v[2:5], v[244:247], v[222:225], v[2:5]
	v_mfma_f32_16x16x32_bf16 v[30:33], v[240:243], v[184:187], v[30:33]
	v_mfma_f32_16x16x32_bf16 v[26:29], v[248:251], v[184:187], v[26:29]
	v_mfma_f32_16x16x32_bf16 v[22:25], v[240:243], v[192:195], v[22:25]
	v_mfma_f32_16x16x32_bf16 v[18:21], v[248:251], v[192:195], v[18:21]
	v_mfma_f32_16x16x32_bf16 v[14:17], v[240:243], v[200:203], v[14:17]
	v_mfma_f32_16x16x32_bf16 v[10:13], v[248:251], v[200:203], v[10:13]
	v_mfma_f32_16x16x32_bf16 v[6:9], v[240:243], v[232:235], v[6:9]
	v_mfma_f32_16x16x32_bf16 v[2:5], v[248:251], v[232:235], v[2:5]
	s_setprio 0
	s_add_i32 s0, s0, 2
	s_add_u32 s10, s10, 0x100
	s_addc_u32 s11, s11, 0
	s_cmpk_lt_u32 s0, 0x54
	s_barrier
	s_cbranch_scc1 .LBB0_761
	s_add_i32 s1, s1, 0x1e000
	s_add_u32 s0, s8, 0x162b80
	s_addc_u32 s1, s9, 0
	v_readfirstlane_b32 s8, v161
	v_lshl_add_u64 v[158:159], s[0:1], 0, v[0:1]
	s_mov_b32 m0, s8
	v_lshl_add_u64 v[130:131], s[0:1], 0, v[130:131]
	v_readfirstlane_b32 s0, v162
	ds_read_b128 v[132:135], v148
	ds_read_b128 v[136:139], v148 offset:1024
	ds_read_b128 v[150:153], v148 offset:2048
	ds_read_b128 v[154:157], v148 offset:3072
	ds_read_b128 v[164:167], v147
	ds_read_b128 v[168:171], v147 offset:1024
	ds_read_b128 v[172:175], v147 offset:2048
	ds_read_b128 v[176:179], v147 offset:3072
	ds_read_b128 v[180:183], v147 offset:4096
	ds_read_b128 v[184:187], v147 offset:5120
	ds_read_b128 v[188:191], v147 offset:6144
	ds_read_b128 v[192:195], v147 offset:7168
	global_load_lds_dwordx4 v[158:159], off
	s_mov_b32 m0, s0
	s_nop 0
	global_load_lds_dwordx4 v[130:131], off
	s_barrier
	s_waitcnt lgkmcnt(0)
	s_setprio 1
	s_waitcnt lgkmcnt(0)
	v_mfma_f32_16x16x32_bf16 v[122:125], v[150:153], v[164:167], v[122:125]
	v_mfma_f32_16x16x32_bf16 v[118:121], v[132:135], v[172:175], v[118:121]
	v_mfma_f32_16x16x32_bf16 v[114:117], v[150:153], v[172:175], v[114:117]
	v_mfma_f32_16x16x32_bf16 v[102:105], v[132:135], v[188:191], v[102:105]
	v_mfma_f32_16x16x32_bf16 v[98:101], v[150:153], v[188:191], v[98:101]
	v_mfma_f32_16x16x32_bf16 v[126:129], v[132:135], v[164:167], v[126:129]
	v_mfma_f32_16x16x32_bf16 v[122:125], v[154:157], v[168:171], v[122:125]
	v_mfma_f32_16x16x32_bf16 v[118:121], v[136:139], v[176:179], v[118:121]
	v_mfma_f32_16x16x32_bf16 v[114:117], v[154:157], v[176:179], v[114:117]
	v_mfma_f32_16x16x32_bf16 v[110:113], v[132:135], v[180:183], v[110:113]
	v_mfma_f32_16x16x32_bf16 v[106:109], v[150:153], v[180:183], v[106:109]
	v_mfma_f32_16x16x32_bf16 v[102:105], v[136:139], v[192:195], v[102:105]
	v_mfma_f32_16x16x32_bf16 v[98:101], v[154:157], v[192:195], v[98:101]
	v_mfma_f32_16x16x32_bf16 v[126:129], v[136:139], v[168:171], v[126:129]
	v_mfma_f32_16x16x32_bf16 v[158:161], v[136:139], v[184:187], v[110:113]
	v_mfma_f32_16x16x32_bf16 v[196:199], v[154:157], v[184:187], v[106:109]
	s_setprio 0
	s_barrier
	ds_read_b128 v[106:109], v148 offset:16384
	ds_read_b128 v[110:113], v148 offset:17408
	ds_read_b128 v[200:203], v148 offset:18432
	ds_read_b128 v[222:225], v148 offset:19456
	s_barrier
	s_waitcnt lgkmcnt(0)
	s_setprio 1
	s_waitcnt lgkmcnt(3)
	v_mfma_f32_16x16x32_bf16 v[86:89], v[106:109], v[172:175], v[86:89]
	s_waitcnt lgkmcnt(1)
	v_mfma_f32_16x16x32_bf16 v[82:85], v[200:203], v[172:175], v[82:85]
	v_mfma_f32_16x16x32_bf16 v[70:73], v[106:109], v[188:191], v[70:73]
	v_mfma_f32_16x16x32_bf16 v[66:69], v[200:203], v[188:191], v[66:69]
	v_mfma_f32_16x16x32_bf16 v[94:97], v[106:109], v[164:167], v[94:97]
	v_mfma_f32_16x16x32_bf16 v[90:93], v[200:203], v[164:167], v[90:93]
	v_mfma_f32_16x16x32_bf16 v[86:89], v[110:113], v[176:179], v[86:89]
	s_waitcnt lgkmcnt(0)
	v_mfma_f32_16x16x32_bf16 v[82:85], v[222:225], v[176:179], v[82:85]
	v_mfma_f32_16x16x32_bf16 v[78:81], v[106:109], v[180:183], v[78:81]
	v_mfma_f32_16x16x32_bf16 v[74:77], v[200:203], v[180:183], v[74:77]
	v_mfma_f32_16x16x32_bf16 v[70:73], v[110:113], v[192:195], v[70:73]
	v_mfma_f32_16x16x32_bf16 v[66:69], v[222:225], v[192:195], v[66:69]
	v_mfma_f32_16x16x32_bf16 v[232:235], v[110:113], v[168:171], v[94:97]
	v_mfma_f32_16x16x32_bf16 v[162:165], v[222:225], v[168:171], v[90:93]
	v_mfma_f32_16x16x32_bf16 v[166:169], v[110:113], v[184:187], v[78:81]
	v_mfma_f32_16x16x32_bf16 v[170:173], v[222:225], v[184:187], v[74:77]
	s_setprio 0
	s_barrier
	s_nop 0
	ds_read_b128 v[74:77], v147 offset:16384
	ds_read_b128 v[78:81], v147 offset:17408
	ds_read_b128 v[90:93], v147 offset:18432
	ds_read_b128 v[94:97], v147 offset:19456
	ds_read_b128 v[174:177], v147 offset:20480
	ds_read_b128 v[178:181], v147 offset:21504
	ds_read_b128 v[182:185], v147 offset:22528
	ds_read_b128 v[186:189], v147 offset:23552
	s_waitcnt vmcnt(4)
	s_barrier
	s_waitcnt lgkmcnt(0)
	s_setprio 1
	s_waitcnt lgkmcnt(7)
	v_mfma_f32_16x16x32_bf16 v[62:65], v[132:135], v[74:77], v[62:65]
	v_mfma_f32_16x16x32_bf16 v[58:61], v[150:153], v[74:77], v[58:61]
	s_waitcnt lgkmcnt(5)
	v_mfma_f32_16x16x32_bf16 v[54:57], v[132:135], v[90:93], v[54:57]
	v_mfma_f32_16x16x32_bf16 v[50:53], v[150:153], v[90:93], v[50:53]
	s_waitcnt lgkmcnt(1)
	v_mfma_f32_16x16x32_bf16 v[38:41], v[132:135], v[182:185], v[38:41]
	v_mfma_f32_16x16x32_bf16 v[34:37], v[150:153], v[182:185], v[34:37]
	v_mfma_f32_16x16x32_bf16 v[62:65], v[136:139], v[78:81], v[62:65]
	v_mfma_f32_16x16x32_bf16 v[58:61], v[154:157], v[78:81], v[58:61]
	v_mfma_f32_16x16x32_bf16 v[54:57], v[136:139], v[94:97], v[54:57]
	v_mfma_f32_16x16x32_bf16 v[50:53], v[154:157], v[94:97], v[50:53]
	v_mfma_f32_16x16x32_bf16 v[46:49], v[132:135], v[174:177], v[46:49]
	v_mfma_f32_16x16x32_bf16 v[42:45], v[150:153], v[174:177], v[42:45]
	s_waitcnt lgkmcnt(0)
	v_mfma_f32_16x16x32_bf16 v[38:41], v[136:139], v[186:189], v[38:41]
	v_mfma_f32_16x16x32_bf16 v[34:37], v[154:157], v[186:189], v[34:37]
	v_mfma_f32_16x16x32_bf16 v[190:193], v[136:139], v[178:181], v[46:49]
	v_mfma_f32_16x16x32_bf16 v[236:239], v[154:157], v[178:181], v[42:45]
	s_setprio 0
	s_setprio 1
	v_mfma_f32_16x16x32_bf16 v[22:25], v[106:109], v[90:93], v[22:25]
	v_mfma_f32_16x16x32_bf16 v[18:21], v[200:203], v[90:93], v[18:21]
	v_mfma_f32_16x16x32_bf16 v[6:9], v[106:109], v[182:185], v[6:9]
	v_mfma_f32_16x16x32_bf16 v[2:5], v[200:203], v[182:185], v[2:5]
	v_mfma_f32_16x16x32_bf16 v[30:33], v[106:109], v[74:77], v[30:33]
	v_mfma_f32_16x16x32_bf16 v[26:29], v[200:203], v[74:77], v[26:29]
	v_mfma_f32_16x16x32_bf16 v[22:25], v[110:113], v[94:97], v[22:25]
	v_mfma_f32_16x16x32_bf16 v[18:21], v[222:225], v[94:97], v[18:21]
	v_mfma_f32_16x16x32_bf16 v[14:17], v[106:109], v[174:177], v[14:17]
	v_mfma_f32_16x16x32_bf16 v[10:13], v[200:203], v[174:177], v[10:13]
	v_mfma_f32_16x16x32_bf16 v[6:9], v[110:113], v[186:189], v[6:9]
	v_mfma_f32_16x16x32_bf16 v[2:5], v[222:225], v[186:189], v[2:5]
	v_mfma_f32_16x16x32_bf16 v[134:137], v[110:113], v[78:81], v[30:33]
	v_mfma_f32_16x16x32_bf16 v[150:153], v[222:225], v[78:81], v[26:29]
	v_mfma_f32_16x16x32_bf16 v[154:157], v[110:113], v[178:181], v[14:17]
	v_mfma_f32_16x16x32_bf16 v[174:177], v[222:225], v[178:181], v[10:13]
	s_setprio 0
	s_barrier
	s_nop 0
	ds_read_b128 v[10:13], v148 offset:32768
	ds_read_b128 v[14:17], v148 offset:33792
	ds_read_b128 v[178:181], v148 offset:34816
	ds_read_b128 v[182:185], v148 offset:35840
	ds_read_b128 v[26:29], v147 offset:32768
	ds_read_b128 v[30:33], v147 offset:33792
	ds_read_b128 v[42:45], v147 offset:34816
	ds_read_b128 v[46:49], v147 offset:35840
	ds_read_b128 v[186:189], v147 offset:36864
	ds_read_b128 v[200:203], v147 offset:37888
	ds_read_b128 v[222:225], v147 offset:38912
	ds_read_b128 v[240:243], v147 offset:39936
	s_waitcnt vmcnt(2)
	s_barrier
	s_waitcnt lgkmcnt(0)
	s_setprio 1
	s_waitcnt lgkmcnt(7)
	v_mfma_f32_16x16x32_bf16 v[74:77], v[10:13], v[26:29], v[126:129]
	s_waitcnt lgkmcnt(6)
	v_mfma_f32_16x16x32_bf16 v[130:133], v[14:17], v[30:33], v[74:77]
	v_mfma_f32_16x16x32_bf16 v[74:77], v[178:181], v[26:29], v[122:125]
	v_mfma_f32_16x16x32_bf16 v[122:125], v[182:185], v[30:33], v[74:77]
	s_waitcnt lgkmcnt(5)
	v_mfma_f32_16x16x32_bf16 v[74:77], v[10:13], v[42:45], v[118:121]
	s_waitcnt lgkmcnt(4)
	v_mfma_f32_16x16x32_bf16 v[110:113], v[14:17], v[46:49], v[74:77]
	v_mfma_f32_16x16x32_bf16 v[74:77], v[178:181], v[42:45], v[114:117]
	v_mfma_f32_16x16x32_bf16 v[106:109], v[182:185], v[46:49], v[74:77]
	s_waitcnt lgkmcnt(3)
	v_mfma_f32_16x16x32_bf16 v[74:77], v[10:13], v[186:189], v[158:161]
	s_waitcnt lgkmcnt(2)
	v_mfma_f32_16x16x32_bf16 v[94:97], v[14:17], v[200:203], v[74:77]
	v_mfma_f32_16x16x32_bf16 v[74:77], v[178:181], v[186:189], v[196:199]
	v_mfma_f32_16x16x32_bf16 v[90:93], v[182:185], v[200:203], v[74:77]
	s_waitcnt lgkmcnt(1)
	v_mfma_f32_16x16x32_bf16 v[74:77], v[10:13], v[222:225], v[102:105]
	s_waitcnt lgkmcnt(0)
	v_mfma_f32_16x16x32_bf16 v[78:81], v[14:17], v[240:243], v[74:77]
	v_mfma_f32_16x16x32_bf16 v[74:77], v[178:181], v[222:225], v[98:101]
	v_mfma_f32_16x16x32_bf16 v[74:77], v[182:185], v[240:243], v[74:77]
	s_setprio 0
	s_barrier
	ds_read_b128 v[126:129], v148 offset:49152
	ds_read_b128 v[158:161], v148 offset:50176
	ds_read_b128 v[194:197], v148 offset:51200
	ds_read_b128 v[244:247], v148 offset:52224
	s_waitcnt vmcnt(0)
	s_barrier
	s_waitcnt lgkmcnt(0)
	s_setprio 1
	s_waitcnt lgkmcnt(3)
	v_mfma_f32_16x16x32_bf16 v[98:101], v[126:129], v[26:29], v[232:235]
	s_waitcnt lgkmcnt(1)
	v_mfma_f32_16x16x32_bf16 v[26:29], v[194:197], v[26:29], v[162:165]
	s_waitcnt lgkmcnt(0)
	v_mfma_f32_16x16x32_bf16 v[114:117], v[244:247], v[30:33], v[26:29]
	v_mfma_f32_16x16x32_bf16 v[26:29], v[126:129], v[42:45], v[86:89]
	v_mfma_f32_16x16x32_bf16 v[102:105], v[158:161], v[46:49], v[26:29]
	v_mfma_f32_16x16x32_bf16 v[26:29], v[194:197], v[42:45], v[82:85]
	v_mfma_f32_16x16x32_bf16 v[118:121], v[158:161], v[30:33], v[98:101]
	v_mfma_f32_16x16x32_bf16 v[98:101], v[244:247], v[46:49], v[26:29]
	v_mfma_f32_16x16x32_bf16 v[26:29], v[126:129], v[186:189], v[166:169]
	v_mfma_f32_16x16x32_bf16 v[86:89], v[158:161], v[200:203], v[26:29]
	v_mfma_f32_16x16x32_bf16 v[26:29], v[194:197], v[186:189], v[170:173]
	v_mfma_f32_16x16x32_bf16 v[82:85], v[244:247], v[200:203], v[26:29]
	v_mfma_f32_16x16x32_bf16 v[26:29], v[126:129], v[222:225], v[70:73]
	v_mfma_f32_16x16x32_bf16 v[70:73], v[158:161], v[240:243], v[26:29]
	v_mfma_f32_16x16x32_bf16 v[26:29], v[194:197], v[222:225], v[66:69]
	v_mfma_f32_16x16x32_bf16 v[66:69], v[244:247], v[240:243], v[26:29]
	s_setprio 0
	s_barrier
	ds_read_b128 v[162:165], v147 offset:49152
	ds_read_b128 v[166:169], v147 offset:50176
	ds_read_b128 v[170:173], v147 offset:51200
	ds_read_b128 v[186:189], v147 offset:52224
	ds_read_b128 v[198:201], v147 offset:53248
	ds_read_b128 v[202:205], v147 offset:54272
	ds_read_b128 v[222:225], v147 offset:55296
	ds_read_b128 v[146:149], v147 offset:56320
	s_barrier
	s_waitcnt lgkmcnt(0)
	s_setprio 1
	s_waitcnt lgkmcnt(7)
	v_mfma_f32_16x16x32_bf16 v[26:29], v[10:13], v[162:165], v[62:65]
	s_waitcnt lgkmcnt(6)
	v_mfma_f32_16x16x32_bf16 v[62:65], v[14:17], v[166:169], v[26:29]
	v_mfma_f32_16x16x32_bf16 v[26:29], v[178:181], v[162:165], v[58:61]
	v_mfma_f32_16x16x32_bf16 v[58:61], v[182:185], v[166:169], v[26:29]
	s_waitcnt lgkmcnt(5)
	v_mfma_f32_16x16x32_bf16 v[26:29], v[10:13], v[170:173], v[54:57]
	s_waitcnt lgkmcnt(4)
	v_mfma_f32_16x16x32_bf16 v[46:49], v[14:17], v[186:189], v[26:29]
	v_mfma_f32_16x16x32_bf16 v[26:29], v[178:181], v[170:173], v[50:53]
	v_mfma_f32_16x16x32_bf16 v[42:45], v[182:185], v[186:189], v[26:29]
	s_waitcnt lgkmcnt(3)
	v_mfma_f32_16x16x32_bf16 v[26:29], v[10:13], v[198:201], v[190:193]
	s_waitcnt lgkmcnt(1)
	v_mfma_f32_16x16x32_bf16 v[10:13], v[10:13], v[222:225], v[38:41]
	v_mfma_f32_16x16x32_bf16 v[30:33], v[14:17], v[202:205], v[26:29]
	v_mfma_f32_16x16x32_bf16 v[26:29], v[178:181], v[198:201], v[236:239]
	s_waitcnt lgkmcnt(0)
	v_mfma_f32_16x16x32_bf16 v[14:17], v[14:17], v[146:149], v[10:13]
	v_mfma_f32_16x16x32_bf16 v[10:13], v[178:181], v[222:225], v[34:37]
	v_mfma_f32_16x16x32_bf16 v[26:29], v[182:185], v[202:205], v[26:29]
	v_mfma_f32_16x16x32_bf16 v[10:13], v[182:185], v[146:149], v[10:13]
	s_setprio 0
	s_setprio 1
	v_mfma_f32_16x16x32_bf16 v[34:37], v[126:129], v[162:165], v[134:137]
	v_mfma_f32_16x16x32_bf16 v[54:57], v[158:161], v[166:169], v[34:37]
	v_mfma_f32_16x16x32_bf16 v[34:37], v[194:197], v[162:165], v[150:153]
	v_mfma_f32_16x16x32_bf16 v[18:21], v[194:197], v[170:173], v[18:21]
	v_mfma_f32_16x16x32_bf16 v[50:53], v[244:247], v[166:169], v[34:37]
	v_mfma_f32_16x16x32_bf16 v[22:25], v[126:129], v[170:173], v[22:25]
	v_mfma_f32_16x16x32_bf16 v[34:37], v[244:247], v[186:189], v[18:21]
	v_mfma_f32_16x16x32_bf16 v[18:21], v[126:129], v[198:201], v[154:157]
	v_mfma_f32_16x16x32_bf16 v[38:41], v[158:161], v[186:189], v[22:25]
	v_mfma_f32_16x16x32_bf16 v[22:25], v[158:161], v[202:205], v[18:21]
	v_mfma_f32_16x16x32_bf16 v[18:21], v[194:197], v[198:201], v[174:177]
	v_mfma_f32_16x16x32_bf16 v[6:9], v[126:129], v[222:225], v[6:9]
	v_mfma_f32_16x16x32_bf16 v[2:5], v[194:197], v[222:225], v[2:5]
	v_mfma_f32_16x16x32_bf16 v[18:21], v[244:247], v[202:205], v[18:21]
	v_mfma_f32_16x16x32_bf16 v[6:9], v[158:161], v[146:149], v[6:9]
	v_mfma_f32_16x16x32_bf16 v[2:5], v[244:247], v[146:149], v[2:5]
	s_setprio 0
	s_movk_i32 s0, 0x100
	v_cmp_gt_u32_e32 vcc, s0, v140
	s_barrier
	s_and_saveexec_b64 s[0:1], vcc
	s_cbranch_execz .LBB0_764
	s_barrier
